# pk LSCAN unit + hand-written rpass (modes 1,2) + barrier non-leaders poll TOPGEN
# speedup vs baseline: 1.0552x; 1.0552x over previous
.LBB0_179:
	s_or_b64 exec, exec, s[6:7]
	v_cvt_f32_u32_e32 v4, v2
	s_waitcnt vmcnt(0)
	v_readfirstlane_b32 s4, v3
	v_sub_u32_e32 v3, 0, v2
	v_rcp_iflag_f32_e32 v4, v4
	v_add_u32_e32 v5, s4, v1
	v_mul_f32_e32 v4, 0x4f7ffffe, v4
	v_cvt_u32_f32_e32 v4, v4
	v_mul_lo_u32 v1, v3, v4
	v_mul_hi_u32 v1, v4, v1
	v_add_u32_e32 v1, v4, v1
	v_mul_hi_u32 v1, v5, v1
	v_mul_lo_u32 v3, v1, v2
	v_sub_u32_e32 v3, v5, v3
	v_add_u32_e32 v4, 1, v1
	v_cmp_ge_u32_e32 vcc, v3, v2
	s_nop 1
	v_cndmask_b32_e32 v1, v1, v4, vcc
	v_sub_u32_e32 v4, v3, v2
	v_cndmask_b32_e32 v3, v3, v4, vcc
	v_add_u32_e32 v4, 1, v1
	v_cmp_ge_u32_e32 vcc, v3, v2
	v_add_u32_e32 v3, 1, v5
	s_nop 0
	v_cndmask_b32_e32 v1, v1, v4, vcc
	v_mul_lo_u32 v4, v2, v1
	v_add_u32_e32 v2, v4, v2
	v_cmp_ne_u32_e32 vcc, v3, v2
	s_and_saveexec_b64 s[4:5], vcc
	s_xor_b64 s[4:5], exec, s[4:5]
	s_cbranch_execz .LBB0_193
	s_waitcnt lgkmcnt(0)
	v_readlane_b32 s10, v242, 7
	v_readlane_b32 s11, v242, 8
	v_mov_b32_e32 v0, 0
	s_add_u32 s10, s10, 0x3500
	s_addc_u32 s11, s11, 0
	global_load_dword v0, v0, s[10:11] sc1
	s_waitcnt vmcnt(0)
	v_cmp_eq_u32_e32 vcc, v0, v1
	s_and_saveexec_b64 s[6:7], vcc
	s_cbranch_execz .LBB0_192
	v_readlane_b32 s12, v242, 1
	v_readlane_b32 s14, v242, 3
	v_readlane_b32 s13, v242, 2
	v_readlane_b32 s15, v242, 4
	s_add_u32 s8, s14, 0x30f4300
	s_addc_u32 s9, s15, 0
	s_mov_b32 s22, 1
	s_mov_b64 s[12:13], 0
	v_mov_b32_e32 v0, 0
	s_branch .LBB0_183

.LBB0_961:
	s_waitcnt vmcnt(0) lgkmcnt(0)
	v_readlane_b32 s0, v242, 42
	v_readlane_b32 s1, v242, 43
	v_readlane_b32 s4, v242, 3
	v_readlane_b32 s5, v242, 4
	s_lshr_b32 s6, s24, 2
	s_and_b32 s7, s24, 3
	s_cmp_gt_u32 s6, 11
	s_cselect_b32 s8, 1, 0
	s_mul_i32 s9, s8, 12
	s_sub_i32 s9, s6, s9
	s_sub_u32 s0, s0, 0x118
	s_subb_u32 s1, s1, 0
	s_load_dwordx2 s[2:3], s[0:1], 0x30
	s_lshr_b32 s10, s9, 1
	s_and_b32 s11, s9, 1
	s_lshl_b32 s29, s8, 1
	s_add_i32 s29, s29, 0
	s_lshl_b32 s29, s29, 1
	s_add_i32 s29, s29, s11
	s_mul_i32 s29, s29, 6
	s_add_i32 s29, s29, s10
	s_lshl_b32 s29, s29, 14
	v_and_b32_e32 v20, 15, v137
	v_lshrrev_b32_e32 v21, 4, v137
	v_lshlrev_b32_e32 v22, 4, v137
	s_lshl_b32 s38, s7, 12
	v_add_u32_e32 v22, s38, v22
	s_waitcnt lgkmcnt(0)
	s_add_u32 s2, s2, s29
	s_addc_u32 s3, s3, 0
	global_load_dwordx4 v[0:3], v22, s[2:3]
	s_mul_i32 s38, s11, 0xf00000
	s_mul_i32 s39, s11, 0x780000
	s_add_u32 s29, s38, 0x9278100
	s_add_u32 s12, s4, s29
	s_addc_u32 s13, s5, 0
	s_add_u32 s29, s39, 0xb078100
	s_add_u32 s14, s4, s29
	s_addc_u32 s15, s5, 0
	s_add_u32 s29, s39, 0xbf78100
	s_add_u32 s18, s4, s29
	s_addc_u32 s19, s5, 0
	s_add_u32 s29, s39, 0xddc8100
	s_add_u32 s22, s4, s29
	s_addc_u32 s23, s5, 0
	s_add_u32 s16, s4, 0xce78100
	s_addc_u32 s17, s5, 0
	s_add_u32 s20, s4, 0x5b78100
	s_addc_u32 s21, s5, 0
	s_lshl_b32 s38, s11, 1
	s_sub_i32 s38, 1, s38
	s_mul_i32 s25, s38, 24576
	s_mul_i32 s26, s38, 12288
	s_mul_i32 s27, s38, 0x16000
	s_lshl_b32 s39, s8, 10
	s_addk_i32 s39, 0x2000
	s_mul_i32 s44, s11, 1023
	s_add_i32 s39, s39, s44
	v_mul_i32_i24_e32 v23, s38, v21
	v_mul_i32_i24_e32 v24, s38, v20
	v_add_u32_e32 v23, s39, v23
	v_add_u32_e32 v24, s39, v24
	s_lshl_b32 s38, s10, 8
	s_lshl_b32 s39, s10, 7
	s_movk_i32 s44, 0x600
	v_lshlrev_b32_e32 v25, 4, v20
	v_mul_lo_u32 v174, v23, s44
	v_add3_u32 v174, v174, s38, v25
	s_movk_i32 s44, 0x300
	v_lshlrev_b32_e32 v26, 3, v20
	v_mul_lo_u32 v175, v23, s44
	v_add3_u32 v175, v175, s39, v26
	v_mul_lo_u32 v145, v24, s44
	s_lshl_b32 s44, s7, 5
	s_add_i32 s44, s44, s39
	v_lshlrev_b32_e32 v27, 1, v21
	v_add3_u32 v145, v145, s44, v27
	s_movk_i32 s44, 0x1600
	v_mul_lo_u32 v180, v23, s44
	v_lshlrev_b32_e32 v28, 2, v20
	s_lshl_b32 s44, s7, 6
	s_add_i32 s44, s44, s38
	s_addk_i32 s44, 0xc00
	v_add3_u32 v181, v180, s44, v28
	v_add3_u32 v180, v180, s38, v25
	v_mov_b32_e32 v88, v25
	v_lshlrev_b32_e32 v90, 4, v21
	v_mul_u32_u24_e32 v91, 0x600, v21
	v_add_u32_e32 v91, v91, v25
	v_and_b32_e32 v29, 3, v20
	v_cmp_eq_u32_e64 s[30:31], 1, v29
	v_cmp_eq_u32_e64 s[34:35], 2, v29
	v_cmp_eq_u32_e64 s[36:37], 3, v29
	s_mov_b32 s28, 0
	s_setprio 3
	global_load_dwordx4 v[104:107], v174, s[12:13]
	global_load_dwordx2 v[146:147], v175, s[14:15]
	global_load_dwordx2 v[148:149], v175, s[16:17]
	global_load_dwordx2 v[150:151], v175, s[18:19]
	global_load_dwordx4 v[108:111], v180, s[20:21]
	global_load_dword v170, v181, s[20:21]
	v_add_u32_e32 v174, s25, v174
	v_add_u32_e32 v175, s26, v175
	v_add_u32_e32 v180, s27, v180
	v_add_u32_e32 v181, s27, v181
	global_load_dwordx4 v[112:115], v174, s[12:13]
	global_load_dwordx2 v[152:153], v175, s[14:15]
	global_load_dwordx2 v[154:155], v175, s[16:17]
	global_load_dwordx2 v[156:157], v175, s[18:19]
	global_load_dwordx4 v[116:119], v180, s[20:21]
	global_load_dword v171, v181, s[20:21]
	v_add_u32_e32 v174, s25, v174
	v_add_u32_e32 v175, s26, v175
	v_add_u32_e32 v180, s27, v180
	v_add_u32_e32 v181, s27, v181
	global_load_dwordx4 v[120:123], v174, s[12:13]
	global_load_dwordx2 v[158:159], v175, s[14:15]
	global_load_dwordx2 v[160:161], v175, s[16:17]
	global_load_dwordx2 v[162:163], v175, s[18:19]
	global_load_dwordx4 v[124:127], v180, s[20:21]
	global_load_dword v172, v181, s[20:21]
	v_add_u32_e32 v174, s25, v174
	v_add_u32_e32 v175, s26, v175
	v_add_u32_e32 v180, s27, v180
	v_add_u32_e32 v181, s27, v181
	global_load_dwordx4 v[128:131], v174, s[12:13]
	global_load_dwordx2 v[164:165], v175, s[14:15]
	global_load_dwordx2 v[166:167], v175, s[16:17]
	global_load_dwordx2 v[168:169], v175, s[18:19]
	global_load_dwordx4 v[132:135], v180, s[20:21]
	global_load_dword v173, v181, s[20:21]
	v_add_u32_e32 v174, s25, v174
	v_add_u32_e32 v175, s26, v175
	v_add_u32_e32 v180, s27, v180
	v_add_u32_e32 v181, s27, v181
	s_waitcnt vmcnt(18)
	ds_write_b128 v91, v[104:107] offset:0
	ds_write_b128 v91, v[108:111] offset:1024
	ds_write_b32 v91, v170 offset:1280
	v_lshlrev_b32_e32 v176, 16, v146
	v_and_b32_e32 v177, 0xffff0000, v146
	v_lshlrev_b32_e32 v178, 16, v147
	v_and_b32_e32 v179, 0xffff0000, v147
	ds_write_b128 v91, v[176:179] offset:256
	v_lshlrev_b32_e32 v176, 16, v148
	v_and_b32_e32 v177, 0xffff0000, v148
	v_lshlrev_b32_e32 v178, 16, v149
	v_and_b32_e32 v179, 0xffff0000, v149
	ds_write_b128 v91, v[176:179] offset:512
	v_lshlrev_b32_e32 v176, 16, v150
	v_and_b32_e32 v177, 0xffff0000, v150
	v_lshlrev_b32_e32 v178, 16, v151
	v_and_b32_e32 v179, 0xffff0000, v151
	ds_write_b128 v91, v[176:179] offset:768
	s_waitcnt lgkmcnt(0)
	s_barrier
	ds_read_b128 v[28:31], v88 offset:512
	ds_read_b128 v[24:27], v88 offset:256
	ds_read_b128 v[20:23], v88 offset:0
	ds_read_b128 v[32:35], v88 offset:768
	ds_read_b128 v[36:39], v88 offset:1024
	ds_read2st64_b32 v[16:17], v90 offset0:5 offset1:11
	ds_read_b128 v[48:51], v88 offset:2048
	ds_read_b128 v[44:47], v88 offset:1792
	ds_read_b128 v[40:43], v88 offset:1536
	ds_read_b128 v[52:55], v88 offset:2304
	ds_read_b128 v[56:59], v88 offset:2560
.Lls0_loop:
	s_waitcnt lgkmcnt(5)
	v_pk_mul_f32 v[4:5], v[0:1], v[28:29] neg_lo:[0,1] neg_hi:[0,1]
	ds_read_b128 v[68:71], v88 offset:3584
	v_pk_fma_f32 v[4:5], v[2:3], v[30:31], v[4:5] neg_lo:[0,1,0] neg_hi:[0,1,0]
	ds_read_b128 v[64:67], v88 offset:3328
	v_pk_mul_f32 v[8:9], v[24:25], v[16:17] op_sel_hi:[1,0]
	v_add_f32_e32 v4, v4, v5
	ds_read_b128 v[60:63], v88 offset:3072
	v_pk_mul_f32 v[10:11], v[26:27], v[16:17] op_sel_hi:[1,0]
	v_add_f32_dpp v4, v4, v4 quad_perm:[1,0,3,2] row_mask:0xf bank_mask:0xf bound_ctrl:1
	ds_read_b128 v[72:75], v88 offset:3840
	v_pk_fma_f32 v[8:9], v[0:1], v[20:21], v[8:9]
	v_add_f32_dpp v4, v4, v4 quad_perm:[2,3,0,1] row_mask:0xf bank_mask:0xf bound_ctrl:1
	v_add_f32_dpp v6, v6, v6 quad_perm:[1,0,3,2] row_mask:0xf bank_mask:0xf bound_ctrl:1
	v_pk_fma_f32 v[10:11], v[2:3], v[22:23], v[10:11]
	v_add_f32_dpp v4, v4, v4 row_ror:4 row_mask:0xf bank_mask:0xf bound_ctrl:1
	v_add_f32_dpp v6, v6, v6 quad_perm:[2,3,0,1] row_mask:0xf bank_mask:0xf bound_ctrl:1
	ds_read_b128 v[76:79], v88 offset:4096
	v_add_f32_dpp v4, v4, v4 row_ror:8 row_mask:0xf bank_mask:0xf bound_ctrl:1
	v_add_f32_dpp v6, v6, v6 row_ror:4 row_mask:0xf bank_mask:0xf bound_ctrl:1
	v_pk_fma_f32 v[0:1], v[4:5], v[32:33], v[8:9] op_sel_hi:[0,1,1]
	v_pk_fma_f32 v[2:3], v[4:5], v[34:35], v[10:11] op_sel_hi:[0,1,1]
	v_add_f32_dpp v15, v6, v6 row_ror:8 row_mask:0xf bank_mask:0x8 bound_ctrl:1
	v_pk_mul_f32 v[6:7], v[0:1], v[36:37]
	v_pk_fma_f32 v[6:7], v[2:3], v[38:39], v[6:7]
	v_add_f32_e32 v6, v6, v7
	ds_read2st64_b32 v[18:19], v90 offset0:17 offset1:23
	s_cmp_lt_u32 s28, 15
	s_cbranch_scc0 .Lls0_skip0
	global_load_dwordx4 v[104:107], v174, s[12:13]
	global_load_dwordx2 v[146:147], v175, s[14:15]
	global_load_dwordx2 v[148:149], v175, s[16:17]
	global_load_dwordx2 v[150:151], v175, s[18:19]
	global_load_dwordx4 v[108:111], v180, s[20:21]
	global_load_dword v170, v181, s[20:21]
	v_add_u32_e32 v174, s25, v174
	v_add_u32_e32 v175, s26, v175
	v_add_u32_e32 v180, s27, v180
	v_add_u32_e32 v181, s27, v181
.Lls0_back0:
	s_cmp_eq_u32 s28, 0
	s_cbranch_scc1 .Lls0_noy
	v_cndmask_b32_e64 v176, v12, v13, s[30:31]
	v_cndmask_b32_e64 v176, v176, v14, s[34:35]
	v_cndmask_b32_e64 v176, v176, v15, s[36:37]
	v_cvt_pk_bf16_f32 v176, v176, v176
	global_store_short v145, v176, s[22:23]
	v_add_u32_e32 v145, s26, v145
.Lls0_noy:
	s_waitcnt lgkmcnt(6)
	v_pk_mul_f32 v[4:5], v[0:1], v[48:49] neg_lo:[0,1] neg_hi:[0,1]
	ds_read_b128 v[92:95], v88 offset:5120
	v_pk_fma_f32 v[4:5], v[2:3], v[50:51], v[4:5] neg_lo:[0,1,0] neg_hi:[0,1,0]
	ds_read_b128 v[84:87], v88 offset:4864
	v_pk_mul_f32 v[8:9], v[44:45], v[16:17] op_sel:[0,1] op_sel_hi:[1,1]
	v_add_f32_e32 v4, v4, v5
	ds_read_b128 v[80:83], v88 offset:4608
	v_pk_mul_f32 v[10:11], v[46:47], v[16:17] op_sel:[0,1] op_sel_hi:[1,1]
	v_add_f32_dpp v4, v4, v4 quad_perm:[1,0,3,2] row_mask:0xf bank_mask:0xf bound_ctrl:1
	ds_read_b128 v[96:99], v88 offset:5376
	v_pk_fma_f32 v[8:9], v[0:1], v[40:41], v[8:9]
	v_add_f32_dpp v4, v4, v4 quad_perm:[2,3,0,1] row_mask:0xf bank_mask:0xf bound_ctrl:1
	v_add_f32_dpp v6, v6, v6 quad_perm:[1,0,3,2] row_mask:0xf bank_mask:0xf bound_ctrl:1
	v_pk_fma_f32 v[10:11], v[2:3], v[42:43], v[10:11]
	v_add_f32_dpp v4, v4, v4 row_ror:4 row_mask:0xf bank_mask:0xf bound_ctrl:1
	v_add_f32_dpp v6, v6, v6 quad_perm:[2,3,0,1] row_mask:0xf bank_mask:0xf bound_ctrl:1
	ds_read_b128 v[100:103], v88 offset:5632
	v_add_f32_dpp v4, v4, v4 row_ror:8 row_mask:0xf bank_mask:0xf bound_ctrl:1
	v_add_f32_dpp v6, v6, v6 row_ror:4 row_mask:0xf bank_mask:0xf bound_ctrl:1
	v_pk_fma_f32 v[0:1], v[4:5], v[52:53], v[8:9] op_sel_hi:[0,1,1]
	v_pk_fma_f32 v[2:3], v[4:5], v[54:55], v[10:11] op_sel_hi:[0,1,1]
	v_add_f32_dpp v12, v6, v6 row_ror:8 row_mask:0xf bank_mask:0x1 bound_ctrl:1
	v_pk_mul_f32 v[6:7], v[0:1], v[56:57]
	v_pk_fma_f32 v[6:7], v[2:3], v[58:59], v[6:7]
	v_add_f32_e32 v6, v6, v7
	s_waitcnt lgkmcnt(5)
	v_pk_mul_f32 v[4:5], v[0:1], v[68:69] neg_lo:[0,1] neg_hi:[0,1]
	ds_read_b128 v[28:31], v88 offset:6656
	v_pk_fma_f32 v[4:5], v[2:3], v[70:71], v[4:5] neg_lo:[0,1,0] neg_hi:[0,1,0]
	ds_read_b128 v[24:27], v88 offset:6400
	v_pk_mul_f32 v[8:9], v[64:65], v[18:19] op_sel_hi:[1,0]
	v_add_f32_e32 v4, v4, v5
	ds_read_b128 v[20:23], v88 offset:6144
	v_pk_mul_f32 v[10:11], v[66:67], v[18:19] op_sel_hi:[1,0]
	v_add_f32_dpp v4, v4, v4 quad_perm:[1,0,3,2] row_mask:0xf bank_mask:0xf bound_ctrl:1
	ds_read_b128 v[32:35], v88 offset:6912
	v_pk_fma_f32 v[8:9], v[0:1], v[60:61], v[8:9]
	v_add_f32_dpp v4, v4, v4 quad_perm:[2,3,0,1] row_mask:0xf bank_mask:0xf bound_ctrl:1
	v_add_f32_dpp v6, v6, v6 quad_perm:[1,0,3,2] row_mask:0xf bank_mask:0xf bound_ctrl:1
	v_pk_fma_f32 v[10:11], v[2:3], v[62:63], v[10:11]
	v_add_f32_dpp v4, v4, v4 row_ror:4 row_mask:0xf bank_mask:0xf bound_ctrl:1
	v_add_f32_dpp v6, v6, v6 quad_perm:[2,3,0,1] row_mask:0xf bank_mask:0xf bound_ctrl:1
	ds_read_b128 v[36:39], v88 offset:7168
	v_add_f32_dpp v4, v4, v4 row_ror:8 row_mask:0xf bank_mask:0xf bound_ctrl:1
	v_add_f32_dpp v6, v6, v6 row_ror:4 row_mask:0xf bank_mask:0xf bound_ctrl:1
	v_pk_fma_f32 v[0:1], v[4:5], v[72:73], v[8:9] op_sel_hi:[0,1,1]
	v_pk_fma_f32 v[2:3], v[4:5], v[74:75], v[10:11] op_sel_hi:[0,1,1]
	v_add_f32_dpp v13, v6, v6 row_ror:8 row_mask:0xf bank_mask:0x1 bound_ctrl:1
	v_pk_mul_f32 v[6:7], v[0:1], v[76:77]
	v_pk_fma_f32 v[6:7], v[2:3], v[78:79], v[6:7]
	v_add_f32_e32 v6, v6, v7
	ds_read2st64_b32 v[16:17], v90 offset0:29 offset1:35
	s_waitcnt lgkmcnt(6)
	v_pk_mul_f32 v[4:5], v[0:1], v[92:93] neg_lo:[0,1] neg_hi:[0,1]
	ds_read_b128 v[48:51], v88 offset:8192
	v_pk_fma_f32 v[4:5], v[2:3], v[94:95], v[4:5] neg_lo:[0,1,0] neg_hi:[0,1,0]
	ds_read_b128 v[44:47], v88 offset:7936
	v_pk_mul_f32 v[8:9], v[84:85], v[18:19] op_sel:[0,1] op_sel_hi:[1,1]
	v_add_f32_e32 v4, v4, v5
	ds_read_b128 v[40:43], v88 offset:7680
	v_pk_mul_f32 v[10:11], v[86:87], v[18:19] op_sel:[0,1] op_sel_hi:[1,1]
	v_add_f32_dpp v4, v4, v4 quad_perm:[1,0,3,2] row_mask:0xf bank_mask:0xf bound_ctrl:1
	ds_read_b128 v[52:55], v88 offset:8448
	v_pk_fma_f32 v[8:9], v[0:1], v[80:81], v[8:9]
	v_add_f32_dpp v4, v4, v4 quad_perm:[2,3,0,1] row_mask:0xf bank_mask:0xf bound_ctrl:1
	v_add_f32_dpp v6, v6, v6 quad_perm:[1,0,3,2] row_mask:0xf bank_mask:0xf bound_ctrl:1
	v_pk_fma_f32 v[10:11], v[2:3], v[82:83], v[10:11]
	v_add_f32_dpp v4, v4, v4 row_ror:4 row_mask:0xf bank_mask:0xf bound_ctrl:1
	v_add_f32_dpp v6, v6, v6 quad_perm:[2,3,0,1] row_mask:0xf bank_mask:0xf bound_ctrl:1
	ds_read_b128 v[56:59], v88 offset:8704
	v_add_f32_dpp v4, v4, v4 row_ror:8 row_mask:0xf bank_mask:0xf bound_ctrl:1
	v_add_f32_dpp v6, v6, v6 row_ror:4 row_mask:0xf bank_mask:0xf bound_ctrl:1
	v_pk_fma_f32 v[0:1], v[4:5], v[96:97], v[8:9] op_sel_hi:[0,1,1]
	v_pk_fma_f32 v[2:3], v[4:5], v[98:99], v[10:11] op_sel_hi:[0,1,1]
	v_add_f32_dpp v14, v6, v6 row_ror:8 row_mask:0xf bank_mask:0x1 bound_ctrl:1
	v_pk_mul_f32 v[6:7], v[0:1], v[100:101]
	v_pk_fma_f32 v[6:7], v[2:3], v[102:103], v[6:7]
	v_add_f32_e32 v6, v6, v7
	s_waitcnt lgkmcnt(5)
	v_pk_mul_f32 v[4:5], v[0:1], v[28:29] neg_lo:[0,1] neg_hi:[0,1]
	ds_read_b128 v[68:71], v88 offset:9728
	v_pk_fma_f32 v[4:5], v[2:3], v[30:31], v[4:5] neg_lo:[0,1,0] neg_hi:[0,1,0]
	ds_read_b128 v[64:67], v88 offset:9472
	v_pk_mul_f32 v[8:9], v[24:25], v[16:17] op_sel_hi:[1,0]
	v_add_f32_e32 v4, v4, v5
	ds_read_b128 v[60:63], v88 offset:9216
	v_pk_mul_f32 v[10:11], v[26:27], v[16:17] op_sel_hi:[1,0]
	v_add_f32_dpp v4, v4, v4 quad_perm:[1,0,3,2] row_mask:0xf bank_mask:0xf bound_ctrl:1
	ds_read_b128 v[72:75], v88 offset:9984
	v_pk_fma_f32 v[8:9], v[0:1], v[20:21], v[8:9]
	v_add_f32_dpp v4, v4, v4 quad_perm:[2,3,0,1] row_mask:0xf bank_mask:0xf bound_ctrl:1
	v_add_f32_dpp v6, v6, v6 quad_perm:[1,0,3,2] row_mask:0xf bank_mask:0xf bound_ctrl:1
	v_pk_fma_f32 v[10:11], v[2:3], v[22:23], v[10:11]
	v_add_f32_dpp v4, v4, v4 row_ror:4 row_mask:0xf bank_mask:0xf bound_ctrl:1
	v_add_f32_dpp v6, v6, v6 quad_perm:[2,3,0,1] row_mask:0xf bank_mask:0xf bound_ctrl:1
	ds_read_b128 v[76:79], v88 offset:10240
	v_add_f32_dpp v4, v4, v4 row_ror:8 row_mask:0xf bank_mask:0xf bound_ctrl:1
	v_add_f32_dpp v6, v6, v6 row_ror:4 row_mask:0xf bank_mask:0xf bound_ctrl:1
	v_pk_fma_f32 v[0:1], v[4:5], v[32:33], v[8:9] op_sel_hi:[0,1,1]
	v_pk_fma_f32 v[2:3], v[4:5], v[34:35], v[10:11] op_sel_hi:[0,1,1]
	v_add_f32_dpp v15, v6, v6 row_ror:8 row_mask:0xf bank_mask:0x1 bound_ctrl:1
	v_pk_mul_f32 v[6:7], v[0:1], v[36:37]
	v_pk_fma_f32 v[6:7], v[2:3], v[38:39], v[6:7]
	v_add_f32_e32 v6, v6, v7
	ds_read2st64_b32 v[18:19], v90 offset0:41 offset1:47
	s_waitcnt vmcnt(18)
	ds_write_b128 v91, v[112:115] offset:24576
	s_waitcnt lgkmcnt(7)
	v_pk_mul_f32 v[4:5], v[0:1], v[48:49] neg_lo:[0,1] neg_hi:[0,1]
	ds_read_b128 v[92:95], v88 offset:11264
	v_pk_fma_f32 v[4:5], v[2:3], v[50:51], v[4:5] neg_lo:[0,1,0] neg_hi:[0,1,0]
	ds_read_b128 v[84:87], v88 offset:11008
	v_pk_mul_f32 v[8:9], v[44:45], v[16:17] op_sel:[0,1] op_sel_hi:[1,1]
	v_add_f32_e32 v4, v4, v5
	ds_read_b128 v[80:83], v88 offset:10752
	v_pk_mul_f32 v[10:11], v[46:47], v[16:17] op_sel:[0,1] op_sel_hi:[1,1]
	v_add_f32_dpp v4, v4, v4 quad_perm:[1,0,3,2] row_mask:0xf bank_mask:0xf bound_ctrl:1
	ds_read_b128 v[96:99], v88 offset:11520
	v_pk_fma_f32 v[8:9], v[0:1], v[40:41], v[8:9]
	v_add_f32_dpp v4, v4, v4 quad_perm:[2,3,0,1] row_mask:0xf bank_mask:0xf bound_ctrl:1
	v_add_f32_dpp v6, v6, v6 quad_perm:[1,0,3,2] row_mask:0xf bank_mask:0xf bound_ctrl:1
	v_pk_fma_f32 v[10:11], v[2:3], v[42:43], v[10:11]
	v_add_f32_dpp v4, v4, v4 row_ror:4 row_mask:0xf bank_mask:0xf bound_ctrl:1
	v_add_f32_dpp v6, v6, v6 quad_perm:[2,3,0,1] row_mask:0xf bank_mask:0xf bound_ctrl:1
	ds_read_b128 v[100:103], v88 offset:11776
	v_add_f32_dpp v4, v4, v4 row_ror:8 row_mask:0xf bank_mask:0xf bound_ctrl:1
	v_add_f32_dpp v6, v6, v6 row_ror:4 row_mask:0xf bank_mask:0xf bound_ctrl:1
	v_pk_fma_f32 v[0:1], v[4:5], v[52:53], v[8:9] op_sel_hi:[0,1,1]
	v_pk_fma_f32 v[2:3], v[4:5], v[54:55], v[10:11] op_sel_hi:[0,1,1]
	v_add_f32_dpp v12, v6, v6 row_ror:8 row_mask:0xf bank_mask:0x2 bound_ctrl:1
	v_pk_mul_f32 v[6:7], v[0:1], v[56:57]
	v_pk_fma_f32 v[6:7], v[2:3], v[58:59], v[6:7]
	v_add_f32_e32 v6, v6, v7
	ds_write_b128 v91, v[116:119] offset:25600
	ds_write_b32 v91, v171 offset:25856
	s_waitcnt lgkmcnt(8)
	v_pk_mul_f32 v[4:5], v[0:1], v[68:69] neg_lo:[0,1] neg_hi:[0,1]
	ds_read_b128 v[28:31], v88 offset:12800
	v_pk_fma_f32 v[4:5], v[2:3], v[70:71], v[4:5] neg_lo:[0,1,0] neg_hi:[0,1,0]
	ds_read_b128 v[24:27], v88 offset:12544
	v_pk_mul_f32 v[8:9], v[64:65], v[18:19] op_sel_hi:[1,0]
	v_add_f32_e32 v4, v4, v5
	ds_read_b128 v[20:23], v88 offset:12288
	v_pk_mul_f32 v[10:11], v[66:67], v[18:19] op_sel_hi:[1,0]
	v_add_f32_dpp v4, v4, v4 quad_perm:[1,0,3,2] row_mask:0xf bank_mask:0xf bound_ctrl:1
	ds_read_b128 v[32:35], v88 offset:13056
	v_pk_fma_f32 v[8:9], v[0:1], v[60:61], v[8:9]
	v_add_f32_dpp v4, v4, v4 quad_perm:[2,3,0,1] row_mask:0xf bank_mask:0xf bound_ctrl:1
	v_add_f32_dpp v6, v6, v6 quad_perm:[1,0,3,2] row_mask:0xf bank_mask:0xf bound_ctrl:1
	v_pk_fma_f32 v[10:11], v[2:3], v[62:63], v[10:11]
	v_add_f32_dpp v4, v4, v4 row_ror:4 row_mask:0xf bank_mask:0xf bound_ctrl:1
	v_add_f32_dpp v6, v6, v6 quad_perm:[2,3,0,1] row_mask:0xf bank_mask:0xf bound_ctrl:1
	ds_read_b128 v[36:39], v88 offset:13312
	v_add_f32_dpp v4, v4, v4 row_ror:8 row_mask:0xf bank_mask:0xf bound_ctrl:1
	v_add_f32_dpp v6, v6, v6 row_ror:4 row_mask:0xf bank_mask:0xf bound_ctrl:1
	v_pk_fma_f32 v[0:1], v[4:5], v[72:73], v[8:9] op_sel_hi:[0,1,1]
	v_pk_fma_f32 v[2:3], v[4:5], v[74:75], v[10:11] op_sel_hi:[0,1,1]
	v_add_f32_dpp v13, v6, v6 row_ror:8 row_mask:0xf bank_mask:0x2 bound_ctrl:1
	v_pk_mul_f32 v[6:7], v[0:1], v[76:77]
	v_pk_fma_f32 v[6:7], v[2:3], v[78:79], v[6:7]
	v_add_f32_e32 v6, v6, v7
	ds_read2st64_b32 v[16:17], v90 offset0:53 offset1:59
	v_lshlrev_b32_e32 v176, 16, v152
	v_and_b32_e32 v177, 0xffff0000, v152
	s_waitcnt lgkmcnt(8)
	v_pk_mul_f32 v[4:5], v[0:1], v[92:93] neg_lo:[0,1] neg_hi:[0,1]
	ds_read_b128 v[48:51], v88 offset:14336
	v_pk_fma_f32 v[4:5], v[2:3], v[94:95], v[4:5] neg_lo:[0,1,0] neg_hi:[0,1,0]
	ds_read_b128 v[44:47], v88 offset:14080
	v_pk_mul_f32 v[8:9], v[84:85], v[18:19] op_sel:[0,1] op_sel_hi:[1,1]
	v_add_f32_e32 v4, v4, v5
	ds_read_b128 v[40:43], v88 offset:13824
	v_pk_mul_f32 v[10:11], v[86:87], v[18:19] op_sel:[0,1] op_sel_hi:[1,1]
	v_add_f32_dpp v4, v4, v4 quad_perm:[1,0,3,2] row_mask:0xf bank_mask:0xf bound_ctrl:1
	ds_read_b128 v[52:55], v88 offset:14592
	v_pk_fma_f32 v[8:9], v[0:1], v[80:81], v[8:9]
	v_add_f32_dpp v4, v4, v4 quad_perm:[2,3,0,1] row_mask:0xf bank_mask:0xf bound_ctrl:1
	v_add_f32_dpp v6, v6, v6 quad_perm:[1,0,3,2] row_mask:0xf bank_mask:0xf bound_ctrl:1
	v_pk_fma_f32 v[10:11], v[2:3], v[82:83], v[10:11]
	v_add_f32_dpp v4, v4, v4 row_ror:4 row_mask:0xf bank_mask:0xf bound_ctrl:1
	v_add_f32_dpp v6, v6, v6 quad_perm:[2,3,0,1] row_mask:0xf bank_mask:0xf bound_ctrl:1
	ds_read_b128 v[56:59], v88 offset:14848
	v_add_f32_dpp v4, v4, v4 row_ror:8 row_mask:0xf bank_mask:0xf bound_ctrl:1
	v_add_f32_dpp v6, v6, v6 row_ror:4 row_mask:0xf bank_mask:0xf bound_ctrl:1
	v_pk_fma_f32 v[0:1], v[4:5], v[96:97], v[8:9] op_sel_hi:[0,1,1]
	v_pk_fma_f32 v[2:3], v[4:5], v[98:99], v[10:11] op_sel_hi:[0,1,1]
	v_add_f32_dpp v14, v6, v6 row_ror:8 row_mask:0xf bank_mask:0x2 bound_ctrl:1
	v_pk_mul_f32 v[6:7], v[0:1], v[100:101]
	v_pk_fma_f32 v[6:7], v[2:3], v[102:103], v[6:7]
	v_add_f32_e32 v6, v6, v7
	v_lshlrev_b32_e32 v178, 16, v153
	v_and_b32_e32 v179, 0xffff0000, v153
	s_waitcnt lgkmcnt(5)
	v_pk_mul_f32 v[4:5], v[0:1], v[28:29] neg_lo:[0,1] neg_hi:[0,1]
	ds_read_b128 v[68:71], v88 offset:15872
	v_pk_fma_f32 v[4:5], v[2:3], v[30:31], v[4:5] neg_lo:[0,1,0] neg_hi:[0,1,0]
	ds_read_b128 v[64:67], v88 offset:15616
	v_pk_mul_f32 v[8:9], v[24:25], v[16:17] op_sel_hi:[1,0]
	v_add_f32_e32 v4, v4, v5
	ds_read_b128 v[60:63], v88 offset:15360
	v_pk_mul_f32 v[10:11], v[26:27], v[16:17] op_sel_hi:[1,0]
	v_add_f32_dpp v4, v4, v4 quad_perm:[1,0,3,2] row_mask:0xf bank_mask:0xf bound_ctrl:1
	ds_read_b128 v[72:75], v88 offset:16128
	v_pk_fma_f32 v[8:9], v[0:1], v[20:21], v[8:9]
	v_add_f32_dpp v4, v4, v4 quad_perm:[2,3,0,1] row_mask:0xf bank_mask:0xf bound_ctrl:1
	v_add_f32_dpp v6, v6, v6 quad_perm:[1,0,3,2] row_mask:0xf bank_mask:0xf bound_ctrl:1
	v_pk_fma_f32 v[10:11], v[2:3], v[22:23], v[10:11]
	v_add_f32_dpp v4, v4, v4 row_ror:4 row_mask:0xf bank_mask:0xf bound_ctrl:1
	v_add_f32_dpp v6, v6, v6 quad_perm:[2,3,0,1] row_mask:0xf bank_mask:0xf bound_ctrl:1
	ds_read_b128 v[76:79], v88 offset:16384
	v_add_f32_dpp v4, v4, v4 row_ror:8 row_mask:0xf bank_mask:0xf bound_ctrl:1
	v_add_f32_dpp v6, v6, v6 row_ror:4 row_mask:0xf bank_mask:0xf bound_ctrl:1
	v_pk_fma_f32 v[0:1], v[4:5], v[32:33], v[8:9] op_sel_hi:[0,1,1]
	v_pk_fma_f32 v[2:3], v[4:5], v[34:35], v[10:11] op_sel_hi:[0,1,1]
	v_add_f32_dpp v15, v6, v6 row_ror:8 row_mask:0xf bank_mask:0x2 bound_ctrl:1
	v_pk_mul_f32 v[6:7], v[0:1], v[36:37]
	v_pk_fma_f32 v[6:7], v[2:3], v[38:39], v[6:7]
	v_add_f32_e32 v6, v6, v7
	ds_read2st64_b32 v[18:19], v90 offset0:65 offset1:71
	ds_write_b128 v91, v[176:179] offset:24832
	v_lshlrev_b32_e32 v176, 16, v154
	s_waitcnt lgkmcnt(7)
	v_pk_mul_f32 v[4:5], v[0:1], v[48:49] neg_lo:[0,1] neg_hi:[0,1]
	ds_read_b128 v[92:95], v88 offset:17408
	v_pk_fma_f32 v[4:5], v[2:3], v[50:51], v[4:5] neg_lo:[0,1,0] neg_hi:[0,1,0]
	ds_read_b128 v[84:87], v88 offset:17152
	v_pk_mul_f32 v[8:9], v[44:45], v[16:17] op_sel:[0,1] op_sel_hi:[1,1]
	v_add_f32_e32 v4, v4, v5
	ds_read_b128 v[80:83], v88 offset:16896
	v_pk_mul_f32 v[10:11], v[46:47], v[16:17] op_sel:[0,1] op_sel_hi:[1,1]
	v_add_f32_dpp v4, v4, v4 quad_perm:[1,0,3,2] row_mask:0xf bank_mask:0xf bound_ctrl:1
	ds_read_b128 v[96:99], v88 offset:17664
	v_pk_fma_f32 v[8:9], v[0:1], v[40:41], v[8:9]
	v_add_f32_dpp v4, v4, v4 quad_perm:[2,3,0,1] row_mask:0xf bank_mask:0xf bound_ctrl:1
	v_add_f32_dpp v6, v6, v6 quad_perm:[1,0,3,2] row_mask:0xf bank_mask:0xf bound_ctrl:1
	v_pk_fma_f32 v[10:11], v[2:3], v[42:43], v[10:11]
	v_add_f32_dpp v4, v4, v4 row_ror:4 row_mask:0xf bank_mask:0xf bound_ctrl:1
	v_add_f32_dpp v6, v6, v6 quad_perm:[2,3,0,1] row_mask:0xf bank_mask:0xf bound_ctrl:1
	ds_read_b128 v[100:103], v88 offset:17920
	v_add_f32_dpp v4, v4, v4 row_ror:8 row_mask:0xf bank_mask:0xf bound_ctrl:1
	v_add_f32_dpp v6, v6, v6 row_ror:4 row_mask:0xf bank_mask:0xf bound_ctrl:1
	v_pk_fma_f32 v[0:1], v[4:5], v[52:53], v[8:9] op_sel_hi:[0,1,1]
	v_pk_fma_f32 v[2:3], v[4:5], v[54:55], v[10:11] op_sel_hi:[0,1,1]
	v_add_f32_dpp v12, v6, v6 row_ror:8 row_mask:0xf bank_mask:0x4 bound_ctrl:1
	v_pk_mul_f32 v[6:7], v[0:1], v[56:57]
	v_pk_fma_f32 v[6:7], v[2:3], v[58:59], v[6:7]
	v_add_f32_e32 v6, v6, v7
	v_and_b32_e32 v177, 0xffff0000, v154
	v_lshlrev_b32_e32 v178, 16, v155
	s_waitcnt lgkmcnt(6)
	v_pk_mul_f32 v[4:5], v[0:1], v[68:69] neg_lo:[0,1] neg_hi:[0,1]
	ds_read_b128 v[28:31], v88 offset:18944
	v_pk_fma_f32 v[4:5], v[2:3], v[70:71], v[4:5] neg_lo:[0,1,0] neg_hi:[0,1,0]
	ds_read_b128 v[24:27], v88 offset:18688
	v_pk_mul_f32 v[8:9], v[64:65], v[18:19] op_sel_hi:[1,0]
	v_add_f32_e32 v4, v4, v5
	ds_read_b128 v[20:23], v88 offset:18432
	v_pk_mul_f32 v[10:11], v[66:67], v[18:19] op_sel_hi:[1,0]
	v_add_f32_dpp v4, v4, v4 quad_perm:[1,0,3,2] row_mask:0xf bank_mask:0xf bound_ctrl:1
	ds_read_b128 v[32:35], v88 offset:19200
	v_pk_fma_f32 v[8:9], v[0:1], v[60:61], v[8:9]
	v_add_f32_dpp v4, v4, v4 quad_perm:[2,3,0,1] row_mask:0xf bank_mask:0xf bound_ctrl:1
	v_add_f32_dpp v6, v6, v6 quad_perm:[1,0,3,2] row_mask:0xf bank_mask:0xf bound_ctrl:1
	v_pk_fma_f32 v[10:11], v[2:3], v[62:63], v[10:11]
	v_add_f32_dpp v4, v4, v4 row_ror:4 row_mask:0xf bank_mask:0xf bound_ctrl:1
	v_add_f32_dpp v6, v6, v6 quad_perm:[2,3,0,1] row_mask:0xf bank_mask:0xf bound_ctrl:1
	ds_read_b128 v[36:39], v88 offset:19456
	v_add_f32_dpp v4, v4, v4 row_ror:8 row_mask:0xf bank_mask:0xf bound_ctrl:1
	v_add_f32_dpp v6, v6, v6 row_ror:4 row_mask:0xf bank_mask:0xf bound_ctrl:1
	v_pk_fma_f32 v[0:1], v[4:5], v[72:73], v[8:9] op_sel_hi:[0,1,1]
	v_pk_fma_f32 v[2:3], v[4:5], v[74:75], v[10:11] op_sel_hi:[0,1,1]
	v_add_f32_dpp v13, v6, v6 row_ror:8 row_mask:0xf bank_mask:0x4 bound_ctrl:1
	v_pk_mul_f32 v[6:7], v[0:1], v[76:77]
	v_pk_fma_f32 v[6:7], v[2:3], v[78:79], v[6:7]
	v_add_f32_e32 v6, v6, v7
	ds_read2st64_b32 v[16:17], v90 offset0:77 offset1:83
	v_and_b32_e32 v179, 0xffff0000, v155
	ds_write_b128 v91, v[176:179] offset:25088
	s_waitcnt lgkmcnt(7)
	v_pk_mul_f32 v[4:5], v[0:1], v[92:93] neg_lo:[0,1] neg_hi:[0,1]
	ds_read_b128 v[48:51], v88 offset:20480
	v_pk_fma_f32 v[4:5], v[2:3], v[94:95], v[4:5] neg_lo:[0,1,0] neg_hi:[0,1,0]
	ds_read_b128 v[44:47], v88 offset:20224
	v_pk_mul_f32 v[8:9], v[84:85], v[18:19] op_sel:[0,1] op_sel_hi:[1,1]
	v_add_f32_e32 v4, v4, v5
	ds_read_b128 v[40:43], v88 offset:19968
	v_pk_mul_f32 v[10:11], v[86:87], v[18:19] op_sel:[0,1] op_sel_hi:[1,1]
	v_add_f32_dpp v4, v4, v4 quad_perm:[1,0,3,2] row_mask:0xf bank_mask:0xf bound_ctrl:1
	ds_read_b128 v[52:55], v88 offset:20736
	v_pk_fma_f32 v[8:9], v[0:1], v[80:81], v[8:9]
	v_add_f32_dpp v4, v4, v4 quad_perm:[2,3,0,1] row_mask:0xf bank_mask:0xf bound_ctrl:1
	v_add_f32_dpp v6, v6, v6 quad_perm:[1,0,3,2] row_mask:0xf bank_mask:0xf bound_ctrl:1
	v_pk_fma_f32 v[10:11], v[2:3], v[82:83], v[10:11]
	v_add_f32_dpp v4, v4, v4 row_ror:4 row_mask:0xf bank_mask:0xf bound_ctrl:1
	v_add_f32_dpp v6, v6, v6 quad_perm:[2,3,0,1] row_mask:0xf bank_mask:0xf bound_ctrl:1
	ds_read_b128 v[56:59], v88 offset:20992
	v_add_f32_dpp v4, v4, v4 row_ror:8 row_mask:0xf bank_mask:0xf bound_ctrl:1
	v_add_f32_dpp v6, v6, v6 row_ror:4 row_mask:0xf bank_mask:0xf bound_ctrl:1
	v_pk_fma_f32 v[0:1], v[4:5], v[96:97], v[8:9] op_sel_hi:[0,1,1]
	v_pk_fma_f32 v[2:3], v[4:5], v[98:99], v[10:11] op_sel_hi:[0,1,1]
	v_add_f32_dpp v14, v6, v6 row_ror:8 row_mask:0xf bank_mask:0x4 bound_ctrl:1
	v_pk_mul_f32 v[6:7], v[0:1], v[100:101]
	v_pk_fma_f32 v[6:7], v[2:3], v[102:103], v[6:7]
	v_add_f32_e32 v6, v6, v7
	v_lshlrev_b32_e32 v176, 16, v156
	v_and_b32_e32 v177, 0xffff0000, v156
	s_waitcnt lgkmcnt(6)
	v_pk_mul_f32 v[4:5], v[0:1], v[28:29] neg_lo:[0,1] neg_hi:[0,1]
	ds_read_b128 v[68:71], v88 offset:22016
	v_pk_fma_f32 v[4:5], v[2:3], v[30:31], v[4:5] neg_lo:[0,1,0] neg_hi:[0,1,0]
	ds_read_b128 v[64:67], v88 offset:21760
	v_pk_mul_f32 v[8:9], v[24:25], v[16:17] op_sel_hi:[1,0]
	v_add_f32_e32 v4, v4, v5
	ds_read_b128 v[60:63], v88 offset:21504
	v_pk_mul_f32 v[10:11], v[26:27], v[16:17] op_sel_hi:[1,0]
	v_add_f32_dpp v4, v4, v4 quad_perm:[1,0,3,2] row_mask:0xf bank_mask:0xf bound_ctrl:1
	ds_read_b128 v[72:75], v88 offset:22272
	v_pk_fma_f32 v[8:9], v[0:1], v[20:21], v[8:9]
	v_add_f32_dpp v4, v4, v4 quad_perm:[2,3,0,1] row_mask:0xf bank_mask:0xf bound_ctrl:1
	v_add_f32_dpp v6, v6, v6 quad_perm:[1,0,3,2] row_mask:0xf bank_mask:0xf bound_ctrl:1
	v_pk_fma_f32 v[10:11], v[2:3], v[22:23], v[10:11]
	v_add_f32_dpp v4, v4, v4 row_ror:4 row_mask:0xf bank_mask:0xf bound_ctrl:1
	v_add_f32_dpp v6, v6, v6 quad_perm:[2,3,0,1] row_mask:0xf bank_mask:0xf bound_ctrl:1
	ds_read_b128 v[76:79], v88 offset:22528
	v_add_f32_dpp v4, v4, v4 row_ror:8 row_mask:0xf bank_mask:0xf bound_ctrl:1
	v_add_f32_dpp v6, v6, v6 row_ror:4 row_mask:0xf bank_mask:0xf bound_ctrl:1
	v_pk_fma_f32 v[0:1], v[4:5], v[32:33], v[8:9] op_sel_hi:[0,1,1]
	v_pk_fma_f32 v[2:3], v[4:5], v[34:35], v[10:11] op_sel_hi:[0,1,1]
	v_add_f32_dpp v15, v6, v6 row_ror:8 row_mask:0xf bank_mask:0x4 bound_ctrl:1
	v_pk_mul_f32 v[6:7], v[0:1], v[36:37]
	v_pk_fma_f32 v[6:7], v[2:3], v[38:39], v[6:7]
	v_add_f32_e32 v6, v6, v7
	ds_read2st64_b32 v[18:19], v90 offset0:89 offset1:95
	v_lshlrev_b32_e32 v178, 16, v157
	v_and_b32_e32 v179, 0xffff0000, v157
	ds_write_b128 v91, v[176:179] offset:25344
	s_waitcnt lgkmcnt(7)
	v_pk_mul_f32 v[4:5], v[0:1], v[48:49] neg_lo:[0,1] neg_hi:[0,1]
	ds_read_b128 v[92:95], v88 offset:23552
	v_pk_fma_f32 v[4:5], v[2:3], v[50:51], v[4:5] neg_lo:[0,1,0] neg_hi:[0,1,0]
	ds_read_b128 v[84:87], v88 offset:23296
	v_pk_mul_f32 v[8:9], v[44:45], v[16:17] op_sel:[0,1] op_sel_hi:[1,1]
	v_add_f32_e32 v4, v4, v5
	ds_read_b128 v[80:83], v88 offset:23040
	v_pk_mul_f32 v[10:11], v[46:47], v[16:17] op_sel:[0,1] op_sel_hi:[1,1]
	v_add_f32_dpp v4, v4, v4 quad_perm:[1,0,3,2] row_mask:0xf bank_mask:0xf bound_ctrl:1
	ds_read_b128 v[96:99], v88 offset:23808
	v_pk_fma_f32 v[8:9], v[0:1], v[40:41], v[8:9]
	v_add_f32_dpp v4, v4, v4 quad_perm:[2,3,0,1] row_mask:0xf bank_mask:0xf bound_ctrl:1
	v_add_f32_dpp v6, v6, v6 quad_perm:[1,0,3,2] row_mask:0xf bank_mask:0xf bound_ctrl:1
	v_pk_fma_f32 v[10:11], v[2:3], v[42:43], v[10:11]
	v_add_f32_dpp v4, v4, v4 row_ror:4 row_mask:0xf bank_mask:0xf bound_ctrl:1
	v_add_f32_dpp v6, v6, v6 quad_perm:[2,3,0,1] row_mask:0xf bank_mask:0xf bound_ctrl:1
	ds_read_b128 v[100:103], v88 offset:24064
	v_add_f32_dpp v4, v4, v4 row_ror:8 row_mask:0xf bank_mask:0xf bound_ctrl:1
	v_add_f32_dpp v6, v6, v6 row_ror:4 row_mask:0xf bank_mask:0xf bound_ctrl:1
	v_pk_fma_f32 v[0:1], v[4:5], v[52:53], v[8:9] op_sel_hi:[0,1,1]
	v_pk_fma_f32 v[2:3], v[4:5], v[54:55], v[10:11] op_sel_hi:[0,1,1]
	v_add_f32_dpp v12, v6, v6 row_ror:8 row_mask:0xf bank_mask:0x8 bound_ctrl:1
	v_pk_mul_f32 v[6:7], v[0:1], v[56:57]
	v_pk_fma_f32 v[6:7], v[2:3], v[58:59], v[6:7]
	v_add_f32_e32 v6, v6, v7
	s_waitcnt lgkmcnt(0)
	s_barrier
	v_pk_mul_f32 v[4:5], v[0:1], v[68:69] neg_lo:[0,1] neg_hi:[0,1]
	ds_read_b128 v[28:31], v88 offset:25088
	v_pk_fma_f32 v[4:5], v[2:3], v[70:71], v[4:5] neg_lo:[0,1,0] neg_hi:[0,1,0]
	ds_read_b128 v[24:27], v88 offset:24832
	v_pk_mul_f32 v[8:9], v[64:65], v[18:19] op_sel_hi:[1,0]
	v_add_f32_e32 v4, v4, v5
	ds_read_b128 v[20:23], v88 offset:24576
	v_pk_mul_f32 v[10:11], v[66:67], v[18:19] op_sel_hi:[1,0]
	v_add_f32_dpp v4, v4, v4 quad_perm:[1,0,3,2] row_mask:0xf bank_mask:0xf bound_ctrl:1
	ds_read_b128 v[32:35], v88 offset:25344
	v_pk_fma_f32 v[8:9], v[0:1], v[60:61], v[8:9]
	v_add_f32_dpp v4, v4, v4 quad_perm:[2,3,0,1] row_mask:0xf bank_mask:0xf bound_ctrl:1
	v_add_f32_dpp v6, v6, v6 quad_perm:[1,0,3,2] row_mask:0xf bank_mask:0xf bound_ctrl:1
	v_pk_fma_f32 v[10:11], v[2:3], v[62:63], v[10:11]
	v_add_f32_dpp v4, v4, v4 row_ror:4 row_mask:0xf bank_mask:0xf bound_ctrl:1
	v_add_f32_dpp v6, v6, v6 quad_perm:[2,3,0,1] row_mask:0xf bank_mask:0xf bound_ctrl:1
	ds_read_b128 v[36:39], v88 offset:25600
	v_add_f32_dpp v4, v4, v4 row_ror:8 row_mask:0xf bank_mask:0xf bound_ctrl:1
	v_add_f32_dpp v6, v6, v6 row_ror:4 row_mask:0xf bank_mask:0xf bound_ctrl:1
	v_pk_fma_f32 v[0:1], v[4:5], v[72:73], v[8:9] op_sel_hi:[0,1,1]
	v_pk_fma_f32 v[2:3], v[4:5], v[74:75], v[10:11] op_sel_hi:[0,1,1]
	v_add_f32_dpp v13, v6, v6 row_ror:8 row_mask:0xf bank_mask:0x8 bound_ctrl:1
	v_pk_mul_f32 v[6:7], v[0:1], v[76:77]
	v_pk_fma_f32 v[6:7], v[2:3], v[78:79], v[6:7]
	v_add_f32_e32 v6, v6, v7
	ds_read2st64_b32 v[16:17], v90 offset0:101 offset1:107
	s_waitcnt lgkmcnt(6)
	v_pk_mul_f32 v[4:5], v[0:1], v[92:93] neg_lo:[0,1] neg_hi:[0,1]
	ds_read_b128 v[48:51], v88 offset:26624
	v_pk_fma_f32 v[4:5], v[2:3], v[94:95], v[4:5] neg_lo:[0,1,0] neg_hi:[0,1,0]
	ds_read_b128 v[44:47], v88 offset:26368
	v_pk_mul_f32 v[8:9], v[84:85], v[18:19] op_sel:[0,1] op_sel_hi:[1,1]
	v_add_f32_e32 v4, v4, v5
	ds_read_b128 v[40:43], v88 offset:26112
	v_pk_mul_f32 v[10:11], v[86:87], v[18:19] op_sel:[0,1] op_sel_hi:[1,1]
	v_add_f32_dpp v4, v4, v4 quad_perm:[1,0,3,2] row_mask:0xf bank_mask:0xf bound_ctrl:1
	ds_read_b128 v[52:55], v88 offset:26880
	v_pk_fma_f32 v[8:9], v[0:1], v[80:81], v[8:9]
	v_add_f32_dpp v4, v4, v4 quad_perm:[2,3,0,1] row_mask:0xf bank_mask:0xf bound_ctrl:1
	v_add_f32_dpp v6, v6, v6 quad_perm:[1,0,3,2] row_mask:0xf bank_mask:0xf bound_ctrl:1
	v_pk_fma_f32 v[10:11], v[2:3], v[82:83], v[10:11]
	v_add_f32_dpp v4, v4, v4 row_ror:4 row_mask:0xf bank_mask:0xf bound_ctrl:1
	v_add_f32_dpp v6, v6, v6 quad_perm:[2,3,0,1] row_mask:0xf bank_mask:0xf bound_ctrl:1
	ds_read_b128 v[56:59], v88 offset:27136
	v_add_f32_dpp v4, v4, v4 row_ror:8 row_mask:0xf bank_mask:0xf bound_ctrl:1
	v_add_f32_dpp v6, v6, v6 row_ror:4 row_mask:0xf bank_mask:0xf bound_ctrl:1
	v_pk_fma_f32 v[0:1], v[4:5], v[96:97], v[8:9] op_sel_hi:[0,1,1]
	v_pk_fma_f32 v[2:3], v[4:5], v[98:99], v[10:11] op_sel_hi:[0,1,1]
	v_add_f32_dpp v14, v6, v6 row_ror:8 row_mask:0xf bank_mask:0x8 bound_ctrl:1
	v_pk_mul_f32 v[6:7], v[0:1], v[100:101]
	v_pk_fma_f32 v[6:7], v[2:3], v[102:103], v[6:7]
	v_add_f32_e32 v6, v6, v7
	s_waitcnt lgkmcnt(5)
	v_pk_mul_f32 v[4:5], v[0:1], v[28:29] neg_lo:[0,1] neg_hi:[0,1]
	ds_read_b128 v[68:71], v88 offset:28160
	v_pk_fma_f32 v[4:5], v[2:3], v[30:31], v[4:5] neg_lo:[0,1,0] neg_hi:[0,1,0]
	ds_read_b128 v[64:67], v88 offset:27904
	v_pk_mul_f32 v[8:9], v[24:25], v[16:17] op_sel_hi:[1,0]
	v_add_f32_e32 v4, v4, v5
	ds_read_b128 v[60:63], v88 offset:27648
	v_pk_mul_f32 v[10:11], v[26:27], v[16:17] op_sel_hi:[1,0]
	v_add_f32_dpp v4, v4, v4 quad_perm:[1,0,3,2] row_mask:0xf bank_mask:0xf bound_ctrl:1
	ds_read_b128 v[72:75], v88 offset:28416
	v_pk_fma_f32 v[8:9], v[0:1], v[20:21], v[8:9]
	v_add_f32_dpp v4, v4, v4 quad_perm:[2,3,0,1] row_mask:0xf bank_mask:0xf bound_ctrl:1
	v_add_f32_dpp v6, v6, v6 quad_perm:[1,0,3,2] row_mask:0xf bank_mask:0xf bound_ctrl:1
	v_pk_fma_f32 v[10:11], v[2:3], v[22:23], v[10:11]
	v_add_f32_dpp v4, v4, v4 row_ror:4 row_mask:0xf bank_mask:0xf bound_ctrl:1
	v_add_f32_dpp v6, v6, v6 quad_perm:[2,3,0,1] row_mask:0xf bank_mask:0xf bound_ctrl:1
	ds_read_b128 v[76:79], v88 offset:28672
	v_add_f32_dpp v4, v4, v4 row_ror:8 row_mask:0xf bank_mask:0xf bound_ctrl:1
	v_add_f32_dpp v6, v6, v6 row_ror:4 row_mask:0xf bank_mask:0xf bound_ctrl:1
	v_pk_fma_f32 v[0:1], v[4:5], v[32:33], v[8:9] op_sel_hi:[0,1,1]
	v_pk_fma_f32 v[2:3], v[4:5], v[34:35], v[10:11] op_sel_hi:[0,1,1]
	v_add_f32_dpp v15, v6, v6 row_ror:8 row_mask:0xf bank_mask:0x8 bound_ctrl:1
	v_pk_mul_f32 v[6:7], v[0:1], v[36:37]
	v_pk_fma_f32 v[6:7], v[2:3], v[38:39], v[6:7]
	v_add_f32_e32 v6, v6, v7
	ds_read2st64_b32 v[18:19], v90 offset0:113 offset1:119
	s_cmp_lt_u32 s28, 15
	s_cbranch_scc0 .Lls0_skip1
	global_load_dwordx4 v[112:115], v174, s[12:13]
	global_load_dwordx2 v[152:153], v175, s[14:15]
	global_load_dwordx2 v[154:155], v175, s[16:17]
	global_load_dwordx2 v[156:157], v175, s[18:19]
	global_load_dwordx4 v[116:119], v180, s[20:21]
	global_load_dword v171, v181, s[20:21]
	v_add_u32_e32 v174, s25, v174
	v_add_u32_e32 v175, s26, v175
	v_add_u32_e32 v180, s27, v180
	v_add_u32_e32 v181, s27, v181
.Lls0_back1:
	v_cndmask_b32_e64 v176, v12, v13, s[30:31]
	v_cndmask_b32_e64 v176, v176, v14, s[34:35]
	v_cndmask_b32_e64 v176, v176, v15, s[36:37]
	v_cvt_pk_bf16_f32 v176, v176, v176
	global_store_short v145, v176, s[22:23]
	v_add_u32_e32 v145, s26, v145
	s_waitcnt lgkmcnt(6)
	v_pk_mul_f32 v[4:5], v[0:1], v[48:49] neg_lo:[0,1] neg_hi:[0,1]
	ds_read_b128 v[92:95], v88 offset:29696
	v_pk_fma_f32 v[4:5], v[2:3], v[50:51], v[4:5] neg_lo:[0,1,0] neg_hi:[0,1,0]
	ds_read_b128 v[84:87], v88 offset:29440
	v_pk_mul_f32 v[8:9], v[44:45], v[16:17] op_sel:[0,1] op_sel_hi:[1,1]
	v_add_f32_e32 v4, v4, v5
	ds_read_b128 v[80:83], v88 offset:29184
	v_pk_mul_f32 v[10:11], v[46:47], v[16:17] op_sel:[0,1] op_sel_hi:[1,1]
	v_add_f32_dpp v4, v4, v4 quad_perm:[1,0,3,2] row_mask:0xf bank_mask:0xf bound_ctrl:1
	ds_read_b128 v[96:99], v88 offset:29952
	v_pk_fma_f32 v[8:9], v[0:1], v[40:41], v[8:9]
	v_add_f32_dpp v4, v4, v4 quad_perm:[2,3,0,1] row_mask:0xf bank_mask:0xf bound_ctrl:1
	v_add_f32_dpp v6, v6, v6 quad_perm:[1,0,3,2] row_mask:0xf bank_mask:0xf bound_ctrl:1
	v_pk_fma_f32 v[10:11], v[2:3], v[42:43], v[10:11]
	v_add_f32_dpp v4, v4, v4 row_ror:4 row_mask:0xf bank_mask:0xf bound_ctrl:1
	v_add_f32_dpp v6, v6, v6 quad_perm:[2,3,0,1] row_mask:0xf bank_mask:0xf bound_ctrl:1
	ds_read_b128 v[100:103], v88 offset:30208
	v_add_f32_dpp v4, v4, v4 row_ror:8 row_mask:0xf bank_mask:0xf bound_ctrl:1
	v_add_f32_dpp v6, v6, v6 row_ror:4 row_mask:0xf bank_mask:0xf bound_ctrl:1
	v_pk_fma_f32 v[0:1], v[4:5], v[52:53], v[8:9] op_sel_hi:[0,1,1]
	v_pk_fma_f32 v[2:3], v[4:5], v[54:55], v[10:11] op_sel_hi:[0,1,1]
	v_add_f32_dpp v12, v6, v6 row_ror:8 row_mask:0xf bank_mask:0x1 bound_ctrl:1
	v_pk_mul_f32 v[6:7], v[0:1], v[56:57]
	v_pk_fma_f32 v[6:7], v[2:3], v[58:59], v[6:7]
	v_add_f32_e32 v6, v6, v7
	s_waitcnt lgkmcnt(5)
	v_pk_mul_f32 v[4:5], v[0:1], v[68:69] neg_lo:[0,1] neg_hi:[0,1]
	ds_read_b128 v[28:31], v88 offset:31232
	v_pk_fma_f32 v[4:5], v[2:3], v[70:71], v[4:5] neg_lo:[0,1,0] neg_hi:[0,1,0]
	ds_read_b128 v[24:27], v88 offset:30976
	v_pk_mul_f32 v[8:9], v[64:65], v[18:19] op_sel_hi:[1,0]
	v_add_f32_e32 v4, v4, v5
	ds_read_b128 v[20:23], v88 offset:30720
	v_pk_mul_f32 v[10:11], v[66:67], v[18:19] op_sel_hi:[1,0]
	v_add_f32_dpp v4, v4, v4 quad_perm:[1,0,3,2] row_mask:0xf bank_mask:0xf bound_ctrl:1
	ds_read_b128 v[32:35], v88 offset:31488
	v_pk_fma_f32 v[8:9], v[0:1], v[60:61], v[8:9]
	v_add_f32_dpp v4, v4, v4 quad_perm:[2,3,0,1] row_mask:0xf bank_mask:0xf bound_ctrl:1
	v_add_f32_dpp v6, v6, v6 quad_perm:[1,0,3,2] row_mask:0xf bank_mask:0xf bound_ctrl:1
	v_pk_fma_f32 v[10:11], v[2:3], v[62:63], v[10:11]
	v_add_f32_dpp v4, v4, v4 row_ror:4 row_mask:0xf bank_mask:0xf bound_ctrl:1
	v_add_f32_dpp v6, v6, v6 quad_perm:[2,3,0,1] row_mask:0xf bank_mask:0xf bound_ctrl:1
	ds_read_b128 v[36:39], v88 offset:31744
	v_add_f32_dpp v4, v4, v4 row_ror:8 row_mask:0xf bank_mask:0xf bound_ctrl:1
	v_add_f32_dpp v6, v6, v6 row_ror:4 row_mask:0xf bank_mask:0xf bound_ctrl:1
	v_pk_fma_f32 v[0:1], v[4:5], v[72:73], v[8:9] op_sel_hi:[0,1,1]
	v_pk_fma_f32 v[2:3], v[4:5], v[74:75], v[10:11] op_sel_hi:[0,1,1]
	v_add_f32_dpp v13, v6, v6 row_ror:8 row_mask:0xf bank_mask:0x1 bound_ctrl:1
	v_pk_mul_f32 v[6:7], v[0:1], v[76:77]
	v_pk_fma_f32 v[6:7], v[2:3], v[78:79], v[6:7]
	v_add_f32_e32 v6, v6, v7
	ds_read2st64_b32 v[16:17], v90 offset0:125 offset1:131
	s_waitcnt lgkmcnt(6)
	v_pk_mul_f32 v[4:5], v[0:1], v[92:93] neg_lo:[0,1] neg_hi:[0,1]
	ds_read_b128 v[48:51], v88 offset:32768
	v_pk_fma_f32 v[4:5], v[2:3], v[94:95], v[4:5] neg_lo:[0,1,0] neg_hi:[0,1,0]
	ds_read_b128 v[44:47], v88 offset:32512
	v_pk_mul_f32 v[8:9], v[84:85], v[18:19] op_sel:[0,1] op_sel_hi:[1,1]
	v_add_f32_e32 v4, v4, v5
	ds_read_b128 v[40:43], v88 offset:32256
	v_pk_mul_f32 v[10:11], v[86:87], v[18:19] op_sel:[0,1] op_sel_hi:[1,1]
	v_add_f32_dpp v4, v4, v4 quad_perm:[1,0,3,2] row_mask:0xf bank_mask:0xf bound_ctrl:1
	ds_read_b128 v[52:55], v88 offset:33024
	v_pk_fma_f32 v[8:9], v[0:1], v[80:81], v[8:9]
	v_add_f32_dpp v4, v4, v4 quad_perm:[2,3,0,1] row_mask:0xf bank_mask:0xf bound_ctrl:1
	v_add_f32_dpp v6, v6, v6 quad_perm:[1,0,3,2] row_mask:0xf bank_mask:0xf bound_ctrl:1
	v_pk_fma_f32 v[10:11], v[2:3], v[82:83], v[10:11]
	v_add_f32_dpp v4, v4, v4 row_ror:4 row_mask:0xf bank_mask:0xf bound_ctrl:1
	v_add_f32_dpp v6, v6, v6 quad_perm:[2,3,0,1] row_mask:0xf bank_mask:0xf bound_ctrl:1
	ds_read_b128 v[56:59], v88 offset:33280
	v_add_f32_dpp v4, v4, v4 row_ror:8 row_mask:0xf bank_mask:0xf bound_ctrl:1
	v_add_f32_dpp v6, v6, v6 row_ror:4 row_mask:0xf bank_mask:0xf bound_ctrl:1
	v_pk_fma_f32 v[0:1], v[4:5], v[96:97], v[8:9] op_sel_hi:[0,1,1]
	v_pk_fma_f32 v[2:3], v[4:5], v[98:99], v[10:11] op_sel_hi:[0,1,1]
	v_add_f32_dpp v14, v6, v6 row_ror:8 row_mask:0xf bank_mask:0x1 bound_ctrl:1
	v_pk_mul_f32 v[6:7], v[0:1], v[100:101]
	v_pk_fma_f32 v[6:7], v[2:3], v[102:103], v[6:7]
	v_add_f32_e32 v6, v6, v7
	s_waitcnt lgkmcnt(5)
	v_pk_mul_f32 v[4:5], v[0:1], v[28:29] neg_lo:[0,1] neg_hi:[0,1]
	ds_read_b128 v[68:71], v88 offset:34304
	v_pk_fma_f32 v[4:5], v[2:3], v[30:31], v[4:5] neg_lo:[0,1,0] neg_hi:[0,1,0]
	ds_read_b128 v[64:67], v88 offset:34048
	v_pk_mul_f32 v[8:9], v[24:25], v[16:17] op_sel_hi:[1,0]
	v_add_f32_e32 v4, v4, v5
	ds_read_b128 v[60:63], v88 offset:33792
	v_pk_mul_f32 v[10:11], v[26:27], v[16:17] op_sel_hi:[1,0]
	v_add_f32_dpp v4, v4, v4 quad_perm:[1,0,3,2] row_mask:0xf bank_mask:0xf bound_ctrl:1
	ds_read_b128 v[72:75], v88 offset:34560
	v_pk_fma_f32 v[8:9], v[0:1], v[20:21], v[8:9]
	v_add_f32_dpp v4, v4, v4 quad_perm:[2,3,0,1] row_mask:0xf bank_mask:0xf bound_ctrl:1
	v_add_f32_dpp v6, v6, v6 quad_perm:[1,0,3,2] row_mask:0xf bank_mask:0xf bound_ctrl:1
	v_pk_fma_f32 v[10:11], v[2:3], v[22:23], v[10:11]
	v_add_f32_dpp v4, v4, v4 row_ror:4 row_mask:0xf bank_mask:0xf bound_ctrl:1
	v_add_f32_dpp v6, v6, v6 quad_perm:[2,3,0,1] row_mask:0xf bank_mask:0xf bound_ctrl:1
	ds_read_b128 v[76:79], v88 offset:34816
	v_add_f32_dpp v4, v4, v4 row_ror:8 row_mask:0xf bank_mask:0xf bound_ctrl:1
	v_add_f32_dpp v6, v6, v6 row_ror:4 row_mask:0xf bank_mask:0xf bound_ctrl:1
	v_pk_fma_f32 v[0:1], v[4:5], v[32:33], v[8:9] op_sel_hi:[0,1,1]
	v_pk_fma_f32 v[2:3], v[4:5], v[34:35], v[10:11] op_sel_hi:[0,1,1]
	v_add_f32_dpp v15, v6, v6 row_ror:8 row_mask:0xf bank_mask:0x1 bound_ctrl:1
	v_pk_mul_f32 v[6:7], v[0:1], v[36:37]
	v_pk_fma_f32 v[6:7], v[2:3], v[38:39], v[6:7]
	v_add_f32_e32 v6, v6, v7
	ds_read2st64_b32 v[18:19], v90 offset0:137 offset1:143
	s_waitcnt vmcnt(19)
	ds_write_b128 v91, v[120:123] offset:0
	s_waitcnt lgkmcnt(7)
	v_pk_mul_f32 v[4:5], v[0:1], v[48:49] neg_lo:[0,1] neg_hi:[0,1]
	ds_read_b128 v[92:95], v88 offset:35840
	v_pk_fma_f32 v[4:5], v[2:3], v[50:51], v[4:5] neg_lo:[0,1,0] neg_hi:[0,1,0]
	ds_read_b128 v[84:87], v88 offset:35584
	v_pk_mul_f32 v[8:9], v[44:45], v[16:17] op_sel:[0,1] op_sel_hi:[1,1]
	v_add_f32_e32 v4, v4, v5
	ds_read_b128 v[80:83], v88 offset:35328
	v_pk_mul_f32 v[10:11], v[46:47], v[16:17] op_sel:[0,1] op_sel_hi:[1,1]
	v_add_f32_dpp v4, v4, v4 quad_perm:[1,0,3,2] row_mask:0xf bank_mask:0xf bound_ctrl:1
	ds_read_b128 v[96:99], v88 offset:36096
	v_pk_fma_f32 v[8:9], v[0:1], v[40:41], v[8:9]
	v_add_f32_dpp v4, v4, v4 quad_perm:[2,3,0,1] row_mask:0xf bank_mask:0xf bound_ctrl:1
	v_add_f32_dpp v6, v6, v6 quad_perm:[1,0,3,2] row_mask:0xf bank_mask:0xf bound_ctrl:1
	v_pk_fma_f32 v[10:11], v[2:3], v[42:43], v[10:11]
	v_add_f32_dpp v4, v4, v4 row_ror:4 row_mask:0xf bank_mask:0xf bound_ctrl:1
	v_add_f32_dpp v6, v6, v6 quad_perm:[2,3,0,1] row_mask:0xf bank_mask:0xf bound_ctrl:1
	ds_read_b128 v[100:103], v88 offset:36352
	v_add_f32_dpp v4, v4, v4 row_ror:8 row_mask:0xf bank_mask:0xf bound_ctrl:1
	v_add_f32_dpp v6, v6, v6 row_ror:4 row_mask:0xf bank_mask:0xf bound_ctrl:1
	v_pk_fma_f32 v[0:1], v[4:5], v[52:53], v[8:9] op_sel_hi:[0,1,1]
	v_pk_fma_f32 v[2:3], v[4:5], v[54:55], v[10:11] op_sel_hi:[0,1,1]
	v_add_f32_dpp v12, v6, v6 row_ror:8 row_mask:0xf bank_mask:0x2 bound_ctrl:1
	v_pk_mul_f32 v[6:7], v[0:1], v[56:57]
	v_pk_fma_f32 v[6:7], v[2:3], v[58:59], v[6:7]
	v_add_f32_e32 v6, v6, v7
	ds_write_b128 v91, v[124:127] offset:1024
	ds_write_b32 v91, v172 offset:1280
	s_waitcnt lgkmcnt(8)
	v_pk_mul_f32 v[4:5], v[0:1], v[68:69] neg_lo:[0,1] neg_hi:[0,1]
	ds_read_b128 v[28:31], v88 offset:37376
	v_pk_fma_f32 v[4:5], v[2:3], v[70:71], v[4:5] neg_lo:[0,1,0] neg_hi:[0,1,0]
	ds_read_b128 v[24:27], v88 offset:37120
	v_pk_mul_f32 v[8:9], v[64:65], v[18:19] op_sel_hi:[1,0]
	v_add_f32_e32 v4, v4, v5
	ds_read_b128 v[20:23], v88 offset:36864
	v_pk_mul_f32 v[10:11], v[66:67], v[18:19] op_sel_hi:[1,0]
	v_add_f32_dpp v4, v4, v4 quad_perm:[1,0,3,2] row_mask:0xf bank_mask:0xf bound_ctrl:1
	ds_read_b128 v[32:35], v88 offset:37632
	v_pk_fma_f32 v[8:9], v[0:1], v[60:61], v[8:9]
	v_add_f32_dpp v4, v4, v4 quad_perm:[2,3,0,1] row_mask:0xf bank_mask:0xf bound_ctrl:1
	v_add_f32_dpp v6, v6, v6 quad_perm:[1,0,3,2] row_mask:0xf bank_mask:0xf bound_ctrl:1
	v_pk_fma_f32 v[10:11], v[2:3], v[62:63], v[10:11]
	v_add_f32_dpp v4, v4, v4 row_ror:4 row_mask:0xf bank_mask:0xf bound_ctrl:1
	v_add_f32_dpp v6, v6, v6 quad_perm:[2,3,0,1] row_mask:0xf bank_mask:0xf bound_ctrl:1
	ds_read_b128 v[36:39], v88 offset:37888
	v_add_f32_dpp v4, v4, v4 row_ror:8 row_mask:0xf bank_mask:0xf bound_ctrl:1
	v_add_f32_dpp v6, v6, v6 row_ror:4 row_mask:0xf bank_mask:0xf bound_ctrl:1
	v_pk_fma_f32 v[0:1], v[4:5], v[72:73], v[8:9] op_sel_hi:[0,1,1]
	v_pk_fma_f32 v[2:3], v[4:5], v[74:75], v[10:11] op_sel_hi:[0,1,1]
	v_add_f32_dpp v13, v6, v6 row_ror:8 row_mask:0xf bank_mask:0x2 bound_ctrl:1
	v_pk_mul_f32 v[6:7], v[0:1], v[76:77]
	v_pk_fma_f32 v[6:7], v[2:3], v[78:79], v[6:7]
	v_add_f32_e32 v6, v6, v7
	ds_read2st64_b32 v[16:17], v90 offset0:149 offset1:155
	v_lshlrev_b32_e32 v176, 16, v158
	v_and_b32_e32 v177, 0xffff0000, v158
	s_waitcnt lgkmcnt(8)
	v_pk_mul_f32 v[4:5], v[0:1], v[92:93] neg_lo:[0,1] neg_hi:[0,1]
	ds_read_b128 v[48:51], v88 offset:38912
	v_pk_fma_f32 v[4:5], v[2:3], v[94:95], v[4:5] neg_lo:[0,1,0] neg_hi:[0,1,0]
	ds_read_b128 v[44:47], v88 offset:38656
	v_pk_mul_f32 v[8:9], v[84:85], v[18:19] op_sel:[0,1] op_sel_hi:[1,1]
	v_add_f32_e32 v4, v4, v5
	ds_read_b128 v[40:43], v88 offset:38400
	v_pk_mul_f32 v[10:11], v[86:87], v[18:19] op_sel:[0,1] op_sel_hi:[1,1]
	v_add_f32_dpp v4, v4, v4 quad_perm:[1,0,3,2] row_mask:0xf bank_mask:0xf bound_ctrl:1
	ds_read_b128 v[52:55], v88 offset:39168
	v_pk_fma_f32 v[8:9], v[0:1], v[80:81], v[8:9]
	v_add_f32_dpp v4, v4, v4 quad_perm:[2,3,0,1] row_mask:0xf bank_mask:0xf bound_ctrl:1
	v_add_f32_dpp v6, v6, v6 quad_perm:[1,0,3,2] row_mask:0xf bank_mask:0xf bound_ctrl:1
	v_pk_fma_f32 v[10:11], v[2:3], v[82:83], v[10:11]
	v_add_f32_dpp v4, v4, v4 row_ror:4 row_mask:0xf bank_mask:0xf bound_ctrl:1
	v_add_f32_dpp v6, v6, v6 quad_perm:[2,3,0,1] row_mask:0xf bank_mask:0xf bound_ctrl:1
	ds_read_b128 v[56:59], v88 offset:39424
	v_add_f32_dpp v4, v4, v4 row_ror:8 row_mask:0xf bank_mask:0xf bound_ctrl:1
	v_add_f32_dpp v6, v6, v6 row_ror:4 row_mask:0xf bank_mask:0xf bound_ctrl:1
	v_pk_fma_f32 v[0:1], v[4:5], v[96:97], v[8:9] op_sel_hi:[0,1,1]
	v_pk_fma_f32 v[2:3], v[4:5], v[98:99], v[10:11] op_sel_hi:[0,1,1]
	v_add_f32_dpp v14, v6, v6 row_ror:8 row_mask:0xf bank_mask:0x2 bound_ctrl:1
	v_pk_mul_f32 v[6:7], v[0:1], v[100:101]
	v_pk_fma_f32 v[6:7], v[2:3], v[102:103], v[6:7]
	v_add_f32_e32 v6, v6, v7
	v_lshlrev_b32_e32 v178, 16, v159
	v_and_b32_e32 v179, 0xffff0000, v159
	s_waitcnt lgkmcnt(5)
	v_pk_mul_f32 v[4:5], v[0:1], v[28:29] neg_lo:[0,1] neg_hi:[0,1]
	ds_read_b128 v[68:71], v88 offset:40448
	v_pk_fma_f32 v[4:5], v[2:3], v[30:31], v[4:5] neg_lo:[0,1,0] neg_hi:[0,1,0]
	ds_read_b128 v[64:67], v88 offset:40192
	v_pk_mul_f32 v[8:9], v[24:25], v[16:17] op_sel_hi:[1,0]
	v_add_f32_e32 v4, v4, v5
	ds_read_b128 v[60:63], v88 offset:39936
	v_pk_mul_f32 v[10:11], v[26:27], v[16:17] op_sel_hi:[1,0]
	v_add_f32_dpp v4, v4, v4 quad_perm:[1,0,3,2] row_mask:0xf bank_mask:0xf bound_ctrl:1
	ds_read_b128 v[72:75], v88 offset:40704
	v_pk_fma_f32 v[8:9], v[0:1], v[20:21], v[8:9]
	v_add_f32_dpp v4, v4, v4 quad_perm:[2,3,0,1] row_mask:0xf bank_mask:0xf bound_ctrl:1
	v_add_f32_dpp v6, v6, v6 quad_perm:[1,0,3,2] row_mask:0xf bank_mask:0xf bound_ctrl:1
	v_pk_fma_f32 v[10:11], v[2:3], v[22:23], v[10:11]
	v_add_f32_dpp v4, v4, v4 row_ror:4 row_mask:0xf bank_mask:0xf bound_ctrl:1
	v_add_f32_dpp v6, v6, v6 quad_perm:[2,3,0,1] row_mask:0xf bank_mask:0xf bound_ctrl:1
	ds_read_b128 v[76:79], v88 offset:40960
	v_add_f32_dpp v4, v4, v4 row_ror:8 row_mask:0xf bank_mask:0xf bound_ctrl:1
	v_add_f32_dpp v6, v6, v6 row_ror:4 row_mask:0xf bank_mask:0xf bound_ctrl:1
	v_pk_fma_f32 v[0:1], v[4:5], v[32:33], v[8:9] op_sel_hi:[0,1,1]
	v_pk_fma_f32 v[2:3], v[4:5], v[34:35], v[10:11] op_sel_hi:[0,1,1]
	v_add_f32_dpp v15, v6, v6 row_ror:8 row_mask:0xf bank_mask:0x2 bound_ctrl:1
	v_pk_mul_f32 v[6:7], v[0:1], v[36:37]
	v_pk_fma_f32 v[6:7], v[2:3], v[38:39], v[6:7]
	v_add_f32_e32 v6, v6, v7
	ds_read2st64_b32 v[18:19], v90 offset0:161 offset1:167
	ds_write_b128 v91, v[176:179] offset:256
	v_lshlrev_b32_e32 v176, 16, v160
	s_waitcnt lgkmcnt(7)
	v_pk_mul_f32 v[4:5], v[0:1], v[48:49] neg_lo:[0,1] neg_hi:[0,1]
	ds_read_b128 v[92:95], v88 offset:41984
	v_pk_fma_f32 v[4:5], v[2:3], v[50:51], v[4:5] neg_lo:[0,1,0] neg_hi:[0,1,0]
	ds_read_b128 v[84:87], v88 offset:41728
	v_pk_mul_f32 v[8:9], v[44:45], v[16:17] op_sel:[0,1] op_sel_hi:[1,1]
	v_add_f32_e32 v4, v4, v5
	ds_read_b128 v[80:83], v88 offset:41472
	v_pk_mul_f32 v[10:11], v[46:47], v[16:17] op_sel:[0,1] op_sel_hi:[1,1]
	v_add_f32_dpp v4, v4, v4 quad_perm:[1,0,3,2] row_mask:0xf bank_mask:0xf bound_ctrl:1
	ds_read_b128 v[96:99], v88 offset:42240
	v_pk_fma_f32 v[8:9], v[0:1], v[40:41], v[8:9]
	v_add_f32_dpp v4, v4, v4 quad_perm:[2,3,0,1] row_mask:0xf bank_mask:0xf bound_ctrl:1
	v_add_f32_dpp v6, v6, v6 quad_perm:[1,0,3,2] row_mask:0xf bank_mask:0xf bound_ctrl:1
	v_pk_fma_f32 v[10:11], v[2:3], v[42:43], v[10:11]
	v_add_f32_dpp v4, v4, v4 row_ror:4 row_mask:0xf bank_mask:0xf bound_ctrl:1
	v_add_f32_dpp v6, v6, v6 quad_perm:[2,3,0,1] row_mask:0xf bank_mask:0xf bound_ctrl:1
	ds_read_b128 v[100:103], v88 offset:42496
	v_add_f32_dpp v4, v4, v4 row_ror:8 row_mask:0xf bank_mask:0xf bound_ctrl:1
	v_add_f32_dpp v6, v6, v6 row_ror:4 row_mask:0xf bank_mask:0xf bound_ctrl:1
	v_pk_fma_f32 v[0:1], v[4:5], v[52:53], v[8:9] op_sel_hi:[0,1,1]
	v_pk_fma_f32 v[2:3], v[4:5], v[54:55], v[10:11] op_sel_hi:[0,1,1]
	v_add_f32_dpp v12, v6, v6 row_ror:8 row_mask:0xf bank_mask:0x4 bound_ctrl:1
	v_pk_mul_f32 v[6:7], v[0:1], v[56:57]
	v_pk_fma_f32 v[6:7], v[2:3], v[58:59], v[6:7]
	v_add_f32_e32 v6, v6, v7
	v_and_b32_e32 v177, 0xffff0000, v160
	v_lshlrev_b32_e32 v178, 16, v161
	s_waitcnt lgkmcnt(6)
	v_pk_mul_f32 v[4:5], v[0:1], v[68:69] neg_lo:[0,1] neg_hi:[0,1]
	ds_read_b128 v[28:31], v88 offset:43520
	v_pk_fma_f32 v[4:5], v[2:3], v[70:71], v[4:5] neg_lo:[0,1,0] neg_hi:[0,1,0]
	ds_read_b128 v[24:27], v88 offset:43264
	v_pk_mul_f32 v[8:9], v[64:65], v[18:19] op_sel_hi:[1,0]
	v_add_f32_e32 v4, v4, v5
	ds_read_b128 v[20:23], v88 offset:43008
	v_pk_mul_f32 v[10:11], v[66:67], v[18:19] op_sel_hi:[1,0]
	v_add_f32_dpp v4, v4, v4 quad_perm:[1,0,3,2] row_mask:0xf bank_mask:0xf bound_ctrl:1
	ds_read_b128 v[32:35], v88 offset:43776
	v_pk_fma_f32 v[8:9], v[0:1], v[60:61], v[8:9]
	v_add_f32_dpp v4, v4, v4 quad_perm:[2,3,0,1] row_mask:0xf bank_mask:0xf bound_ctrl:1
	v_add_f32_dpp v6, v6, v6 quad_perm:[1,0,3,2] row_mask:0xf bank_mask:0xf bound_ctrl:1
	v_pk_fma_f32 v[10:11], v[2:3], v[62:63], v[10:11]
	v_add_f32_dpp v4, v4, v4 row_ror:4 row_mask:0xf bank_mask:0xf bound_ctrl:1
	v_add_f32_dpp v6, v6, v6 quad_perm:[2,3,0,1] row_mask:0xf bank_mask:0xf bound_ctrl:1
	ds_read_b128 v[36:39], v88 offset:44032
	v_add_f32_dpp v4, v4, v4 row_ror:8 row_mask:0xf bank_mask:0xf bound_ctrl:1
	v_add_f32_dpp v6, v6, v6 row_ror:4 row_mask:0xf bank_mask:0xf bound_ctrl:1
	v_pk_fma_f32 v[0:1], v[4:5], v[72:73], v[8:9] op_sel_hi:[0,1,1]
	v_pk_fma_f32 v[2:3], v[4:5], v[74:75], v[10:11] op_sel_hi:[0,1,1]
	v_add_f32_dpp v13, v6, v6 row_ror:8 row_mask:0xf bank_mask:0x4 bound_ctrl:1
	v_pk_mul_f32 v[6:7], v[0:1], v[76:77]
	v_pk_fma_f32 v[6:7], v[2:3], v[78:79], v[6:7]
	v_add_f32_e32 v6, v6, v7
	ds_read2st64_b32 v[16:17], v90 offset0:173 offset1:179
	v_and_b32_e32 v179, 0xffff0000, v161
	ds_write_b128 v91, v[176:179] offset:512
	s_waitcnt lgkmcnt(7)
	v_pk_mul_f32 v[4:5], v[0:1], v[92:93] neg_lo:[0,1] neg_hi:[0,1]
	ds_read_b128 v[48:51], v88 offset:45056
	v_pk_fma_f32 v[4:5], v[2:3], v[94:95], v[4:5] neg_lo:[0,1,0] neg_hi:[0,1,0]
	ds_read_b128 v[44:47], v88 offset:44800
	v_pk_mul_f32 v[8:9], v[84:85], v[18:19] op_sel:[0,1] op_sel_hi:[1,1]
	v_add_f32_e32 v4, v4, v5
	ds_read_b128 v[40:43], v88 offset:44544
	v_pk_mul_f32 v[10:11], v[86:87], v[18:19] op_sel:[0,1] op_sel_hi:[1,1]
	v_add_f32_dpp v4, v4, v4 quad_perm:[1,0,3,2] row_mask:0xf bank_mask:0xf bound_ctrl:1
	ds_read_b128 v[52:55], v88 offset:45312
	v_pk_fma_f32 v[8:9], v[0:1], v[80:81], v[8:9]
	v_add_f32_dpp v4, v4, v4 quad_perm:[2,3,0,1] row_mask:0xf bank_mask:0xf bound_ctrl:1
	v_add_f32_dpp v6, v6, v6 quad_perm:[1,0,3,2] row_mask:0xf bank_mask:0xf bound_ctrl:1
	v_pk_fma_f32 v[10:11], v[2:3], v[82:83], v[10:11]
	v_add_f32_dpp v4, v4, v4 row_ror:4 row_mask:0xf bank_mask:0xf bound_ctrl:1
	v_add_f32_dpp v6, v6, v6 quad_perm:[2,3,0,1] row_mask:0xf bank_mask:0xf bound_ctrl:1
	ds_read_b128 v[56:59], v88 offset:45568
	v_add_f32_dpp v4, v4, v4 row_ror:8 row_mask:0xf bank_mask:0xf bound_ctrl:1
	v_add_f32_dpp v6, v6, v6 row_ror:4 row_mask:0xf bank_mask:0xf bound_ctrl:1
	v_pk_fma_f32 v[0:1], v[4:5], v[96:97], v[8:9] op_sel_hi:[0,1,1]
	v_pk_fma_f32 v[2:3], v[4:5], v[98:99], v[10:11] op_sel_hi:[0,1,1]
	v_add_f32_dpp v14, v6, v6 row_ror:8 row_mask:0xf bank_mask:0x4 bound_ctrl:1
	v_pk_mul_f32 v[6:7], v[0:1], v[100:101]
	v_pk_fma_f32 v[6:7], v[2:3], v[102:103], v[6:7]
	v_add_f32_e32 v6, v6, v7
	v_lshlrev_b32_e32 v176, 16, v162
	v_and_b32_e32 v177, 0xffff0000, v162
	s_waitcnt lgkmcnt(6)
	v_pk_mul_f32 v[4:5], v[0:1], v[28:29] neg_lo:[0,1] neg_hi:[0,1]
	ds_read_b128 v[68:71], v88 offset:46592
	v_pk_fma_f32 v[4:5], v[2:3], v[30:31], v[4:5] neg_lo:[0,1,0] neg_hi:[0,1,0]
	ds_read_b128 v[64:67], v88 offset:46336
	v_pk_mul_f32 v[8:9], v[24:25], v[16:17] op_sel_hi:[1,0]
	v_add_f32_e32 v4, v4, v5
	ds_read_b128 v[60:63], v88 offset:46080
	v_pk_mul_f32 v[10:11], v[26:27], v[16:17] op_sel_hi:[1,0]
	v_add_f32_dpp v4, v4, v4 quad_perm:[1,0,3,2] row_mask:0xf bank_mask:0xf bound_ctrl:1
	ds_read_b128 v[72:75], v88 offset:46848
	v_pk_fma_f32 v[8:9], v[0:1], v[20:21], v[8:9]
	v_add_f32_dpp v4, v4, v4 quad_perm:[2,3,0,1] row_mask:0xf bank_mask:0xf bound_ctrl:1
	v_add_f32_dpp v6, v6, v6 quad_perm:[1,0,3,2] row_mask:0xf bank_mask:0xf bound_ctrl:1
	v_pk_fma_f32 v[10:11], v[2:3], v[22:23], v[10:11]
	v_add_f32_dpp v4, v4, v4 row_ror:4 row_mask:0xf bank_mask:0xf bound_ctrl:1
	v_add_f32_dpp v6, v6, v6 quad_perm:[2,3,0,1] row_mask:0xf bank_mask:0xf bound_ctrl:1
	ds_read_b128 v[76:79], v88 offset:47104
	v_add_f32_dpp v4, v4, v4 row_ror:8 row_mask:0xf bank_mask:0xf bound_ctrl:1
	v_add_f32_dpp v6, v6, v6 row_ror:4 row_mask:0xf bank_mask:0xf bound_ctrl:1
	v_pk_fma_f32 v[0:1], v[4:5], v[32:33], v[8:9] op_sel_hi:[0,1,1]
	v_pk_fma_f32 v[2:3], v[4:5], v[34:35], v[10:11] op_sel_hi:[0,1,1]
	v_add_f32_dpp v15, v6, v6 row_ror:8 row_mask:0xf bank_mask:0x4 bound_ctrl:1
	v_pk_mul_f32 v[6:7], v[0:1], v[36:37]
	v_pk_fma_f32 v[6:7], v[2:3], v[38:39], v[6:7]
	v_add_f32_e32 v6, v6, v7
	ds_read2st64_b32 v[18:19], v90 offset0:185 offset1:191
	v_lshlrev_b32_e32 v178, 16, v163
	v_and_b32_e32 v179, 0xffff0000, v163
	ds_write_b128 v91, v[176:179] offset:768
	s_waitcnt lgkmcnt(7)
	v_pk_mul_f32 v[4:5], v[0:1], v[48:49] neg_lo:[0,1] neg_hi:[0,1]
	ds_read_b128 v[92:95], v88 offset:48128
	v_pk_fma_f32 v[4:5], v[2:3], v[50:51], v[4:5] neg_lo:[0,1,0] neg_hi:[0,1,0]
	ds_read_b128 v[84:87], v88 offset:47872
	v_pk_mul_f32 v[8:9], v[44:45], v[16:17] op_sel:[0,1] op_sel_hi:[1,1]
	v_add_f32_e32 v4, v4, v5
	ds_read_b128 v[80:83], v88 offset:47616
	v_pk_mul_f32 v[10:11], v[46:47], v[16:17] op_sel:[0,1] op_sel_hi:[1,1]
	v_add_f32_dpp v4, v4, v4 quad_perm:[1,0,3,2] row_mask:0xf bank_mask:0xf bound_ctrl:1
	ds_read_b128 v[96:99], v88 offset:48384
	v_pk_fma_f32 v[8:9], v[0:1], v[40:41], v[8:9]
	v_add_f32_dpp v4, v4, v4 quad_perm:[2,3,0,1] row_mask:0xf bank_mask:0xf bound_ctrl:1
	v_add_f32_dpp v6, v6, v6 quad_perm:[1,0,3,2] row_mask:0xf bank_mask:0xf bound_ctrl:1
	v_pk_fma_f32 v[10:11], v[2:3], v[42:43], v[10:11]
	v_add_f32_dpp v4, v4, v4 row_ror:4 row_mask:0xf bank_mask:0xf bound_ctrl:1
	v_add_f32_dpp v6, v6, v6 quad_perm:[2,3,0,1] row_mask:0xf bank_mask:0xf bound_ctrl:1
	ds_read_b128 v[100:103], v88 offset:48640
	v_add_f32_dpp v4, v4, v4 row_ror:8 row_mask:0xf bank_mask:0xf bound_ctrl:1
	v_add_f32_dpp v6, v6, v6 row_ror:4 row_mask:0xf bank_mask:0xf bound_ctrl:1
	v_pk_fma_f32 v[0:1], v[4:5], v[52:53], v[8:9] op_sel_hi:[0,1,1]
	v_pk_fma_f32 v[2:3], v[4:5], v[54:55], v[10:11] op_sel_hi:[0,1,1]
	v_add_f32_dpp v12, v6, v6 row_ror:8 row_mask:0xf bank_mask:0x8 bound_ctrl:1
	v_pk_mul_f32 v[6:7], v[0:1], v[56:57]
	v_pk_fma_f32 v[6:7], v[2:3], v[58:59], v[6:7]
	v_add_f32_e32 v6, v6, v7
	s_waitcnt lgkmcnt(0)
	s_barrier
	v_pk_mul_f32 v[4:5], v[0:1], v[68:69] neg_lo:[0,1] neg_hi:[0,1]
	ds_read_b128 v[28:31], v88 offset:512
	v_pk_fma_f32 v[4:5], v[2:3], v[70:71], v[4:5] neg_lo:[0,1,0] neg_hi:[0,1,0]
	ds_read_b128 v[24:27], v88 offset:256
	v_pk_mul_f32 v[8:9], v[64:65], v[18:19] op_sel_hi:[1,0]
	v_add_f32_e32 v4, v4, v5
	ds_read_b128 v[20:23], v88 offset:0
	v_pk_mul_f32 v[10:11], v[66:67], v[18:19] op_sel_hi:[1,0]
	v_add_f32_dpp v4, v4, v4 quad_perm:[1,0,3,2] row_mask:0xf bank_mask:0xf bound_ctrl:1
	ds_read_b128 v[32:35], v88 offset:768
	v_pk_fma_f32 v[8:9], v[0:1], v[60:61], v[8:9]
	v_add_f32_dpp v4, v4, v4 quad_perm:[2,3,0,1] row_mask:0xf bank_mask:0xf bound_ctrl:1
	v_add_f32_dpp v6, v6, v6 quad_perm:[1,0,3,2] row_mask:0xf bank_mask:0xf bound_ctrl:1
	v_pk_fma_f32 v[10:11], v[2:3], v[62:63], v[10:11]
	v_add_f32_dpp v4, v4, v4 row_ror:4 row_mask:0xf bank_mask:0xf bound_ctrl:1
	v_add_f32_dpp v6, v6, v6 quad_perm:[2,3,0,1] row_mask:0xf bank_mask:0xf bound_ctrl:1
	ds_read_b128 v[36:39], v88 offset:1024
	v_add_f32_dpp v4, v4, v4 row_ror:8 row_mask:0xf bank_mask:0xf bound_ctrl:1
	v_add_f32_dpp v6, v6, v6 row_ror:4 row_mask:0xf bank_mask:0xf bound_ctrl:1
	v_pk_fma_f32 v[0:1], v[4:5], v[72:73], v[8:9] op_sel_hi:[0,1,1]
	v_pk_fma_f32 v[2:3], v[4:5], v[74:75], v[10:11] op_sel_hi:[0,1,1]
	v_add_f32_dpp v13, v6, v6 row_ror:8 row_mask:0xf bank_mask:0x8 bound_ctrl:1
	v_pk_mul_f32 v[6:7], v[0:1], v[76:77]
	v_pk_fma_f32 v[6:7], v[2:3], v[78:79], v[6:7]
	v_add_f32_e32 v6, v6, v7
	ds_read2st64_b32 v[16:17], v90 offset0:5 offset1:11
	s_waitcnt lgkmcnt(6)
	v_pk_mul_f32 v[4:5], v[0:1], v[92:93] neg_lo:[0,1] neg_hi:[0,1]
	ds_read_b128 v[48:51], v88 offset:2048
	v_pk_fma_f32 v[4:5], v[2:3], v[94:95], v[4:5] neg_lo:[0,1,0] neg_hi:[0,1,0]
	ds_read_b128 v[44:47], v88 offset:1792
	v_pk_mul_f32 v[8:9], v[84:85], v[18:19] op_sel:[0,1] op_sel_hi:[1,1]
	v_add_f32_e32 v4, v4, v5
	ds_read_b128 v[40:43], v88 offset:1536
	v_pk_mul_f32 v[10:11], v[86:87], v[18:19] op_sel:[0,1] op_sel_hi:[1,1]
	v_add_f32_dpp v4, v4, v4 quad_perm:[1,0,3,2] row_mask:0xf bank_mask:0xf bound_ctrl:1
	ds_read_b128 v[52:55], v88 offset:2304
	v_pk_fma_f32 v[8:9], v[0:1], v[80:81], v[8:9]
	v_add_f32_dpp v4, v4, v4 quad_perm:[2,3,0,1] row_mask:0xf bank_mask:0xf bound_ctrl:1
	v_add_f32_dpp v6, v6, v6 quad_perm:[1,0,3,2] row_mask:0xf bank_mask:0xf bound_ctrl:1
	v_pk_fma_f32 v[10:11], v[2:3], v[82:83], v[10:11]
	v_add_f32_dpp v4, v4, v4 row_ror:4 row_mask:0xf bank_mask:0xf bound_ctrl:1
	v_add_f32_dpp v6, v6, v6 quad_perm:[2,3,0,1] row_mask:0xf bank_mask:0xf bound_ctrl:1
	ds_read_b128 v[56:59], v88 offset:2560
	v_add_f32_dpp v4, v4, v4 row_ror:8 row_mask:0xf bank_mask:0xf bound_ctrl:1
	v_add_f32_dpp v6, v6, v6 row_ror:4 row_mask:0xf bank_mask:0xf bound_ctrl:1
	v_pk_fma_f32 v[0:1], v[4:5], v[96:97], v[8:9] op_sel_hi:[0,1,1]
	v_pk_fma_f32 v[2:3], v[4:5], v[98:99], v[10:11] op_sel_hi:[0,1,1]
	v_add_f32_dpp v14, v6, v6 row_ror:8 row_mask:0xf bank_mask:0x8 bound_ctrl:1
	v_pk_mul_f32 v[6:7], v[0:1], v[100:101]
	v_pk_fma_f32 v[6:7], v[2:3], v[102:103], v[6:7]
	v_add_f32_e32 v6, v6, v7
	s_waitcnt lgkmcnt(5)
	v_pk_mul_f32 v[4:5], v[0:1], v[28:29] neg_lo:[0,1] neg_hi:[0,1]
	ds_read_b128 v[68:71], v88 offset:3584
	v_pk_fma_f32 v[4:5], v[2:3], v[30:31], v[4:5] neg_lo:[0,1,0] neg_hi:[0,1,0]
	ds_read_b128 v[64:67], v88 offset:3328
	v_pk_mul_f32 v[8:9], v[24:25], v[16:17] op_sel_hi:[1,0]
	v_add_f32_e32 v4, v4, v5
	ds_read_b128 v[60:63], v88 offset:3072
	v_pk_mul_f32 v[10:11], v[26:27], v[16:17] op_sel_hi:[1,0]
	v_add_f32_dpp v4, v4, v4 quad_perm:[1,0,3,2] row_mask:0xf bank_mask:0xf bound_ctrl:1
	ds_read_b128 v[72:75], v88 offset:3840
	v_pk_fma_f32 v[8:9], v[0:1], v[20:21], v[8:9]
	v_add_f32_dpp v4, v4, v4 quad_perm:[2,3,0,1] row_mask:0xf bank_mask:0xf bound_ctrl:1
	v_add_f32_dpp v6, v6, v6 quad_perm:[1,0,3,2] row_mask:0xf bank_mask:0xf bound_ctrl:1
	v_pk_fma_f32 v[10:11], v[2:3], v[22:23], v[10:11]
	v_add_f32_dpp v4, v4, v4 row_ror:4 row_mask:0xf bank_mask:0xf bound_ctrl:1
	v_add_f32_dpp v6, v6, v6 quad_perm:[2,3,0,1] row_mask:0xf bank_mask:0xf bound_ctrl:1
	ds_read_b128 v[76:79], v88 offset:4096
	v_add_f32_dpp v4, v4, v4 row_ror:8 row_mask:0xf bank_mask:0xf bound_ctrl:1
	v_add_f32_dpp v6, v6, v6 row_ror:4 row_mask:0xf bank_mask:0xf bound_ctrl:1
	v_pk_fma_f32 v[0:1], v[4:5], v[32:33], v[8:9] op_sel_hi:[0,1,1]
	v_pk_fma_f32 v[2:3], v[4:5], v[34:35], v[10:11] op_sel_hi:[0,1,1]
	v_add_f32_dpp v15, v6, v6 row_ror:8 row_mask:0xf bank_mask:0x8 bound_ctrl:1
	v_pk_mul_f32 v[6:7], v[0:1], v[36:37]
	v_pk_fma_f32 v[6:7], v[2:3], v[38:39], v[6:7]
	v_add_f32_e32 v6, v6, v7
	ds_read2st64_b32 v[18:19], v90 offset0:17 offset1:23
	s_cmp_lt_u32 s28, 15
	s_cbranch_scc0 .Lls0_skip2
	global_load_dwordx4 v[120:123], v174, s[12:13]
	global_load_dwordx2 v[158:159], v175, s[14:15]
	global_load_dwordx2 v[160:161], v175, s[16:17]
	global_load_dwordx2 v[162:163], v175, s[18:19]
	global_load_dwordx4 v[124:127], v180, s[20:21]
	global_load_dword v172, v181, s[20:21]
	v_add_u32_e32 v174, s25, v174
	v_add_u32_e32 v175, s26, v175
	v_add_u32_e32 v180, s27, v180
	v_add_u32_e32 v181, s27, v181
.Lls0_back2:
	v_cndmask_b32_e64 v176, v12, v13, s[30:31]
	v_cndmask_b32_e64 v176, v176, v14, s[34:35]
	v_cndmask_b32_e64 v176, v176, v15, s[36:37]
	v_cvt_pk_bf16_f32 v176, v176, v176
	global_store_short v145, v176, s[22:23]
	v_add_u32_e32 v145, s26, v145
	s_waitcnt lgkmcnt(6)
	v_pk_mul_f32 v[4:5], v[0:1], v[48:49] neg_lo:[0,1] neg_hi:[0,1]
	ds_read_b128 v[92:95], v88 offset:5120
	v_pk_fma_f32 v[4:5], v[2:3], v[50:51], v[4:5] neg_lo:[0,1,0] neg_hi:[0,1,0]
	ds_read_b128 v[84:87], v88 offset:4864
	v_pk_mul_f32 v[8:9], v[44:45], v[16:17] op_sel:[0,1] op_sel_hi:[1,1]
	v_add_f32_e32 v4, v4, v5
	ds_read_b128 v[80:83], v88 offset:4608
	v_pk_mul_f32 v[10:11], v[46:47], v[16:17] op_sel:[0,1] op_sel_hi:[1,1]
	v_add_f32_dpp v4, v4, v4 quad_perm:[1,0,3,2] row_mask:0xf bank_mask:0xf bound_ctrl:1
	ds_read_b128 v[96:99], v88 offset:5376
	v_pk_fma_f32 v[8:9], v[0:1], v[40:41], v[8:9]
	v_add_f32_dpp v4, v4, v4 quad_perm:[2,3,0,1] row_mask:0xf bank_mask:0xf bound_ctrl:1
	v_add_f32_dpp v6, v6, v6 quad_perm:[1,0,3,2] row_mask:0xf bank_mask:0xf bound_ctrl:1
	v_pk_fma_f32 v[10:11], v[2:3], v[42:43], v[10:11]
	v_add_f32_dpp v4, v4, v4 row_ror:4 row_mask:0xf bank_mask:0xf bound_ctrl:1
	v_add_f32_dpp v6, v6, v6 quad_perm:[2,3,0,1] row_mask:0xf bank_mask:0xf bound_ctrl:1
	ds_read_b128 v[100:103], v88 offset:5632
	v_add_f32_dpp v4, v4, v4 row_ror:8 row_mask:0xf bank_mask:0xf bound_ctrl:1
	v_add_f32_dpp v6, v6, v6 row_ror:4 row_mask:0xf bank_mask:0xf bound_ctrl:1
	v_pk_fma_f32 v[0:1], v[4:5], v[52:53], v[8:9] op_sel_hi:[0,1,1]
	v_pk_fma_f32 v[2:3], v[4:5], v[54:55], v[10:11] op_sel_hi:[0,1,1]
	v_add_f32_dpp v12, v6, v6 row_ror:8 row_mask:0xf bank_mask:0x1 bound_ctrl:1
	v_pk_mul_f32 v[6:7], v[0:1], v[56:57]
	v_pk_fma_f32 v[6:7], v[2:3], v[58:59], v[6:7]
	v_add_f32_e32 v6, v6, v7
	s_waitcnt lgkmcnt(5)
	v_pk_mul_f32 v[4:5], v[0:1], v[68:69] neg_lo:[0,1] neg_hi:[0,1]
	ds_read_b128 v[28:31], v88 offset:6656
	v_pk_fma_f32 v[4:5], v[2:3], v[70:71], v[4:5] neg_lo:[0,1,0] neg_hi:[0,1,0]
	ds_read_b128 v[24:27], v88 offset:6400
	v_pk_mul_f32 v[8:9], v[64:65], v[18:19] op_sel_hi:[1,0]
	v_add_f32_e32 v4, v4, v5
	ds_read_b128 v[20:23], v88 offset:6144
	v_pk_mul_f32 v[10:11], v[66:67], v[18:19] op_sel_hi:[1,0]
	v_add_f32_dpp v4, v4, v4 quad_perm:[1,0,3,2] row_mask:0xf bank_mask:0xf bound_ctrl:1
	ds_read_b128 v[32:35], v88 offset:6912
	v_pk_fma_f32 v[8:9], v[0:1], v[60:61], v[8:9]
	v_add_f32_dpp v4, v4, v4 quad_perm:[2,3,0,1] row_mask:0xf bank_mask:0xf bound_ctrl:1
	v_add_f32_dpp v6, v6, v6 quad_perm:[1,0,3,2] row_mask:0xf bank_mask:0xf bound_ctrl:1
	v_pk_fma_f32 v[10:11], v[2:3], v[62:63], v[10:11]
	v_add_f32_dpp v4, v4, v4 row_ror:4 row_mask:0xf bank_mask:0xf bound_ctrl:1
	v_add_f32_dpp v6, v6, v6 quad_perm:[2,3,0,1] row_mask:0xf bank_mask:0xf bound_ctrl:1
	ds_read_b128 v[36:39], v88 offset:7168
	v_add_f32_dpp v4, v4, v4 row_ror:8 row_mask:0xf bank_mask:0xf bound_ctrl:1
	v_add_f32_dpp v6, v6, v6 row_ror:4 row_mask:0xf bank_mask:0xf bound_ctrl:1
	v_pk_fma_f32 v[0:1], v[4:5], v[72:73], v[8:9] op_sel_hi:[0,1,1]
	v_pk_fma_f32 v[2:3], v[4:5], v[74:75], v[10:11] op_sel_hi:[0,1,1]
	v_add_f32_dpp v13, v6, v6 row_ror:8 row_mask:0xf bank_mask:0x1 bound_ctrl:1
	v_pk_mul_f32 v[6:7], v[0:1], v[76:77]
	v_pk_fma_f32 v[6:7], v[2:3], v[78:79], v[6:7]
	v_add_f32_e32 v6, v6, v7
	ds_read2st64_b32 v[16:17], v90 offset0:29 offset1:35
	s_waitcnt lgkmcnt(6)
	v_pk_mul_f32 v[4:5], v[0:1], v[92:93] neg_lo:[0,1] neg_hi:[0,1]
	ds_read_b128 v[48:51], v88 offset:8192
	v_pk_fma_f32 v[4:5], v[2:3], v[94:95], v[4:5] neg_lo:[0,1,0] neg_hi:[0,1,0]
	ds_read_b128 v[44:47], v88 offset:7936
	v_pk_mul_f32 v[8:9], v[84:85], v[18:19] op_sel:[0,1] op_sel_hi:[1,1]
	v_add_f32_e32 v4, v4, v5
	ds_read_b128 v[40:43], v88 offset:7680
	v_pk_mul_f32 v[10:11], v[86:87], v[18:19] op_sel:[0,1] op_sel_hi:[1,1]
	v_add_f32_dpp v4, v4, v4 quad_perm:[1,0,3,2] row_mask:0xf bank_mask:0xf bound_ctrl:1
	ds_read_b128 v[52:55], v88 offset:8448
	v_pk_fma_f32 v[8:9], v[0:1], v[80:81], v[8:9]
	v_add_f32_dpp v4, v4, v4 quad_perm:[2,3,0,1] row_mask:0xf bank_mask:0xf bound_ctrl:1
	v_add_f32_dpp v6, v6, v6 quad_perm:[1,0,3,2] row_mask:0xf bank_mask:0xf bound_ctrl:1
	v_pk_fma_f32 v[10:11], v[2:3], v[82:83], v[10:11]
	v_add_f32_dpp v4, v4, v4 row_ror:4 row_mask:0xf bank_mask:0xf bound_ctrl:1
	v_add_f32_dpp v6, v6, v6 quad_perm:[2,3,0,1] row_mask:0xf bank_mask:0xf bound_ctrl:1
	ds_read_b128 v[56:59], v88 offset:8704
	v_add_f32_dpp v4, v4, v4 row_ror:8 row_mask:0xf bank_mask:0xf bound_ctrl:1
	v_add_f32_dpp v6, v6, v6 row_ror:4 row_mask:0xf bank_mask:0xf bound_ctrl:1
	v_pk_fma_f32 v[0:1], v[4:5], v[96:97], v[8:9] op_sel_hi:[0,1,1]
	v_pk_fma_f32 v[2:3], v[4:5], v[98:99], v[10:11] op_sel_hi:[0,1,1]
	v_add_f32_dpp v14, v6, v6 row_ror:8 row_mask:0xf bank_mask:0x1 bound_ctrl:1
	v_pk_mul_f32 v[6:7], v[0:1], v[100:101]
	v_pk_fma_f32 v[6:7], v[2:3], v[102:103], v[6:7]
	v_add_f32_e32 v6, v6, v7
	s_waitcnt lgkmcnt(5)
	v_pk_mul_f32 v[4:5], v[0:1], v[28:29] neg_lo:[0,1] neg_hi:[0,1]
	ds_read_b128 v[68:71], v88 offset:9728
	v_pk_fma_f32 v[4:5], v[2:3], v[30:31], v[4:5] neg_lo:[0,1,0] neg_hi:[0,1,0]
	ds_read_b128 v[64:67], v88 offset:9472
	v_pk_mul_f32 v[8:9], v[24:25], v[16:17] op_sel_hi:[1,0]
	v_add_f32_e32 v4, v4, v5
	ds_read_b128 v[60:63], v88 offset:9216
	v_pk_mul_f32 v[10:11], v[26:27], v[16:17] op_sel_hi:[1,0]
	v_add_f32_dpp v4, v4, v4 quad_perm:[1,0,3,2] row_mask:0xf bank_mask:0xf bound_ctrl:1
	ds_read_b128 v[72:75], v88 offset:9984
	v_pk_fma_f32 v[8:9], v[0:1], v[20:21], v[8:9]
	v_add_f32_dpp v4, v4, v4 quad_perm:[2,3,0,1] row_mask:0xf bank_mask:0xf bound_ctrl:1
	v_add_f32_dpp v6, v6, v6 quad_perm:[1,0,3,2] row_mask:0xf bank_mask:0xf bound_ctrl:1
	v_pk_fma_f32 v[10:11], v[2:3], v[22:23], v[10:11]
	v_add_f32_dpp v4, v4, v4 row_ror:4 row_mask:0xf bank_mask:0xf bound_ctrl:1
	v_add_f32_dpp v6, v6, v6 quad_perm:[2,3,0,1] row_mask:0xf bank_mask:0xf bound_ctrl:1
	ds_read_b128 v[76:79], v88 offset:10240
	v_add_f32_dpp v4, v4, v4 row_ror:8 row_mask:0xf bank_mask:0xf bound_ctrl:1
	v_add_f32_dpp v6, v6, v6 row_ror:4 row_mask:0xf bank_mask:0xf bound_ctrl:1
	v_pk_fma_f32 v[0:1], v[4:5], v[32:33], v[8:9] op_sel_hi:[0,1,1]
	v_pk_fma_f32 v[2:3], v[4:5], v[34:35], v[10:11] op_sel_hi:[0,1,1]
	v_add_f32_dpp v15, v6, v6 row_ror:8 row_mask:0xf bank_mask:0x1 bound_ctrl:1
	v_pk_mul_f32 v[6:7], v[0:1], v[36:37]
	v_pk_fma_f32 v[6:7], v[2:3], v[38:39], v[6:7]
	v_add_f32_e32 v6, v6, v7
	ds_read2st64_b32 v[18:19], v90 offset0:41 offset1:47
	s_waitcnt vmcnt(20)
	ds_write_b128 v91, v[128:131] offset:24576
	s_waitcnt lgkmcnt(7)
	v_pk_mul_f32 v[4:5], v[0:1], v[48:49] neg_lo:[0,1] neg_hi:[0,1]
	ds_read_b128 v[92:95], v88 offset:11264
	v_pk_fma_f32 v[4:5], v[2:3], v[50:51], v[4:5] neg_lo:[0,1,0] neg_hi:[0,1,0]
	ds_read_b128 v[84:87], v88 offset:11008
	v_pk_mul_f32 v[8:9], v[44:45], v[16:17] op_sel:[0,1] op_sel_hi:[1,1]
	v_add_f32_e32 v4, v4, v5
	ds_read_b128 v[80:83], v88 offset:10752
	v_pk_mul_f32 v[10:11], v[46:47], v[16:17] op_sel:[0,1] op_sel_hi:[1,1]
	v_add_f32_dpp v4, v4, v4 quad_perm:[1,0,3,2] row_mask:0xf bank_mask:0xf bound_ctrl:1
	ds_read_b128 v[96:99], v88 offset:11520
	v_pk_fma_f32 v[8:9], v[0:1], v[40:41], v[8:9]
	v_add_f32_dpp v4, v4, v4 quad_perm:[2,3,0,1] row_mask:0xf bank_mask:0xf bound_ctrl:1
	v_add_f32_dpp v6, v6, v6 quad_perm:[1,0,3,2] row_mask:0xf bank_mask:0xf bound_ctrl:1
	v_pk_fma_f32 v[10:11], v[2:3], v[42:43], v[10:11]
	v_add_f32_dpp v4, v4, v4 row_ror:4 row_mask:0xf bank_mask:0xf bound_ctrl:1
	v_add_f32_dpp v6, v6, v6 quad_perm:[2,3,0,1] row_mask:0xf bank_mask:0xf bound_ctrl:1
	ds_read_b128 v[100:103], v88 offset:11776
	v_add_f32_dpp v4, v4, v4 row_ror:8 row_mask:0xf bank_mask:0xf bound_ctrl:1
	v_add_f32_dpp v6, v6, v6 row_ror:4 row_mask:0xf bank_mask:0xf bound_ctrl:1
	v_pk_fma_f32 v[0:1], v[4:5], v[52:53], v[8:9] op_sel_hi:[0,1,1]
	v_pk_fma_f32 v[2:3], v[4:5], v[54:55], v[10:11] op_sel_hi:[0,1,1]
	v_add_f32_dpp v12, v6, v6 row_ror:8 row_mask:0xf bank_mask:0x2 bound_ctrl:1
	v_pk_mul_f32 v[6:7], v[0:1], v[56:57]
	v_pk_fma_f32 v[6:7], v[2:3], v[58:59], v[6:7]
	v_add_f32_e32 v6, v6, v7
	ds_write_b128 v91, v[132:135] offset:25600
	ds_write_b32 v91, v173 offset:25856
	s_waitcnt lgkmcnt(8)
	v_pk_mul_f32 v[4:5], v[0:1], v[68:69] neg_lo:[0,1] neg_hi:[0,1]
	ds_read_b128 v[28:31], v88 offset:12800
	v_pk_fma_f32 v[4:5], v[2:3], v[70:71], v[4:5] neg_lo:[0,1,0] neg_hi:[0,1,0]
	ds_read_b128 v[24:27], v88 offset:12544
	v_pk_mul_f32 v[8:9], v[64:65], v[18:19] op_sel_hi:[1,0]
	v_add_f32_e32 v4, v4, v5
	ds_read_b128 v[20:23], v88 offset:12288
	v_pk_mul_f32 v[10:11], v[66:67], v[18:19] op_sel_hi:[1,0]
	v_add_f32_dpp v4, v4, v4 quad_perm:[1,0,3,2] row_mask:0xf bank_mask:0xf bound_ctrl:1
	ds_read_b128 v[32:35], v88 offset:13056
	v_pk_fma_f32 v[8:9], v[0:1], v[60:61], v[8:9]
	v_add_f32_dpp v4, v4, v4 quad_perm:[2,3,0,1] row_mask:0xf bank_mask:0xf bound_ctrl:1
	v_add_f32_dpp v6, v6, v6 quad_perm:[1,0,3,2] row_mask:0xf bank_mask:0xf bound_ctrl:1
	v_pk_fma_f32 v[10:11], v[2:3], v[62:63], v[10:11]
	v_add_f32_dpp v4, v4, v4 row_ror:4 row_mask:0xf bank_mask:0xf bound_ctrl:1
	v_add_f32_dpp v6, v6, v6 quad_perm:[2,3,0,1] row_mask:0xf bank_mask:0xf bound_ctrl:1
	ds_read_b128 v[36:39], v88 offset:13312
	v_add_f32_dpp v4, v4, v4 row_ror:8 row_mask:0xf bank_mask:0xf bound_ctrl:1
	v_add_f32_dpp v6, v6, v6 row_ror:4 row_mask:0xf bank_mask:0xf bound_ctrl:1
	v_pk_fma_f32 v[0:1], v[4:5], v[72:73], v[8:9] op_sel_hi:[0,1,1]
	v_pk_fma_f32 v[2:3], v[4:5], v[74:75], v[10:11] op_sel_hi:[0,1,1]
	v_add_f32_dpp v13, v6, v6 row_ror:8 row_mask:0xf bank_mask:0x2 bound_ctrl:1
	v_pk_mul_f32 v[6:7], v[0:1], v[76:77]
	v_pk_fma_f32 v[6:7], v[2:3], v[78:79], v[6:7]
	v_add_f32_e32 v6, v6, v7
	ds_read2st64_b32 v[16:17], v90 offset0:53 offset1:59
	v_lshlrev_b32_e32 v176, 16, v164
	v_and_b32_e32 v177, 0xffff0000, v164
	s_waitcnt lgkmcnt(8)
	v_pk_mul_f32 v[4:5], v[0:1], v[92:93] neg_lo:[0,1] neg_hi:[0,1]
	ds_read_b128 v[48:51], v88 offset:14336
	v_pk_fma_f32 v[4:5], v[2:3], v[94:95], v[4:5] neg_lo:[0,1,0] neg_hi:[0,1,0]
	ds_read_b128 v[44:47], v88 offset:14080
	v_pk_mul_f32 v[8:9], v[84:85], v[18:19] op_sel:[0,1] op_sel_hi:[1,1]
	v_add_f32_e32 v4, v4, v5
	ds_read_b128 v[40:43], v88 offset:13824
	v_pk_mul_f32 v[10:11], v[86:87], v[18:19] op_sel:[0,1] op_sel_hi:[1,1]
	v_add_f32_dpp v4, v4, v4 quad_perm:[1,0,3,2] row_mask:0xf bank_mask:0xf bound_ctrl:1
	ds_read_b128 v[52:55], v88 offset:14592
	v_pk_fma_f32 v[8:9], v[0:1], v[80:81], v[8:9]
	v_add_f32_dpp v4, v4, v4 quad_perm:[2,3,0,1] row_mask:0xf bank_mask:0xf bound_ctrl:1
	v_add_f32_dpp v6, v6, v6 quad_perm:[1,0,3,2] row_mask:0xf bank_mask:0xf bound_ctrl:1
	v_pk_fma_f32 v[10:11], v[2:3], v[82:83], v[10:11]
	v_add_f32_dpp v4, v4, v4 row_ror:4 row_mask:0xf bank_mask:0xf bound_ctrl:1
	v_add_f32_dpp v6, v6, v6 quad_perm:[2,3,0,1] row_mask:0xf bank_mask:0xf bound_ctrl:1
	ds_read_b128 v[56:59], v88 offset:14848
	v_add_f32_dpp v4, v4, v4 row_ror:8 row_mask:0xf bank_mask:0xf bound_ctrl:1
	v_add_f32_dpp v6, v6, v6 row_ror:4 row_mask:0xf bank_mask:0xf bound_ctrl:1
	v_pk_fma_f32 v[0:1], v[4:5], v[96:97], v[8:9] op_sel_hi:[0,1,1]
	v_pk_fma_f32 v[2:3], v[4:5], v[98:99], v[10:11] op_sel_hi:[0,1,1]
	v_add_f32_dpp v14, v6, v6 row_ror:8 row_mask:0xf bank_mask:0x2 bound_ctrl:1
	v_pk_mul_f32 v[6:7], v[0:1], v[100:101]
	v_pk_fma_f32 v[6:7], v[2:3], v[102:103], v[6:7]
	v_add_f32_e32 v6, v6, v7
	v_lshlrev_b32_e32 v178, 16, v165
	v_and_b32_e32 v179, 0xffff0000, v165
	s_waitcnt lgkmcnt(5)
	v_pk_mul_f32 v[4:5], v[0:1], v[28:29] neg_lo:[0,1] neg_hi:[0,1]
	ds_read_b128 v[68:71], v88 offset:15872
	v_pk_fma_f32 v[4:5], v[2:3], v[30:31], v[4:5] neg_lo:[0,1,0] neg_hi:[0,1,0]
	ds_read_b128 v[64:67], v88 offset:15616
	v_pk_mul_f32 v[8:9], v[24:25], v[16:17] op_sel_hi:[1,0]
	v_add_f32_e32 v4, v4, v5
	ds_read_b128 v[60:63], v88 offset:15360
	v_pk_mul_f32 v[10:11], v[26:27], v[16:17] op_sel_hi:[1,0]
	v_add_f32_dpp v4, v4, v4 quad_perm:[1,0,3,2] row_mask:0xf bank_mask:0xf bound_ctrl:1
	ds_read_b128 v[72:75], v88 offset:16128
	v_pk_fma_f32 v[8:9], v[0:1], v[20:21], v[8:9]
	v_add_f32_dpp v4, v4, v4 quad_perm:[2,3,0,1] row_mask:0xf bank_mask:0xf bound_ctrl:1
	v_add_f32_dpp v6, v6, v6 quad_perm:[1,0,3,2] row_mask:0xf bank_mask:0xf bound_ctrl:1
	v_pk_fma_f32 v[10:11], v[2:3], v[22:23], v[10:11]
	v_add_f32_dpp v4, v4, v4 row_ror:4 row_mask:0xf bank_mask:0xf bound_ctrl:1
	v_add_f32_dpp v6, v6, v6 quad_perm:[2,3,0,1] row_mask:0xf bank_mask:0xf bound_ctrl:1
	ds_read_b128 v[76:79], v88 offset:16384
	v_add_f32_dpp v4, v4, v4 row_ror:8 row_mask:0xf bank_mask:0xf bound_ctrl:1
	v_add_f32_dpp v6, v6, v6 row_ror:4 row_mask:0xf bank_mask:0xf bound_ctrl:1
	v_pk_fma_f32 v[0:1], v[4:5], v[32:33], v[8:9] op_sel_hi:[0,1,1]
	v_pk_fma_f32 v[2:3], v[4:5], v[34:35], v[10:11] op_sel_hi:[0,1,1]
	v_add_f32_dpp v15, v6, v6 row_ror:8 row_mask:0xf bank_mask:0x2 bound_ctrl:1
	v_pk_mul_f32 v[6:7], v[0:1], v[36:37]
	v_pk_fma_f32 v[6:7], v[2:3], v[38:39], v[6:7]
	v_add_f32_e32 v6, v6, v7
	ds_read2st64_b32 v[18:19], v90 offset0:65 offset1:71
	ds_write_b128 v91, v[176:179] offset:24832
	v_lshlrev_b32_e32 v176, 16, v166
	s_waitcnt lgkmcnt(7)
	v_pk_mul_f32 v[4:5], v[0:1], v[48:49] neg_lo:[0,1] neg_hi:[0,1]
	ds_read_b128 v[92:95], v88 offset:17408
	v_pk_fma_f32 v[4:5], v[2:3], v[50:51], v[4:5] neg_lo:[0,1,0] neg_hi:[0,1,0]
	ds_read_b128 v[84:87], v88 offset:17152
	v_pk_mul_f32 v[8:9], v[44:45], v[16:17] op_sel:[0,1] op_sel_hi:[1,1]
	v_add_f32_e32 v4, v4, v5
	ds_read_b128 v[80:83], v88 offset:16896
	v_pk_mul_f32 v[10:11], v[46:47], v[16:17] op_sel:[0,1] op_sel_hi:[1,1]
	v_add_f32_dpp v4, v4, v4 quad_perm:[1,0,3,2] row_mask:0xf bank_mask:0xf bound_ctrl:1
	ds_read_b128 v[96:99], v88 offset:17664
	v_pk_fma_f32 v[8:9], v[0:1], v[40:41], v[8:9]
	v_add_f32_dpp v4, v4, v4 quad_perm:[2,3,0,1] row_mask:0xf bank_mask:0xf bound_ctrl:1
	v_add_f32_dpp v6, v6, v6 quad_perm:[1,0,3,2] row_mask:0xf bank_mask:0xf bound_ctrl:1
	v_pk_fma_f32 v[10:11], v[2:3], v[42:43], v[10:11]
	v_add_f32_dpp v4, v4, v4 row_ror:4 row_mask:0xf bank_mask:0xf bound_ctrl:1
	v_add_f32_dpp v6, v6, v6 quad_perm:[2,3,0,1] row_mask:0xf bank_mask:0xf bound_ctrl:1
	ds_read_b128 v[100:103], v88 offset:17920
	v_add_f32_dpp v4, v4, v4 row_ror:8 row_mask:0xf bank_mask:0xf bound_ctrl:1
	v_add_f32_dpp v6, v6, v6 row_ror:4 row_mask:0xf bank_mask:0xf bound_ctrl:1
	v_pk_fma_f32 v[0:1], v[4:5], v[52:53], v[8:9] op_sel_hi:[0,1,1]
	v_pk_fma_f32 v[2:3], v[4:5], v[54:55], v[10:11] op_sel_hi:[0,1,1]
	v_add_f32_dpp v12, v6, v6 row_ror:8 row_mask:0xf bank_mask:0x4 bound_ctrl:1
	v_pk_mul_f32 v[6:7], v[0:1], v[56:57]
	v_pk_fma_f32 v[6:7], v[2:3], v[58:59], v[6:7]
	v_add_f32_e32 v6, v6, v7
	v_and_b32_e32 v177, 0xffff0000, v166
	v_lshlrev_b32_e32 v178, 16, v167
	s_waitcnt lgkmcnt(6)
	v_pk_mul_f32 v[4:5], v[0:1], v[68:69] neg_lo:[0,1] neg_hi:[0,1]
	ds_read_b128 v[28:31], v88 offset:18944
	v_pk_fma_f32 v[4:5], v[2:3], v[70:71], v[4:5] neg_lo:[0,1,0] neg_hi:[0,1,0]
	ds_read_b128 v[24:27], v88 offset:18688
	v_pk_mul_f32 v[8:9], v[64:65], v[18:19] op_sel_hi:[1,0]
	v_add_f32_e32 v4, v4, v5
	ds_read_b128 v[20:23], v88 offset:18432
	v_pk_mul_f32 v[10:11], v[66:67], v[18:19] op_sel_hi:[1,0]
	v_add_f32_dpp v4, v4, v4 quad_perm:[1,0,3,2] row_mask:0xf bank_mask:0xf bound_ctrl:1
	ds_read_b128 v[32:35], v88 offset:19200
	v_pk_fma_f32 v[8:9], v[0:1], v[60:61], v[8:9]
	v_add_f32_dpp v4, v4, v4 quad_perm:[2,3,0,1] row_mask:0xf bank_mask:0xf bound_ctrl:1
	v_add_f32_dpp v6, v6, v6 quad_perm:[1,0,3,2] row_mask:0xf bank_mask:0xf bound_ctrl:1
	v_pk_fma_f32 v[10:11], v[2:3], v[62:63], v[10:11]
	v_add_f32_dpp v4, v4, v4 row_ror:4 row_mask:0xf bank_mask:0xf bound_ctrl:1
	v_add_f32_dpp v6, v6, v6 quad_perm:[2,3,0,1] row_mask:0xf bank_mask:0xf bound_ctrl:1
	ds_read_b128 v[36:39], v88 offset:19456
	v_add_f32_dpp v4, v4, v4 row_ror:8 row_mask:0xf bank_mask:0xf bound_ctrl:1
	v_add_f32_dpp v6, v6, v6 row_ror:4 row_mask:0xf bank_mask:0xf bound_ctrl:1
	v_pk_fma_f32 v[0:1], v[4:5], v[72:73], v[8:9] op_sel_hi:[0,1,1]
	v_pk_fma_f32 v[2:3], v[4:5], v[74:75], v[10:11] op_sel_hi:[0,1,1]
	v_add_f32_dpp v13, v6, v6 row_ror:8 row_mask:0xf bank_mask:0x4 bound_ctrl:1
	v_pk_mul_f32 v[6:7], v[0:1], v[76:77]
	v_pk_fma_f32 v[6:7], v[2:3], v[78:79], v[6:7]
	v_add_f32_e32 v6, v6, v7
	ds_read2st64_b32 v[16:17], v90 offset0:77 offset1:83
	v_and_b32_e32 v179, 0xffff0000, v167
	ds_write_b128 v91, v[176:179] offset:25088
	s_waitcnt lgkmcnt(7)
	v_pk_mul_f32 v[4:5], v[0:1], v[92:93] neg_lo:[0,1] neg_hi:[0,1]
	ds_read_b128 v[48:51], v88 offset:20480
	v_pk_fma_f32 v[4:5], v[2:3], v[94:95], v[4:5] neg_lo:[0,1,0] neg_hi:[0,1,0]
	ds_read_b128 v[44:47], v88 offset:20224
	v_pk_mul_f32 v[8:9], v[84:85], v[18:19] op_sel:[0,1] op_sel_hi:[1,1]
	v_add_f32_e32 v4, v4, v5
	ds_read_b128 v[40:43], v88 offset:19968
	v_pk_mul_f32 v[10:11], v[86:87], v[18:19] op_sel:[0,1] op_sel_hi:[1,1]
	v_add_f32_dpp v4, v4, v4 quad_perm:[1,0,3,2] row_mask:0xf bank_mask:0xf bound_ctrl:1
	ds_read_b128 v[52:55], v88 offset:20736
	v_pk_fma_f32 v[8:9], v[0:1], v[80:81], v[8:9]
	v_add_f32_dpp v4, v4, v4 quad_perm:[2,3,0,1] row_mask:0xf bank_mask:0xf bound_ctrl:1
	v_add_f32_dpp v6, v6, v6 quad_perm:[1,0,3,2] row_mask:0xf bank_mask:0xf bound_ctrl:1
	v_pk_fma_f32 v[10:11], v[2:3], v[82:83], v[10:11]
	v_add_f32_dpp v4, v4, v4 row_ror:4 row_mask:0xf bank_mask:0xf bound_ctrl:1
	v_add_f32_dpp v6, v6, v6 quad_perm:[2,3,0,1] row_mask:0xf bank_mask:0xf bound_ctrl:1
	ds_read_b128 v[56:59], v88 offset:20992
	v_add_f32_dpp v4, v4, v4 row_ror:8 row_mask:0xf bank_mask:0xf bound_ctrl:1
	v_add_f32_dpp v6, v6, v6 row_ror:4 row_mask:0xf bank_mask:0xf bound_ctrl:1
	v_pk_fma_f32 v[0:1], v[4:5], v[96:97], v[8:9] op_sel_hi:[0,1,1]
	v_pk_fma_f32 v[2:3], v[4:5], v[98:99], v[10:11] op_sel_hi:[0,1,1]
	v_add_f32_dpp v14, v6, v6 row_ror:8 row_mask:0xf bank_mask:0x4 bound_ctrl:1
	v_pk_mul_f32 v[6:7], v[0:1], v[100:101]
	v_pk_fma_f32 v[6:7], v[2:3], v[102:103], v[6:7]
	v_add_f32_e32 v6, v6, v7
	v_lshlrev_b32_e32 v176, 16, v168
	v_and_b32_e32 v177, 0xffff0000, v168
	s_waitcnt lgkmcnt(6)
	v_pk_mul_f32 v[4:5], v[0:1], v[28:29] neg_lo:[0,1] neg_hi:[0,1]
	ds_read_b128 v[68:71], v88 offset:22016
	v_pk_fma_f32 v[4:5], v[2:3], v[30:31], v[4:5] neg_lo:[0,1,0] neg_hi:[0,1,0]
	ds_read_b128 v[64:67], v88 offset:21760
	v_pk_mul_f32 v[8:9], v[24:25], v[16:17] op_sel_hi:[1,0]
	v_add_f32_e32 v4, v4, v5
	ds_read_b128 v[60:63], v88 offset:21504
	v_pk_mul_f32 v[10:11], v[26:27], v[16:17] op_sel_hi:[1,0]
	v_add_f32_dpp v4, v4, v4 quad_perm:[1,0,3,2] row_mask:0xf bank_mask:0xf bound_ctrl:1
	ds_read_b128 v[72:75], v88 offset:22272
	v_pk_fma_f32 v[8:9], v[0:1], v[20:21], v[8:9]
	v_add_f32_dpp v4, v4, v4 quad_perm:[2,3,0,1] row_mask:0xf bank_mask:0xf bound_ctrl:1
	v_add_f32_dpp v6, v6, v6 quad_perm:[1,0,3,2] row_mask:0xf bank_mask:0xf bound_ctrl:1
	v_pk_fma_f32 v[10:11], v[2:3], v[22:23], v[10:11]
	v_add_f32_dpp v4, v4, v4 row_ror:4 row_mask:0xf bank_mask:0xf bound_ctrl:1
	v_add_f32_dpp v6, v6, v6 quad_perm:[2,3,0,1] row_mask:0xf bank_mask:0xf bound_ctrl:1
	ds_read_b128 v[76:79], v88 offset:22528
	v_add_f32_dpp v4, v4, v4 row_ror:8 row_mask:0xf bank_mask:0xf bound_ctrl:1
	v_add_f32_dpp v6, v6, v6 row_ror:4 row_mask:0xf bank_mask:0xf bound_ctrl:1
	v_pk_fma_f32 v[0:1], v[4:5], v[32:33], v[8:9] op_sel_hi:[0,1,1]
	v_pk_fma_f32 v[2:3], v[4:5], v[34:35], v[10:11] op_sel_hi:[0,1,1]
	v_add_f32_dpp v15, v6, v6 row_ror:8 row_mask:0xf bank_mask:0x4 bound_ctrl:1
	v_pk_mul_f32 v[6:7], v[0:1], v[36:37]
	v_pk_fma_f32 v[6:7], v[2:3], v[38:39], v[6:7]
	v_add_f32_e32 v6, v6, v7
	ds_read2st64_b32 v[18:19], v90 offset0:89 offset1:95
	v_lshlrev_b32_e32 v178, 16, v169
	v_and_b32_e32 v179, 0xffff0000, v169
	ds_write_b128 v91, v[176:179] offset:25344
	s_waitcnt lgkmcnt(7)
	v_pk_mul_f32 v[4:5], v[0:1], v[48:49] neg_lo:[0,1] neg_hi:[0,1]
	ds_read_b128 v[92:95], v88 offset:23552
	v_pk_fma_f32 v[4:5], v[2:3], v[50:51], v[4:5] neg_lo:[0,1,0] neg_hi:[0,1,0]
	ds_read_b128 v[84:87], v88 offset:23296
	v_pk_mul_f32 v[8:9], v[44:45], v[16:17] op_sel:[0,1] op_sel_hi:[1,1]
	v_add_f32_e32 v4, v4, v5
	ds_read_b128 v[80:83], v88 offset:23040
	v_pk_mul_f32 v[10:11], v[46:47], v[16:17] op_sel:[0,1] op_sel_hi:[1,1]
	v_add_f32_dpp v4, v4, v4 quad_perm:[1,0,3,2] row_mask:0xf bank_mask:0xf bound_ctrl:1
	ds_read_b128 v[96:99], v88 offset:23808
	v_pk_fma_f32 v[8:9], v[0:1], v[40:41], v[8:9]
	v_add_f32_dpp v4, v4, v4 quad_perm:[2,3,0,1] row_mask:0xf bank_mask:0xf bound_ctrl:1
	v_add_f32_dpp v6, v6, v6 quad_perm:[1,0,3,2] row_mask:0xf bank_mask:0xf bound_ctrl:1
	v_pk_fma_f32 v[10:11], v[2:3], v[42:43], v[10:11]
	v_add_f32_dpp v4, v4, v4 row_ror:4 row_mask:0xf bank_mask:0xf bound_ctrl:1
	v_add_f32_dpp v6, v6, v6 quad_perm:[2,3,0,1] row_mask:0xf bank_mask:0xf bound_ctrl:1
	ds_read_b128 v[100:103], v88 offset:24064
	v_add_f32_dpp v4, v4, v4 row_ror:8 row_mask:0xf bank_mask:0xf bound_ctrl:1
	v_add_f32_dpp v6, v6, v6 row_ror:4 row_mask:0xf bank_mask:0xf bound_ctrl:1
	v_pk_fma_f32 v[0:1], v[4:5], v[52:53], v[8:9] op_sel_hi:[0,1,1]
	v_pk_fma_f32 v[2:3], v[4:5], v[54:55], v[10:11] op_sel_hi:[0,1,1]
	v_add_f32_dpp v12, v6, v6 row_ror:8 row_mask:0xf bank_mask:0x8 bound_ctrl:1
	v_pk_mul_f32 v[6:7], v[0:1], v[56:57]
	v_pk_fma_f32 v[6:7], v[2:3], v[58:59], v[6:7]
	v_add_f32_e32 v6, v6, v7
	s_waitcnt lgkmcnt(0)
	s_barrier
	v_pk_mul_f32 v[4:5], v[0:1], v[68:69] neg_lo:[0,1] neg_hi:[0,1]
	ds_read_b128 v[28:31], v88 offset:25088
	v_pk_fma_f32 v[4:5], v[2:3], v[70:71], v[4:5] neg_lo:[0,1,0] neg_hi:[0,1,0]
	ds_read_b128 v[24:27], v88 offset:24832
	v_pk_mul_f32 v[8:9], v[64:65], v[18:19] op_sel_hi:[1,0]
	v_add_f32_e32 v4, v4, v5
	ds_read_b128 v[20:23], v88 offset:24576
	v_pk_mul_f32 v[10:11], v[66:67], v[18:19] op_sel_hi:[1,0]
	v_add_f32_dpp v4, v4, v4 quad_perm:[1,0,3,2] row_mask:0xf bank_mask:0xf bound_ctrl:1
	ds_read_b128 v[32:35], v88 offset:25344
	v_pk_fma_f32 v[8:9], v[0:1], v[60:61], v[8:9]
	v_add_f32_dpp v4, v4, v4 quad_perm:[2,3,0,1] row_mask:0xf bank_mask:0xf bound_ctrl:1
	v_add_f32_dpp v6, v6, v6 quad_perm:[1,0,3,2] row_mask:0xf bank_mask:0xf bound_ctrl:1
	v_pk_fma_f32 v[10:11], v[2:3], v[62:63], v[10:11]
	v_add_f32_dpp v4, v4, v4 row_ror:4 row_mask:0xf bank_mask:0xf bound_ctrl:1
	v_add_f32_dpp v6, v6, v6 quad_perm:[2,3,0,1] row_mask:0xf bank_mask:0xf bound_ctrl:1
	ds_read_b128 v[36:39], v88 offset:25600
	v_add_f32_dpp v4, v4, v4 row_ror:8 row_mask:0xf bank_mask:0xf bound_ctrl:1
	v_add_f32_dpp v6, v6, v6 row_ror:4 row_mask:0xf bank_mask:0xf bound_ctrl:1
	v_pk_fma_f32 v[0:1], v[4:5], v[72:73], v[8:9] op_sel_hi:[0,1,1]
	v_pk_fma_f32 v[2:3], v[4:5], v[74:75], v[10:11] op_sel_hi:[0,1,1]
	v_add_f32_dpp v13, v6, v6 row_ror:8 row_mask:0xf bank_mask:0x8 bound_ctrl:1
	v_pk_mul_f32 v[6:7], v[0:1], v[76:77]
	v_pk_fma_f32 v[6:7], v[2:3], v[78:79], v[6:7]
	v_add_f32_e32 v6, v6, v7
	ds_read2st64_b32 v[16:17], v90 offset0:101 offset1:107
	s_waitcnt lgkmcnt(6)
	v_pk_mul_f32 v[4:5], v[0:1], v[92:93] neg_lo:[0,1] neg_hi:[0,1]
	ds_read_b128 v[48:51], v88 offset:26624
	v_pk_fma_f32 v[4:5], v[2:3], v[94:95], v[4:5] neg_lo:[0,1,0] neg_hi:[0,1,0]
	ds_read_b128 v[44:47], v88 offset:26368
	v_pk_mul_f32 v[8:9], v[84:85], v[18:19] op_sel:[0,1] op_sel_hi:[1,1]
	v_add_f32_e32 v4, v4, v5
	ds_read_b128 v[40:43], v88 offset:26112
	v_pk_mul_f32 v[10:11], v[86:87], v[18:19] op_sel:[0,1] op_sel_hi:[1,1]
	v_add_f32_dpp v4, v4, v4 quad_perm:[1,0,3,2] row_mask:0xf bank_mask:0xf bound_ctrl:1
	ds_read_b128 v[52:55], v88 offset:26880
	v_pk_fma_f32 v[8:9], v[0:1], v[80:81], v[8:9]
	v_add_f32_dpp v4, v4, v4 quad_perm:[2,3,0,1] row_mask:0xf bank_mask:0xf bound_ctrl:1
	v_add_f32_dpp v6, v6, v6 quad_perm:[1,0,3,2] row_mask:0xf bank_mask:0xf bound_ctrl:1
	v_pk_fma_f32 v[10:11], v[2:3], v[82:83], v[10:11]
	v_add_f32_dpp v4, v4, v4 row_ror:4 row_mask:0xf bank_mask:0xf bound_ctrl:1
	v_add_f32_dpp v6, v6, v6 quad_perm:[2,3,0,1] row_mask:0xf bank_mask:0xf bound_ctrl:1
	ds_read_b128 v[56:59], v88 offset:27136
	v_add_f32_dpp v4, v4, v4 row_ror:8 row_mask:0xf bank_mask:0xf bound_ctrl:1
	v_add_f32_dpp v6, v6, v6 row_ror:4 row_mask:0xf bank_mask:0xf bound_ctrl:1
	v_pk_fma_f32 v[0:1], v[4:5], v[96:97], v[8:9] op_sel_hi:[0,1,1]
	v_pk_fma_f32 v[2:3], v[4:5], v[98:99], v[10:11] op_sel_hi:[0,1,1]
	v_add_f32_dpp v14, v6, v6 row_ror:8 row_mask:0xf bank_mask:0x8 bound_ctrl:1
	v_pk_mul_f32 v[6:7], v[0:1], v[100:101]
	v_pk_fma_f32 v[6:7], v[2:3], v[102:103], v[6:7]
	v_add_f32_e32 v6, v6, v7
	s_waitcnt lgkmcnt(5)
	v_pk_mul_f32 v[4:5], v[0:1], v[28:29] neg_lo:[0,1] neg_hi:[0,1]
	ds_read_b128 v[68:71], v88 offset:28160
	v_pk_fma_f32 v[4:5], v[2:3], v[30:31], v[4:5] neg_lo:[0,1,0] neg_hi:[0,1,0]
	ds_read_b128 v[64:67], v88 offset:27904
	v_pk_mul_f32 v[8:9], v[24:25], v[16:17] op_sel_hi:[1,0]
	v_add_f32_e32 v4, v4, v5
	ds_read_b128 v[60:63], v88 offset:27648
	v_pk_mul_f32 v[10:11], v[26:27], v[16:17] op_sel_hi:[1,0]
	v_add_f32_dpp v4, v4, v4 quad_perm:[1,0,3,2] row_mask:0xf bank_mask:0xf bound_ctrl:1
	ds_read_b128 v[72:75], v88 offset:28416
	v_pk_fma_f32 v[8:9], v[0:1], v[20:21], v[8:9]
	v_add_f32_dpp v4, v4, v4 quad_perm:[2,3,0,1] row_mask:0xf bank_mask:0xf bound_ctrl:1
	v_add_f32_dpp v6, v6, v6 quad_perm:[1,0,3,2] row_mask:0xf bank_mask:0xf bound_ctrl:1
	v_pk_fma_f32 v[10:11], v[2:3], v[22:23], v[10:11]
	v_add_f32_dpp v4, v4, v4 row_ror:4 row_mask:0xf bank_mask:0xf bound_ctrl:1
	v_add_f32_dpp v6, v6, v6 quad_perm:[2,3,0,1] row_mask:0xf bank_mask:0xf bound_ctrl:1
	ds_read_b128 v[76:79], v88 offset:28672
	v_add_f32_dpp v4, v4, v4 row_ror:8 row_mask:0xf bank_mask:0xf bound_ctrl:1
	v_add_f32_dpp v6, v6, v6 row_ror:4 row_mask:0xf bank_mask:0xf bound_ctrl:1
	v_pk_fma_f32 v[0:1], v[4:5], v[32:33], v[8:9] op_sel_hi:[0,1,1]
	v_pk_fma_f32 v[2:3], v[4:5], v[34:35], v[10:11] op_sel_hi:[0,1,1]
	v_add_f32_dpp v15, v6, v6 row_ror:8 row_mask:0xf bank_mask:0x8 bound_ctrl:1
	v_pk_mul_f32 v[6:7], v[0:1], v[36:37]
	v_pk_fma_f32 v[6:7], v[2:3], v[38:39], v[6:7]
	v_add_f32_e32 v6, v6, v7
	ds_read2st64_b32 v[18:19], v90 offset0:113 offset1:119
	s_cmp_lt_u32 s28, 15
	s_cbranch_scc0 .Lls0_skip3
	global_load_dwordx4 v[128:131], v174, s[12:13]
	global_load_dwordx2 v[164:165], v175, s[14:15]
	global_load_dwordx2 v[166:167], v175, s[16:17]
	global_load_dwordx2 v[168:169], v175, s[18:19]
	global_load_dwordx4 v[132:135], v180, s[20:21]
	global_load_dword v173, v181, s[20:21]
	v_add_u32_e32 v174, s25, v174
	v_add_u32_e32 v175, s26, v175
	v_add_u32_e32 v180, s27, v180
	v_add_u32_e32 v181, s27, v181
.Lls0_back3:
	v_cndmask_b32_e64 v176, v12, v13, s[30:31]
	v_cndmask_b32_e64 v176, v176, v14, s[34:35]
	v_cndmask_b32_e64 v176, v176, v15, s[36:37]
	v_cvt_pk_bf16_f32 v176, v176, v176
	global_store_short v145, v176, s[22:23]
	v_add_u32_e32 v145, s26, v145
	s_waitcnt lgkmcnt(6)
	v_pk_mul_f32 v[4:5], v[0:1], v[48:49] neg_lo:[0,1] neg_hi:[0,1]
	ds_read_b128 v[92:95], v88 offset:29696
	v_pk_fma_f32 v[4:5], v[2:3], v[50:51], v[4:5] neg_lo:[0,1,0] neg_hi:[0,1,0]
	ds_read_b128 v[84:87], v88 offset:29440
	v_pk_mul_f32 v[8:9], v[44:45], v[16:17] op_sel:[0,1] op_sel_hi:[1,1]
	v_add_f32_e32 v4, v4, v5
	ds_read_b128 v[80:83], v88 offset:29184
	v_pk_mul_f32 v[10:11], v[46:47], v[16:17] op_sel:[0,1] op_sel_hi:[1,1]
	v_add_f32_dpp v4, v4, v4 quad_perm:[1,0,3,2] row_mask:0xf bank_mask:0xf bound_ctrl:1
	ds_read_b128 v[96:99], v88 offset:29952
	v_pk_fma_f32 v[8:9], v[0:1], v[40:41], v[8:9]
	v_add_f32_dpp v4, v4, v4 quad_perm:[2,3,0,1] row_mask:0xf bank_mask:0xf bound_ctrl:1
	v_add_f32_dpp v6, v6, v6 quad_perm:[1,0,3,2] row_mask:0xf bank_mask:0xf bound_ctrl:1
	v_pk_fma_f32 v[10:11], v[2:3], v[42:43], v[10:11]
	v_add_f32_dpp v4, v4, v4 row_ror:4 row_mask:0xf bank_mask:0xf bound_ctrl:1
	v_add_f32_dpp v6, v6, v6 quad_perm:[2,3,0,1] row_mask:0xf bank_mask:0xf bound_ctrl:1
	ds_read_b128 v[100:103], v88 offset:30208
	v_add_f32_dpp v4, v4, v4 row_ror:8 row_mask:0xf bank_mask:0xf bound_ctrl:1
	v_add_f32_dpp v6, v6, v6 row_ror:4 row_mask:0xf bank_mask:0xf bound_ctrl:1
	v_pk_fma_f32 v[0:1], v[4:5], v[52:53], v[8:9] op_sel_hi:[0,1,1]
	v_pk_fma_f32 v[2:3], v[4:5], v[54:55], v[10:11] op_sel_hi:[0,1,1]
	v_add_f32_dpp v12, v6, v6 row_ror:8 row_mask:0xf bank_mask:0x1 bound_ctrl:1
	v_pk_mul_f32 v[6:7], v[0:1], v[56:57]
	v_pk_fma_f32 v[6:7], v[2:3], v[58:59], v[6:7]
	v_add_f32_e32 v6, v6, v7
	s_waitcnt lgkmcnt(5)
	v_pk_mul_f32 v[4:5], v[0:1], v[68:69] neg_lo:[0,1] neg_hi:[0,1]
	ds_read_b128 v[28:31], v88 offset:31232
	v_pk_fma_f32 v[4:5], v[2:3], v[70:71], v[4:5] neg_lo:[0,1,0] neg_hi:[0,1,0]
	ds_read_b128 v[24:27], v88 offset:30976
	v_pk_mul_f32 v[8:9], v[64:65], v[18:19] op_sel_hi:[1,0]
	v_add_f32_e32 v4, v4, v5
	ds_read_b128 v[20:23], v88 offset:30720
	v_pk_mul_f32 v[10:11], v[66:67], v[18:19] op_sel_hi:[1,0]
	v_add_f32_dpp v4, v4, v4 quad_perm:[1,0,3,2] row_mask:0xf bank_mask:0xf bound_ctrl:1
	ds_read_b128 v[32:35], v88 offset:31488
	v_pk_fma_f32 v[8:9], v[0:1], v[60:61], v[8:9]
	v_add_f32_dpp v4, v4, v4 quad_perm:[2,3,0,1] row_mask:0xf bank_mask:0xf bound_ctrl:1
	v_add_f32_dpp v6, v6, v6 quad_perm:[1,0,3,2] row_mask:0xf bank_mask:0xf bound_ctrl:1
	v_pk_fma_f32 v[10:11], v[2:3], v[62:63], v[10:11]
	v_add_f32_dpp v4, v4, v4 row_ror:4 row_mask:0xf bank_mask:0xf bound_ctrl:1
	v_add_f32_dpp v6, v6, v6 quad_perm:[2,3,0,1] row_mask:0xf bank_mask:0xf bound_ctrl:1
	ds_read_b128 v[36:39], v88 offset:31744
	v_add_f32_dpp v4, v4, v4 row_ror:8 row_mask:0xf bank_mask:0xf bound_ctrl:1
	v_add_f32_dpp v6, v6, v6 row_ror:4 row_mask:0xf bank_mask:0xf bound_ctrl:1
	v_pk_fma_f32 v[0:1], v[4:5], v[72:73], v[8:9] op_sel_hi:[0,1,1]
	v_pk_fma_f32 v[2:3], v[4:5], v[74:75], v[10:11] op_sel_hi:[0,1,1]
	v_add_f32_dpp v13, v6, v6 row_ror:8 row_mask:0xf bank_mask:0x1 bound_ctrl:1
	v_pk_mul_f32 v[6:7], v[0:1], v[76:77]
	v_pk_fma_f32 v[6:7], v[2:3], v[78:79], v[6:7]
	v_add_f32_e32 v6, v6, v7
	ds_read2st64_b32 v[16:17], v90 offset0:125 offset1:131
	s_waitcnt lgkmcnt(6)
	v_pk_mul_f32 v[4:5], v[0:1], v[92:93] neg_lo:[0,1] neg_hi:[0,1]
	ds_read_b128 v[48:51], v88 offset:32768
	v_pk_fma_f32 v[4:5], v[2:3], v[94:95], v[4:5] neg_lo:[0,1,0] neg_hi:[0,1,0]
	ds_read_b128 v[44:47], v88 offset:32512
	v_pk_mul_f32 v[8:9], v[84:85], v[18:19] op_sel:[0,1] op_sel_hi:[1,1]
	v_add_f32_e32 v4, v4, v5
	ds_read_b128 v[40:43], v88 offset:32256
	v_pk_mul_f32 v[10:11], v[86:87], v[18:19] op_sel:[0,1] op_sel_hi:[1,1]
	v_add_f32_dpp v4, v4, v4 quad_perm:[1,0,3,2] row_mask:0xf bank_mask:0xf bound_ctrl:1
	ds_read_b128 v[52:55], v88 offset:33024
	v_pk_fma_f32 v[8:9], v[0:1], v[80:81], v[8:9]
	v_add_f32_dpp v4, v4, v4 quad_perm:[2,3,0,1] row_mask:0xf bank_mask:0xf bound_ctrl:1
	v_add_f32_dpp v6, v6, v6 quad_perm:[1,0,3,2] row_mask:0xf bank_mask:0xf bound_ctrl:1
	v_pk_fma_f32 v[10:11], v[2:3], v[82:83], v[10:11]
	v_add_f32_dpp v4, v4, v4 row_ror:4 row_mask:0xf bank_mask:0xf bound_ctrl:1
	v_add_f32_dpp v6, v6, v6 quad_perm:[2,3,0,1] row_mask:0xf bank_mask:0xf bound_ctrl:1
	ds_read_b128 v[56:59], v88 offset:33280
	v_add_f32_dpp v4, v4, v4 row_ror:8 row_mask:0xf bank_mask:0xf bound_ctrl:1
	v_add_f32_dpp v6, v6, v6 row_ror:4 row_mask:0xf bank_mask:0xf bound_ctrl:1
	v_pk_fma_f32 v[0:1], v[4:5], v[96:97], v[8:9] op_sel_hi:[0,1,1]
	v_pk_fma_f32 v[2:3], v[4:5], v[98:99], v[10:11] op_sel_hi:[0,1,1]
	v_add_f32_dpp v14, v6, v6 row_ror:8 row_mask:0xf bank_mask:0x1 bound_ctrl:1
	v_pk_mul_f32 v[6:7], v[0:1], v[100:101]
	v_pk_fma_f32 v[6:7], v[2:3], v[102:103], v[6:7]
	v_add_f32_e32 v6, v6, v7
	s_waitcnt lgkmcnt(5)
	v_pk_mul_f32 v[4:5], v[0:1], v[28:29] neg_lo:[0,1] neg_hi:[0,1]
	ds_read_b128 v[68:71], v88 offset:34304
	v_pk_fma_f32 v[4:5], v[2:3], v[30:31], v[4:5] neg_lo:[0,1,0] neg_hi:[0,1,0]
	ds_read_b128 v[64:67], v88 offset:34048
	v_pk_mul_f32 v[8:9], v[24:25], v[16:17] op_sel_hi:[1,0]
	v_add_f32_e32 v4, v4, v5
	ds_read_b128 v[60:63], v88 offset:33792
	v_pk_mul_f32 v[10:11], v[26:27], v[16:17] op_sel_hi:[1,0]
	v_add_f32_dpp v4, v4, v4 quad_perm:[1,0,3,2] row_mask:0xf bank_mask:0xf bound_ctrl:1
	ds_read_b128 v[72:75], v88 offset:34560
	v_pk_fma_f32 v[8:9], v[0:1], v[20:21], v[8:9]
	v_add_f32_dpp v4, v4, v4 quad_perm:[2,3,0,1] row_mask:0xf bank_mask:0xf bound_ctrl:1
	v_add_f32_dpp v6, v6, v6 quad_perm:[1,0,3,2] row_mask:0xf bank_mask:0xf bound_ctrl:1
	v_pk_fma_f32 v[10:11], v[2:3], v[22:23], v[10:11]
	v_add_f32_dpp v4, v4, v4 row_ror:4 row_mask:0xf bank_mask:0xf bound_ctrl:1
	v_add_f32_dpp v6, v6, v6 quad_perm:[2,3,0,1] row_mask:0xf bank_mask:0xf bound_ctrl:1
	ds_read_b128 v[76:79], v88 offset:34816
	v_add_f32_dpp v4, v4, v4 row_ror:8 row_mask:0xf bank_mask:0xf bound_ctrl:1
	v_add_f32_dpp v6, v6, v6 row_ror:4 row_mask:0xf bank_mask:0xf bound_ctrl:1
	v_pk_fma_f32 v[0:1], v[4:5], v[32:33], v[8:9] op_sel_hi:[0,1,1]
	v_pk_fma_f32 v[2:3], v[4:5], v[34:35], v[10:11] op_sel_hi:[0,1,1]
	v_add_f32_dpp v15, v6, v6 row_ror:8 row_mask:0xf bank_mask:0x1 bound_ctrl:1
	v_pk_mul_f32 v[6:7], v[0:1], v[36:37]
	v_pk_fma_f32 v[6:7], v[2:3], v[38:39], v[6:7]
	v_add_f32_e32 v6, v6, v7
	ds_read2st64_b32 v[18:19], v90 offset0:137 offset1:143
	s_waitcnt vmcnt(21)
	ds_write_b128 v91, v[104:107] offset:0
	s_waitcnt lgkmcnt(7)
	v_pk_mul_f32 v[4:5], v[0:1], v[48:49] neg_lo:[0,1] neg_hi:[0,1]
	ds_read_b128 v[92:95], v88 offset:35840
	v_pk_fma_f32 v[4:5], v[2:3], v[50:51], v[4:5] neg_lo:[0,1,0] neg_hi:[0,1,0]
	ds_read_b128 v[84:87], v88 offset:35584
	v_pk_mul_f32 v[8:9], v[44:45], v[16:17] op_sel:[0,1] op_sel_hi:[1,1]
	v_add_f32_e32 v4, v4, v5
	ds_read_b128 v[80:83], v88 offset:35328
	v_pk_mul_f32 v[10:11], v[46:47], v[16:17] op_sel:[0,1] op_sel_hi:[1,1]
	v_add_f32_dpp v4, v4, v4 quad_perm:[1,0,3,2] row_mask:0xf bank_mask:0xf bound_ctrl:1
	ds_read_b128 v[96:99], v88 offset:36096
	v_pk_fma_f32 v[8:9], v[0:1], v[40:41], v[8:9]
	v_add_f32_dpp v4, v4, v4 quad_perm:[2,3,0,1] row_mask:0xf bank_mask:0xf bound_ctrl:1
	v_add_f32_dpp v6, v6, v6 quad_perm:[1,0,3,2] row_mask:0xf bank_mask:0xf bound_ctrl:1
	v_pk_fma_f32 v[10:11], v[2:3], v[42:43], v[10:11]
	v_add_f32_dpp v4, v4, v4 row_ror:4 row_mask:0xf bank_mask:0xf bound_ctrl:1
	v_add_f32_dpp v6, v6, v6 quad_perm:[2,3,0,1] row_mask:0xf bank_mask:0xf bound_ctrl:1
	ds_read_b128 v[100:103], v88 offset:36352
	v_add_f32_dpp v4, v4, v4 row_ror:8 row_mask:0xf bank_mask:0xf bound_ctrl:1
	v_add_f32_dpp v6, v6, v6 row_ror:4 row_mask:0xf bank_mask:0xf bound_ctrl:1
	v_pk_fma_f32 v[0:1], v[4:5], v[52:53], v[8:9] op_sel_hi:[0,1,1]
	v_pk_fma_f32 v[2:3], v[4:5], v[54:55], v[10:11] op_sel_hi:[0,1,1]
	v_add_f32_dpp v12, v6, v6 row_ror:8 row_mask:0xf bank_mask:0x2 bound_ctrl:1
	v_pk_mul_f32 v[6:7], v[0:1], v[56:57]
	v_pk_fma_f32 v[6:7], v[2:3], v[58:59], v[6:7]
	v_add_f32_e32 v6, v6, v7
	ds_write_b128 v91, v[108:111] offset:1024
	ds_write_b32 v91, v170 offset:1280
	s_waitcnt lgkmcnt(8)
	v_pk_mul_f32 v[4:5], v[0:1], v[68:69] neg_lo:[0,1] neg_hi:[0,1]
	ds_read_b128 v[28:31], v88 offset:37376
	v_pk_fma_f32 v[4:5], v[2:3], v[70:71], v[4:5] neg_lo:[0,1,0] neg_hi:[0,1,0]
	ds_read_b128 v[24:27], v88 offset:37120
	v_pk_mul_f32 v[8:9], v[64:65], v[18:19] op_sel_hi:[1,0]
	v_add_f32_e32 v4, v4, v5
	ds_read_b128 v[20:23], v88 offset:36864
	v_pk_mul_f32 v[10:11], v[66:67], v[18:19] op_sel_hi:[1,0]
	v_add_f32_dpp v4, v4, v4 quad_perm:[1,0,3,2] row_mask:0xf bank_mask:0xf bound_ctrl:1
	ds_read_b128 v[32:35], v88 offset:37632
	v_pk_fma_f32 v[8:9], v[0:1], v[60:61], v[8:9]
	v_add_f32_dpp v4, v4, v4 quad_perm:[2,3,0,1] row_mask:0xf bank_mask:0xf bound_ctrl:1
	v_add_f32_dpp v6, v6, v6 quad_perm:[1,0,3,2] row_mask:0xf bank_mask:0xf bound_ctrl:1
	v_pk_fma_f32 v[10:11], v[2:3], v[62:63], v[10:11]
	v_add_f32_dpp v4, v4, v4 row_ror:4 row_mask:0xf bank_mask:0xf bound_ctrl:1
	v_add_f32_dpp v6, v6, v6 quad_perm:[2,3,0,1] row_mask:0xf bank_mask:0xf bound_ctrl:1
	ds_read_b128 v[36:39], v88 offset:37888
	v_add_f32_dpp v4, v4, v4 row_ror:8 row_mask:0xf bank_mask:0xf bound_ctrl:1
	v_add_f32_dpp v6, v6, v6 row_ror:4 row_mask:0xf bank_mask:0xf bound_ctrl:1
	v_pk_fma_f32 v[0:1], v[4:5], v[72:73], v[8:9] op_sel_hi:[0,1,1]
	v_pk_fma_f32 v[2:3], v[4:5], v[74:75], v[10:11] op_sel_hi:[0,1,1]
	v_add_f32_dpp v13, v6, v6 row_ror:8 row_mask:0xf bank_mask:0x2 bound_ctrl:1
	v_pk_mul_f32 v[6:7], v[0:1], v[76:77]
	v_pk_fma_f32 v[6:7], v[2:3], v[78:79], v[6:7]
	v_add_f32_e32 v6, v6, v7
	ds_read2st64_b32 v[16:17], v90 offset0:149 offset1:155
	v_lshlrev_b32_e32 v176, 16, v146
	v_and_b32_e32 v177, 0xffff0000, v146
	s_waitcnt lgkmcnt(8)
	v_pk_mul_f32 v[4:5], v[0:1], v[92:93] neg_lo:[0,1] neg_hi:[0,1]
	ds_read_b128 v[48:51], v88 offset:38912
	v_pk_fma_f32 v[4:5], v[2:3], v[94:95], v[4:5] neg_lo:[0,1,0] neg_hi:[0,1,0]
	ds_read_b128 v[44:47], v88 offset:38656
	v_pk_mul_f32 v[8:9], v[84:85], v[18:19] op_sel:[0,1] op_sel_hi:[1,1]
	v_add_f32_e32 v4, v4, v5
	ds_read_b128 v[40:43], v88 offset:38400
	v_pk_mul_f32 v[10:11], v[86:87], v[18:19] op_sel:[0,1] op_sel_hi:[1,1]
	v_add_f32_dpp v4, v4, v4 quad_perm:[1,0,3,2] row_mask:0xf bank_mask:0xf bound_ctrl:1
	ds_read_b128 v[52:55], v88 offset:39168
	v_pk_fma_f32 v[8:9], v[0:1], v[80:81], v[8:9]
	v_add_f32_dpp v4, v4, v4 quad_perm:[2,3,0,1] row_mask:0xf bank_mask:0xf bound_ctrl:1
	v_add_f32_dpp v6, v6, v6 quad_perm:[1,0,3,2] row_mask:0xf bank_mask:0xf bound_ctrl:1
	v_pk_fma_f32 v[10:11], v[2:3], v[82:83], v[10:11]
	v_add_f32_dpp v4, v4, v4 row_ror:4 row_mask:0xf bank_mask:0xf bound_ctrl:1
	v_add_f32_dpp v6, v6, v6 quad_perm:[2,3,0,1] row_mask:0xf bank_mask:0xf bound_ctrl:1
	ds_read_b128 v[56:59], v88 offset:39424
	v_add_f32_dpp v4, v4, v4 row_ror:8 row_mask:0xf bank_mask:0xf bound_ctrl:1
	v_add_f32_dpp v6, v6, v6 row_ror:4 row_mask:0xf bank_mask:0xf bound_ctrl:1
	v_pk_fma_f32 v[0:1], v[4:5], v[96:97], v[8:9] op_sel_hi:[0,1,1]
	v_pk_fma_f32 v[2:3], v[4:5], v[98:99], v[10:11] op_sel_hi:[0,1,1]
	v_add_f32_dpp v14, v6, v6 row_ror:8 row_mask:0xf bank_mask:0x2 bound_ctrl:1
	v_pk_mul_f32 v[6:7], v[0:1], v[100:101]
	v_pk_fma_f32 v[6:7], v[2:3], v[102:103], v[6:7]
	v_add_f32_e32 v6, v6, v7
	v_lshlrev_b32_e32 v178, 16, v147
	v_and_b32_e32 v179, 0xffff0000, v147
	s_waitcnt lgkmcnt(5)
	v_pk_mul_f32 v[4:5], v[0:1], v[28:29] neg_lo:[0,1] neg_hi:[0,1]
	ds_read_b128 v[68:71], v88 offset:40448
	v_pk_fma_f32 v[4:5], v[2:3], v[30:31], v[4:5] neg_lo:[0,1,0] neg_hi:[0,1,0]
	ds_read_b128 v[64:67], v88 offset:40192
	v_pk_mul_f32 v[8:9], v[24:25], v[16:17] op_sel_hi:[1,0]
	v_add_f32_e32 v4, v4, v5
	ds_read_b128 v[60:63], v88 offset:39936
	v_pk_mul_f32 v[10:11], v[26:27], v[16:17] op_sel_hi:[1,0]
	v_add_f32_dpp v4, v4, v4 quad_perm:[1,0,3,2] row_mask:0xf bank_mask:0xf bound_ctrl:1
	ds_read_b128 v[72:75], v88 offset:40704
	v_pk_fma_f32 v[8:9], v[0:1], v[20:21], v[8:9]
	v_add_f32_dpp v4, v4, v4 quad_perm:[2,3,0,1] row_mask:0xf bank_mask:0xf bound_ctrl:1
	v_add_f32_dpp v6, v6, v6 quad_perm:[1,0,3,2] row_mask:0xf bank_mask:0xf bound_ctrl:1
	v_pk_fma_f32 v[10:11], v[2:3], v[22:23], v[10:11]
	v_add_f32_dpp v4, v4, v4 row_ror:4 row_mask:0xf bank_mask:0xf bound_ctrl:1
	v_add_f32_dpp v6, v6, v6 quad_perm:[2,3,0,1] row_mask:0xf bank_mask:0xf bound_ctrl:1
	ds_read_b128 v[76:79], v88 offset:40960
	v_add_f32_dpp v4, v4, v4 row_ror:8 row_mask:0xf bank_mask:0xf bound_ctrl:1
	v_add_f32_dpp v6, v6, v6 row_ror:4 row_mask:0xf bank_mask:0xf bound_ctrl:1
	v_pk_fma_f32 v[0:1], v[4:5], v[32:33], v[8:9] op_sel_hi:[0,1,1]
	v_pk_fma_f32 v[2:3], v[4:5], v[34:35], v[10:11] op_sel_hi:[0,1,1]
	v_add_f32_dpp v15, v6, v6 row_ror:8 row_mask:0xf bank_mask:0x2 bound_ctrl:1
	v_pk_mul_f32 v[6:7], v[0:1], v[36:37]
	v_pk_fma_f32 v[6:7], v[2:3], v[38:39], v[6:7]
	v_add_f32_e32 v6, v6, v7
	ds_read2st64_b32 v[18:19], v90 offset0:161 offset1:167
	ds_write_b128 v91, v[176:179] offset:256
	v_lshlrev_b32_e32 v176, 16, v148
	s_waitcnt lgkmcnt(7)
	v_pk_mul_f32 v[4:5], v[0:1], v[48:49] neg_lo:[0,1] neg_hi:[0,1]
	ds_read_b128 v[92:95], v88 offset:41984
	v_pk_fma_f32 v[4:5], v[2:3], v[50:51], v[4:5] neg_lo:[0,1,0] neg_hi:[0,1,0]
	ds_read_b128 v[84:87], v88 offset:41728
	v_pk_mul_f32 v[8:9], v[44:45], v[16:17] op_sel:[0,1] op_sel_hi:[1,1]
	v_add_f32_e32 v4, v4, v5
	ds_read_b128 v[80:83], v88 offset:41472
	v_pk_mul_f32 v[10:11], v[46:47], v[16:17] op_sel:[0,1] op_sel_hi:[1,1]
	v_add_f32_dpp v4, v4, v4 quad_perm:[1,0,3,2] row_mask:0xf bank_mask:0xf bound_ctrl:1
	ds_read_b128 v[96:99], v88 offset:42240
	v_pk_fma_f32 v[8:9], v[0:1], v[40:41], v[8:9]
	v_add_f32_dpp v4, v4, v4 quad_perm:[2,3,0,1] row_mask:0xf bank_mask:0xf bound_ctrl:1
	v_add_f32_dpp v6, v6, v6 quad_perm:[1,0,3,2] row_mask:0xf bank_mask:0xf bound_ctrl:1
	v_pk_fma_f32 v[10:11], v[2:3], v[42:43], v[10:11]
	v_add_f32_dpp v4, v4, v4 row_ror:4 row_mask:0xf bank_mask:0xf bound_ctrl:1
	v_add_f32_dpp v6, v6, v6 quad_perm:[2,3,0,1] row_mask:0xf bank_mask:0xf bound_ctrl:1
	ds_read_b128 v[100:103], v88 offset:42496
	v_add_f32_dpp v4, v4, v4 row_ror:8 row_mask:0xf bank_mask:0xf bound_ctrl:1
	v_add_f32_dpp v6, v6, v6 row_ror:4 row_mask:0xf bank_mask:0xf bound_ctrl:1
	v_pk_fma_f32 v[0:1], v[4:5], v[52:53], v[8:9] op_sel_hi:[0,1,1]
	v_pk_fma_f32 v[2:3], v[4:5], v[54:55], v[10:11] op_sel_hi:[0,1,1]
	v_add_f32_dpp v12, v6, v6 row_ror:8 row_mask:0xf bank_mask:0x4 bound_ctrl:1
	v_pk_mul_f32 v[6:7], v[0:1], v[56:57]
	v_pk_fma_f32 v[6:7], v[2:3], v[58:59], v[6:7]
	v_add_f32_e32 v6, v6, v7
	v_and_b32_e32 v177, 0xffff0000, v148
	v_lshlrev_b32_e32 v178, 16, v149
	s_waitcnt lgkmcnt(6)
	v_pk_mul_f32 v[4:5], v[0:1], v[68:69] neg_lo:[0,1] neg_hi:[0,1]
	ds_read_b128 v[28:31], v88 offset:43520
	v_pk_fma_f32 v[4:5], v[2:3], v[70:71], v[4:5] neg_lo:[0,1,0] neg_hi:[0,1,0]
	ds_read_b128 v[24:27], v88 offset:43264
	v_pk_mul_f32 v[8:9], v[64:65], v[18:19] op_sel_hi:[1,0]
	v_add_f32_e32 v4, v4, v5
	ds_read_b128 v[20:23], v88 offset:43008
	v_pk_mul_f32 v[10:11], v[66:67], v[18:19] op_sel_hi:[1,0]
	v_add_f32_dpp v4, v4, v4 quad_perm:[1,0,3,2] row_mask:0xf bank_mask:0xf bound_ctrl:1
	ds_read_b128 v[32:35], v88 offset:43776
	v_pk_fma_f32 v[8:9], v[0:1], v[60:61], v[8:9]
	v_add_f32_dpp v4, v4, v4 quad_perm:[2,3,0,1] row_mask:0xf bank_mask:0xf bound_ctrl:1
	v_add_f32_dpp v6, v6, v6 quad_perm:[1,0,3,2] row_mask:0xf bank_mask:0xf bound_ctrl:1
	v_pk_fma_f32 v[10:11], v[2:3], v[62:63], v[10:11]
	v_add_f32_dpp v4, v4, v4 row_ror:4 row_mask:0xf bank_mask:0xf bound_ctrl:1
	v_add_f32_dpp v6, v6, v6 quad_perm:[2,3,0,1] row_mask:0xf bank_mask:0xf bound_ctrl:1
	ds_read_b128 v[36:39], v88 offset:44032
	v_add_f32_dpp v4, v4, v4 row_ror:8 row_mask:0xf bank_mask:0xf bound_ctrl:1
	v_add_f32_dpp v6, v6, v6 row_ror:4 row_mask:0xf bank_mask:0xf bound_ctrl:1
	v_pk_fma_f32 v[0:1], v[4:5], v[72:73], v[8:9] op_sel_hi:[0,1,1]
	v_pk_fma_f32 v[2:3], v[4:5], v[74:75], v[10:11] op_sel_hi:[0,1,1]
	v_add_f32_dpp v13, v6, v6 row_ror:8 row_mask:0xf bank_mask:0x4 bound_ctrl:1
	v_pk_mul_f32 v[6:7], v[0:1], v[76:77]
	v_pk_fma_f32 v[6:7], v[2:3], v[78:79], v[6:7]
	v_add_f32_e32 v6, v6, v7
	ds_read2st64_b32 v[16:17], v90 offset0:173 offset1:179
	v_and_b32_e32 v179, 0xffff0000, v149
	ds_write_b128 v91, v[176:179] offset:512
	s_waitcnt lgkmcnt(7)
	v_pk_mul_f32 v[4:5], v[0:1], v[92:93] neg_lo:[0,1] neg_hi:[0,1]
	ds_read_b128 v[48:51], v88 offset:45056
	v_pk_fma_f32 v[4:5], v[2:3], v[94:95], v[4:5] neg_lo:[0,1,0] neg_hi:[0,1,0]
	ds_read_b128 v[44:47], v88 offset:44800
	v_pk_mul_f32 v[8:9], v[84:85], v[18:19] op_sel:[0,1] op_sel_hi:[1,1]
	v_add_f32_e32 v4, v4, v5
	ds_read_b128 v[40:43], v88 offset:44544
	v_pk_mul_f32 v[10:11], v[86:87], v[18:19] op_sel:[0,1] op_sel_hi:[1,1]
	v_add_f32_dpp v4, v4, v4 quad_perm:[1,0,3,2] row_mask:0xf bank_mask:0xf bound_ctrl:1
	ds_read_b128 v[52:55], v88 offset:45312
	v_pk_fma_f32 v[8:9], v[0:1], v[80:81], v[8:9]
	v_add_f32_dpp v4, v4, v4 quad_perm:[2,3,0,1] row_mask:0xf bank_mask:0xf bound_ctrl:1
	v_add_f32_dpp v6, v6, v6 quad_perm:[1,0,3,2] row_mask:0xf bank_mask:0xf bound_ctrl:1
	v_pk_fma_f32 v[10:11], v[2:3], v[82:83], v[10:11]
	v_add_f32_dpp v4, v4, v4 row_ror:4 row_mask:0xf bank_mask:0xf bound_ctrl:1
	v_add_f32_dpp v6, v6, v6 quad_perm:[2,3,0,1] row_mask:0xf bank_mask:0xf bound_ctrl:1
	ds_read_b128 v[56:59], v88 offset:45568
	v_add_f32_dpp v4, v4, v4 row_ror:8 row_mask:0xf bank_mask:0xf bound_ctrl:1
	v_add_f32_dpp v6, v6, v6 row_ror:4 row_mask:0xf bank_mask:0xf bound_ctrl:1
	v_pk_fma_f32 v[0:1], v[4:5], v[96:97], v[8:9] op_sel_hi:[0,1,1]
	v_pk_fma_f32 v[2:3], v[4:5], v[98:99], v[10:11] op_sel_hi:[0,1,1]
	v_add_f32_dpp v14, v6, v6 row_ror:8 row_mask:0xf bank_mask:0x4 bound_ctrl:1
	v_pk_mul_f32 v[6:7], v[0:1], v[100:101]
	v_pk_fma_f32 v[6:7], v[2:3], v[102:103], v[6:7]
	v_add_f32_e32 v6, v6, v7
	v_lshlrev_b32_e32 v176, 16, v150
	v_and_b32_e32 v177, 0xffff0000, v150
	s_waitcnt lgkmcnt(6)
	v_pk_mul_f32 v[4:5], v[0:1], v[28:29] neg_lo:[0,1] neg_hi:[0,1]
	ds_read_b128 v[68:71], v88 offset:46592
	v_pk_fma_f32 v[4:5], v[2:3], v[30:31], v[4:5] neg_lo:[0,1,0] neg_hi:[0,1,0]
	ds_read_b128 v[64:67], v88 offset:46336
	v_pk_mul_f32 v[8:9], v[24:25], v[16:17] op_sel_hi:[1,0]
	v_add_f32_e32 v4, v4, v5
	ds_read_b128 v[60:63], v88 offset:46080
	v_pk_mul_f32 v[10:11], v[26:27], v[16:17] op_sel_hi:[1,0]
	v_add_f32_dpp v4, v4, v4 quad_perm:[1,0,3,2] row_mask:0xf bank_mask:0xf bound_ctrl:1
	ds_read_b128 v[72:75], v88 offset:46848
	v_pk_fma_f32 v[8:9], v[0:1], v[20:21], v[8:9]
	v_add_f32_dpp v4, v4, v4 quad_perm:[2,3,0,1] row_mask:0xf bank_mask:0xf bound_ctrl:1
	v_add_f32_dpp v6, v6, v6 quad_perm:[1,0,3,2] row_mask:0xf bank_mask:0xf bound_ctrl:1
	v_pk_fma_f32 v[10:11], v[2:3], v[22:23], v[10:11]
	v_add_f32_dpp v4, v4, v4 row_ror:4 row_mask:0xf bank_mask:0xf bound_ctrl:1
	v_add_f32_dpp v6, v6, v6 quad_perm:[2,3,0,1] row_mask:0xf bank_mask:0xf bound_ctrl:1
	ds_read_b128 v[76:79], v88 offset:47104
	v_add_f32_dpp v4, v4, v4 row_ror:8 row_mask:0xf bank_mask:0xf bound_ctrl:1
	v_add_f32_dpp v6, v6, v6 row_ror:4 row_mask:0xf bank_mask:0xf bound_ctrl:1
	v_pk_fma_f32 v[0:1], v[4:5], v[32:33], v[8:9] op_sel_hi:[0,1,1]
	v_pk_fma_f32 v[2:3], v[4:5], v[34:35], v[10:11] op_sel_hi:[0,1,1]
	v_add_f32_dpp v15, v6, v6 row_ror:8 row_mask:0xf bank_mask:0x4 bound_ctrl:1
	v_pk_mul_f32 v[6:7], v[0:1], v[36:37]
	v_pk_fma_f32 v[6:7], v[2:3], v[38:39], v[6:7]
	v_add_f32_e32 v6, v6, v7
	ds_read2st64_b32 v[18:19], v90 offset0:185 offset1:191
	v_lshlrev_b32_e32 v178, 16, v151
	v_and_b32_e32 v179, 0xffff0000, v151
	ds_write_b128 v91, v[176:179] offset:768
	s_waitcnt lgkmcnt(7)
	v_pk_mul_f32 v[4:5], v[0:1], v[48:49] neg_lo:[0,1] neg_hi:[0,1]
	ds_read_b128 v[92:95], v88 offset:48128
	v_pk_fma_f32 v[4:5], v[2:3], v[50:51], v[4:5] neg_lo:[0,1,0] neg_hi:[0,1,0]
	ds_read_b128 v[84:87], v88 offset:47872
	v_pk_mul_f32 v[8:9], v[44:45], v[16:17] op_sel:[0,1] op_sel_hi:[1,1]
	v_add_f32_e32 v4, v4, v5
	ds_read_b128 v[80:83], v88 offset:47616
	v_pk_mul_f32 v[10:11], v[46:47], v[16:17] op_sel:[0,1] op_sel_hi:[1,1]
	v_add_f32_dpp v4, v4, v4 quad_perm:[1,0,3,2] row_mask:0xf bank_mask:0xf bound_ctrl:1
	ds_read_b128 v[96:99], v88 offset:48384
	v_pk_fma_f32 v[8:9], v[0:1], v[40:41], v[8:9]
	v_add_f32_dpp v4, v4, v4 quad_perm:[2,3,0,1] row_mask:0xf bank_mask:0xf bound_ctrl:1
	v_add_f32_dpp v6, v6, v6 quad_perm:[1,0,3,2] row_mask:0xf bank_mask:0xf bound_ctrl:1
	v_pk_fma_f32 v[10:11], v[2:3], v[42:43], v[10:11]
	v_add_f32_dpp v4, v4, v4 row_ror:4 row_mask:0xf bank_mask:0xf bound_ctrl:1
	v_add_f32_dpp v6, v6, v6 quad_perm:[2,3,0,1] row_mask:0xf bank_mask:0xf bound_ctrl:1
	ds_read_b128 v[100:103], v88 offset:48640
	v_add_f32_dpp v4, v4, v4 row_ror:8 row_mask:0xf bank_mask:0xf bound_ctrl:1
	v_add_f32_dpp v6, v6, v6 row_ror:4 row_mask:0xf bank_mask:0xf bound_ctrl:1
	v_pk_fma_f32 v[0:1], v[4:5], v[52:53], v[8:9] op_sel_hi:[0,1,1]
	v_pk_fma_f32 v[2:3], v[4:5], v[54:55], v[10:11] op_sel_hi:[0,1,1]
	v_add_f32_dpp v12, v6, v6 row_ror:8 row_mask:0xf bank_mask:0x8 bound_ctrl:1
	v_pk_mul_f32 v[6:7], v[0:1], v[56:57]
	v_pk_fma_f32 v[6:7], v[2:3], v[58:59], v[6:7]
	v_add_f32_e32 v6, v6, v7
	s_waitcnt lgkmcnt(0)
	s_barrier
	v_pk_mul_f32 v[4:5], v[0:1], v[68:69] neg_lo:[0,1] neg_hi:[0,1]
	ds_read_b128 v[28:31], v88 offset:512
	v_pk_fma_f32 v[4:5], v[2:3], v[70:71], v[4:5] neg_lo:[0,1,0] neg_hi:[0,1,0]
	ds_read_b128 v[24:27], v88 offset:256
	v_pk_mul_f32 v[8:9], v[64:65], v[18:19] op_sel_hi:[1,0]
	v_add_f32_e32 v4, v4, v5
	ds_read_b128 v[20:23], v88 offset:0
	v_pk_mul_f32 v[10:11], v[66:67], v[18:19] op_sel_hi:[1,0]
	v_add_f32_dpp v4, v4, v4 quad_perm:[1,0,3,2] row_mask:0xf bank_mask:0xf bound_ctrl:1
	ds_read_b128 v[32:35], v88 offset:768
	v_pk_fma_f32 v[8:9], v[0:1], v[60:61], v[8:9]
	v_add_f32_dpp v4, v4, v4 quad_perm:[2,3,0,1] row_mask:0xf bank_mask:0xf bound_ctrl:1
	v_add_f32_dpp v6, v6, v6 quad_perm:[1,0,3,2] row_mask:0xf bank_mask:0xf bound_ctrl:1
	v_pk_fma_f32 v[10:11], v[2:3], v[62:63], v[10:11]
	v_add_f32_dpp v4, v4, v4 row_ror:4 row_mask:0xf bank_mask:0xf bound_ctrl:1
	v_add_f32_dpp v6, v6, v6 quad_perm:[2,3,0,1] row_mask:0xf bank_mask:0xf bound_ctrl:1
	ds_read_b128 v[36:39], v88 offset:1024
	v_add_f32_dpp v4, v4, v4 row_ror:8 row_mask:0xf bank_mask:0xf bound_ctrl:1
	v_add_f32_dpp v6, v6, v6 row_ror:4 row_mask:0xf bank_mask:0xf bound_ctrl:1
	v_pk_fma_f32 v[0:1], v[4:5], v[72:73], v[8:9] op_sel_hi:[0,1,1]
	v_pk_fma_f32 v[2:3], v[4:5], v[74:75], v[10:11] op_sel_hi:[0,1,1]
	v_add_f32_dpp v13, v6, v6 row_ror:8 row_mask:0xf bank_mask:0x8 bound_ctrl:1
	v_pk_mul_f32 v[6:7], v[0:1], v[76:77]
	v_pk_fma_f32 v[6:7], v[2:3], v[78:79], v[6:7]
	v_add_f32_e32 v6, v6, v7
	ds_read2st64_b32 v[16:17], v90 offset0:5 offset1:11
	s_waitcnt lgkmcnt(6)
	v_pk_mul_f32 v[4:5], v[0:1], v[92:93] neg_lo:[0,1] neg_hi:[0,1]
	ds_read_b128 v[48:51], v88 offset:2048
	v_pk_fma_f32 v[4:5], v[2:3], v[94:95], v[4:5] neg_lo:[0,1,0] neg_hi:[0,1,0]
	ds_read_b128 v[44:47], v88 offset:1792
	v_pk_mul_f32 v[8:9], v[84:85], v[18:19] op_sel:[0,1] op_sel_hi:[1,1]
	v_add_f32_e32 v4, v4, v5
	ds_read_b128 v[40:43], v88 offset:1536
	v_pk_mul_f32 v[10:11], v[86:87], v[18:19] op_sel:[0,1] op_sel_hi:[1,1]
	v_add_f32_dpp v4, v4, v4 quad_perm:[1,0,3,2] row_mask:0xf bank_mask:0xf bound_ctrl:1
	ds_read_b128 v[52:55], v88 offset:2304
	v_pk_fma_f32 v[8:9], v[0:1], v[80:81], v[8:9]
	v_add_f32_dpp v4, v4, v4 quad_perm:[2,3,0,1] row_mask:0xf bank_mask:0xf bound_ctrl:1
	v_add_f32_dpp v6, v6, v6 quad_perm:[1,0,3,2] row_mask:0xf bank_mask:0xf bound_ctrl:1
	v_pk_fma_f32 v[10:11], v[2:3], v[82:83], v[10:11]
	v_add_f32_dpp v4, v4, v4 row_ror:4 row_mask:0xf bank_mask:0xf bound_ctrl:1
	v_add_f32_dpp v6, v6, v6 quad_perm:[2,3,0,1] row_mask:0xf bank_mask:0xf bound_ctrl:1
	ds_read_b128 v[56:59], v88 offset:2560
	v_add_f32_dpp v4, v4, v4 row_ror:8 row_mask:0xf bank_mask:0xf bound_ctrl:1
	v_add_f32_dpp v6, v6, v6 row_ror:4 row_mask:0xf bank_mask:0xf bound_ctrl:1
	v_pk_fma_f32 v[0:1], v[4:5], v[96:97], v[8:9] op_sel_hi:[0,1,1]
	v_pk_fma_f32 v[2:3], v[4:5], v[98:99], v[10:11] op_sel_hi:[0,1,1]
	v_add_f32_dpp v14, v6, v6 row_ror:8 row_mask:0xf bank_mask:0x8 bound_ctrl:1
	v_pk_mul_f32 v[6:7], v[0:1], v[100:101]
	v_pk_fma_f32 v[6:7], v[2:3], v[102:103], v[6:7]
	v_add_f32_e32 v6, v6, v7
	s_add_i32 s28, s28, 1
	s_cmp_lt_u32 s28, 16
	s_cbranch_scc1 .Lls0_loop
	s_nop 1
	v_add_f32_dpp v6, v6, v6 quad_perm:[1,0,3,2] row_mask:0xf bank_mask:0xf bound_ctrl:1
	s_nop 1
	v_add_f32_dpp v6, v6, v6 quad_perm:[2,3,0,1] row_mask:0xf bank_mask:0xf bound_ctrl:1
	s_nop 1
	v_add_f32_dpp v6, v6, v6 row_ror:4 row_mask:0xf bank_mask:0xf bound_ctrl:1
	s_nop 1
	v_add_f32_dpp v15, v6, v6 row_ror:8 row_mask:0xf bank_mask:0x8 bound_ctrl:1
	s_nop 0
	v_cndmask_b32_e64 v176, v12, v13, s[30:31]
	v_cndmask_b32_e64 v176, v176, v14, s[34:35]
	v_cndmask_b32_e64 v176, v176, v15, s[36:37]
	v_cvt_pk_bf16_f32 v176, v176, v176
	global_store_short v145, v176, s[22:23]
	s_waitcnt lgkmcnt(0)
	s_branch .LBB0_906
.Lls0_skip0:
	s_waitcnt vmcnt(0)
	s_branch .Lls0_back0

.LBB0_1143:
	s_or_b64 exec, exec, s[0:1]
	s_waitcnt lgkmcnt(0)
	v_mov_b32_e32 v0, v137
	v_readlane_b32 s0, v242, 0
	s_barrier
	s_nop 0
	v_ashrrev_i32_e32 v1, 6, v0
	v_lshl_add_u32 v1, s0, 2, v1
	v_readlane_b32 s0, v241, 12
	s_nop 1
	v_mul_lo_u32 v28, v1, s0
	v_add_u32_e32 v1, s0, v28
	v_min_i32_e32 v31, 0x2800, v1
	v_cmp_lt_i32_e32 vcc, v28, v31
	s_and_saveexec_b64 s[0:1], vcc
	s_xor_b64 s[2:3], exec, s[0:1]
	s_cbranch_execz .LBB0_1149
	v_readfirstlane_b32 s6, v28
	v_readfirstlane_b32 s7, v31
	v_readlane_b32 s36, v242, 42
	v_readlane_b32 s37, v242, 43
	v_readlane_b32 s14, v242, 1
	v_readlane_b32 s15, v242, 2
	v_readlane_b32 s20, v242, 3
	v_readlane_b32 s21, v242, 4
	v_and_b32_e32 v236, 63, v137
	v_lshlrev_b32_e32 v237, 3, v236
	v_lshlrev_b32_e32 v236, 4, v236
	v_mov_b32_e32 v238, 0x358637bd
	s_sub_u32 s36, s36, 0x118
	s_subb_u32 s37, s37, 0
	s_load_dwordx2 s[10:11], s[36:37], 0x60
	s_load_dwordx2 s[12:13], s[36:37], 0x68
	s_load_dwordx4 s[16:19], s[36:37], 0x0
	s_add_u32 s22, s20, 0x2f90000
	s_addc_u32 s23, s21, 0
	s_mov_b32 s8, -1
	s_waitcnt lgkmcnt(0)
	s_cmp_lt_u32 s6, 0x2000
	s_cselect_b32 s24, s16, s18
	s_cselect_b32 s25, s17, s19
	s_cselect_b32 s9, 0, 0x2000
	s_sub_u32 s9, s6, s9
	s_lshl_b32 s9, s9, 12
	s_add_u32 s24, s24, s9
	s_addc_u32 s25, s25, 0
	s_lshl_b32 s9, s6, 11
	s_add_u32 s9, s9, 0x9278100
	s_add_u32 s26, s20, s9
	s_addc_u32 s27, s21, 0
	global_load_dwordx2 v[204:205], v237, s[26:27] offset:0
	global_load_dwordx2 v[206:207], v237, s[26:27] offset:512
	global_load_dwordx2 v[208:209], v237, s[26:27] offset:1024
	global_load_dwordx2 v[210:211], v237, s[26:27] offset:1536
	global_load_dwordx4 v[188:191], v236, s[24:25] offset:0
	global_load_dwordx4 v[192:195], v236, s[24:25] offset:1024
	global_load_dwordx4 v[196:199], v236, s[24:25] offset:2048
	global_load_dwordx4 v[200:203], v236, s[24:25] offset:3072
.Lrp10_loop:
	s_sub_u32 s9, s6, 0x2000
	s_ashr_i32 s9, s9, 10
	s_add_i32 s9, s9, 1
	s_max_i32 s9, s9, 0
	s_cmp_eq_u32 s9, s8
	s_cbranch_scc1 .Lrp10_same0
	s_mov_b32 s8, s9
	s_add_i32 s9, s8, 0
	s_mul_i32 s9, s9, 0x6000
	s_add_u32 s36, s22, s9
	s_addc_u32 s37, s23, 0
	s_add_u32 s38, s36, 0x2000
	s_addc_u32 s39, s37, 0
	global_load_dwordx4 v[32:35], v236, s[38:39] offset:0
	global_load_dwordx4 v[36:39], v236, s[38:39] offset:1024
	global_load_dwordx4 v[40:43], v236, s[38:39] offset:2048
	global_load_dwordx4 v[44:47], v236, s[38:39] offset:3072
	global_load_dwordx4 v[48:51], v236, s[10:11] offset:0
	global_load_dwordx4 v[52:55], v236, s[10:11] offset:1024
	global_load_dwordx4 v[56:59], v236, s[10:11] offset:2048
	global_load_dwordx4 v[64:67], v236, s[10:11] offset:3072
	global_load_dwordx4 v[68:71], v236, s[12:13] offset:0
	global_load_dwordx4 v[72:75], v236, s[12:13] offset:1024
	global_load_dwordx4 v[76:79], v236, s[12:13] offset:2048
	global_load_dwordx4 v[100:103], v236, s[12:13] offset:3072
	s_add_u32 s38, s36, 0x4000
	s_addc_u32 s39, s37, 0
	global_load_dwordx4 v[104:107], v236, s[38:39] offset:0
	global_load_dwordx4 v[108:111], v236, s[38:39] offset:1024
	global_load_dwordx4 v[112:115], v236, s[38:39] offset:2048
	global_load_dwordx4 v[116:119], v236, s[38:39] offset:3072
	s_add_u32 s38, s36, 0x3000
	s_addc_u32 s39, s37, 0
	global_load_dwordx4 v[172:175], v236, s[38:39] offset:0
	global_load_dwordx4 v[176:179], v236, s[38:39] offset:1024
	global_load_dwordx4 v[180:183], v236, s[38:39] offset:2048
	global_load_dwordx4 v[184:187], v236, s[38:39] offset:3072
	s_waitcnt vmcnt(0)
	v_mul_f32_e32 v140, v32, v48
	v_mul_f32_e32 v141, v33, v49
	v_mul_f32_e32 v142, v34, v50
	v_mul_f32_e32 v143, v35, v51
	v_mul_f32_e32 v144, v36, v52
	v_mul_f32_e32 v145, v37, v53
	v_mul_f32_e32 v146, v38, v54
	v_mul_f32_e32 v147, v39, v55
	v_mul_f32_e32 v148, v40, v56
	v_mul_f32_e32 v149, v41, v57
	v_mul_f32_e32 v150, v42, v58
	v_mul_f32_e32 v151, v43, v59
	v_mul_f32_e32 v152, v44, v64
	v_mul_f32_e32 v153, v45, v65
	v_mul_f32_e32 v154, v46, v66
	v_mul_f32_e32 v155, v47, v67
	v_add_f32_e32 v104, 1.0, v104
	v_add_f32_e32 v105, 1.0, v105
	v_add_f32_e32 v106, 1.0, v106
	v_add_f32_e32 v107, 1.0, v107
	v_add_f32_e32 v108, 1.0, v108
	v_add_f32_e32 v109, 1.0, v109
	v_add_f32_e32 v110, 1.0, v110
	v_add_f32_e32 v111, 1.0, v111
	v_add_f32_e32 v112, 1.0, v112
	v_add_f32_e32 v113, 1.0, v113
	v_add_f32_e32 v114, 1.0, v114
	v_add_f32_e32 v115, 1.0, v115
	v_add_f32_e32 v116, 1.0, v116
	v_add_f32_e32 v117, 1.0, v117
	v_add_f32_e32 v118, 1.0, v118
	v_add_f32_e32 v119, 1.0, v119
	v_mul_f32_e32 v156, v68, v104
	v_mul_f32_e32 v157, v69, v105
	v_mul_f32_e32 v158, v70, v106
	v_mul_f32_e32 v159, v71, v107
	v_mul_f32_e32 v160, v72, v108
	v_mul_f32_e32 v161, v73, v109
	v_mul_f32_e32 v162, v74, v110
	v_mul_f32_e32 v163, v75, v111
	v_mul_f32_e32 v164, v76, v112
	v_mul_f32_e32 v165, v77, v113
	v_mul_f32_e32 v166, v78, v114
	v_mul_f32_e32 v167, v79, v115
	v_mul_f32_e32 v168, v100, v116
	v_mul_f32_e32 v169, v101, v117
	v_mul_f32_e32 v170, v102, v118
	v_mul_f32_e32 v171, v103, v119
.Lrp10_same0:
	s_lshl_b32 s9, s6, 12
	s_add_u32 s32, s14, s9
	s_addc_u32 s33, s15, 0
	s_lshl_b32 s9, s6, 11
	s_add_u32 s9, s9, 0x30f8100
	s_add_u32 s34, s20, s9
	s_addc_u32 s35, s21, 0
	s_add_i32 s6, s6, 1
	s_cmp_lt_u32 s6, s7
	s_cbranch_scc0 .Lrp10_last0
	s_cmp_lt_u32 s6, 0x2000
	s_cselect_b32 s28, s16, s18
	s_cselect_b32 s29, s17, s19
	s_cselect_b32 s9, 0, 0x2000
	s_sub_u32 s9, s6, s9
	s_lshl_b32 s9, s9, 12
	s_add_u32 s28, s28, s9
	s_addc_u32 s29, s29, 0
	s_lshl_b32 s9, s6, 11
	s_add_u32 s9, s9, 0x9278100
	s_add_u32 s30, s20, s9
	s_addc_u32 s31, s21, 0
	global_load_dwordx2 v[228:229], v237, s[30:31] offset:0
	global_load_dwordx2 v[230:231], v237, s[30:31] offset:512
	global_load_dwordx2 v[232:233], v237, s[30:31] offset:1024
	global_load_dwordx2 v[234:235], v237, s[30:31] offset:1536
	global_load_dwordx4 v[212:215], v236, s[28:29] offset:0
	global_load_dwordx4 v[216:219], v236, s[28:29] offset:1024
	global_load_dwordx4 v[220:223], v236, s[28:29] offset:2048
	global_load_dwordx4 v[224:227], v236, s[28:29] offset:3072
	s_waitcnt vmcnt(16)
	s_branch .Lrp10_go0
.Lrp10_last0:
	s_waitcnt vmcnt(8)
.Lrp10_go0:
	v_lshlrev_b32_e32 v100, 16, v204
	v_and_b32_e32 v101, 0xffff0000, v204
	v_lshlrev_b32_e32 v102, 16, v205
	v_and_b32_e32 v103, 0xffff0000, v205
	v_lshlrev_b32_e32 v104, 16, v206
	v_and_b32_e32 v105, 0xffff0000, v206
	v_lshlrev_b32_e32 v106, 16, v207
	v_and_b32_e32 v107, 0xffff0000, v207
	v_lshlrev_b32_e32 v108, 16, v208
	v_and_b32_e32 v109, 0xffff0000, v208
	v_lshlrev_b32_e32 v110, 16, v209
	v_and_b32_e32 v111, 0xffff0000, v209
	v_lshlrev_b32_e32 v112, 16, v210
	v_and_b32_e32 v113, 0xffff0000, v210
	v_lshlrev_b32_e32 v114, 16, v211
	v_and_b32_e32 v115, 0xffff0000, v211
	v_mul_f32_e32 v132, v100, v100
	v_mul_f32_e32 v133, v101, v101
	v_fmac_f32_e32 v132, v102, v102
	v_fmac_f32_e32 v133, v103, v103
	v_fmac_f32_e32 v132, v104, v104
	v_fmac_f32_e32 v133, v105, v105
	v_fmac_f32_e32 v132, v106, v106
	v_fmac_f32_e32 v133, v107, v107
	v_fmac_f32_e32 v132, v108, v108
	v_fmac_f32_e32 v133, v109, v109
	v_fmac_f32_e32 v132, v110, v110
	v_fmac_f32_e32 v133, v111, v111
	v_fmac_f32_e32 v132, v112, v112
	v_fmac_f32_e32 v133, v113, v113
	v_fmac_f32_e32 v132, v114, v114
	v_fmac_f32_e32 v133, v115, v115
	v_add_f32_e32 v132, v132, v133
	s_nop 1
	v_add_f32_dpp v132, v132, v132 quad_perm:[1,0,3,2] row_mask:0xf bank_mask:0xf bound_ctrl:1
	s_nop 1
	v_add_f32_dpp v132, v132, v132 quad_perm:[2,3,0,1] row_mask:0xf bank_mask:0xf bound_ctrl:1
	s_nop 1
	v_add_f32_dpp v132, v132, v132 row_ror:4 row_mask:0xf bank_mask:0xf bound_ctrl:1
	s_nop 1
	v_add_f32_dpp v132, v132, v132 row_ror:8 row_mask:0xf bank_mask:0xf bound_ctrl:1
	s_nop 1
	v_readlane_b32 s9, v132, 0
	v_readlane_b32 s38, v132, 16
	v_readlane_b32 s39, v132, 32
	v_readlane_b32 s40, v132, 48
	s_nop 2
	v_mov_b32_e32 v132, s9
	v_add_f32_e32 v132, s38, v132
	v_mov_b32_e32 v135, s39
	v_add_f32_e32 v135, s40, v135
	v_add_f32_e32 v132, v132, v135
	v_fmamk_f32 v132, v132, 0x3a800000, v238
	v_rsq_f32_e32 v132, v132
	s_nop 0
	v_mul_f32_e32 v100, v100, v132
	v_mul_f32_e32 v101, v101, v132
	v_mul_f32_e32 v102, v102, v132
	v_mul_f32_e32 v103, v103, v132
	v_mul_f32_e32 v104, v104, v132
	v_mul_f32_e32 v105, v105, v132
	v_mul_f32_e32 v106, v106, v132
	v_mul_f32_e32 v107, v107, v132
	v_mul_f32_e32 v108, v108, v132
	v_mul_f32_e32 v109, v109, v132
	v_mul_f32_e32 v110, v110, v132
	v_mul_f32_e32 v111, v111, v132
	v_mul_f32_e32 v112, v112, v132
	v_mul_f32_e32 v113, v113, v132
	v_mul_f32_e32 v114, v114, v132
	v_mul_f32_e32 v115, v115, v132
	v_fmac_f32_e32 v188, v140, v100
	v_fmac_f32_e32 v189, v141, v101
	v_fmac_f32_e32 v190, v142, v102
	v_fmac_f32_e32 v191, v143, v103
	v_fmac_f32_e32 v192, v144, v104
	v_fmac_f32_e32 v193, v145, v105
	v_fmac_f32_e32 v194, v146, v106
	v_fmac_f32_e32 v195, v147, v107
	v_fmac_f32_e32 v196, v148, v108
	v_fmac_f32_e32 v197, v149, v109
	v_fmac_f32_e32 v198, v150, v110
	v_fmac_f32_e32 v199, v151, v111
	v_fmac_f32_e32 v200, v152, v112
	v_fmac_f32_e32 v201, v153, v113
	v_fmac_f32_e32 v202, v154, v114
	v_fmac_f32_e32 v203, v155, v115
	global_store_dwordx4 v236, v[188:191], s[32:33] offset:0
	global_store_dwordx4 v236, v[192:195], s[32:33] offset:1024
	global_store_dwordx4 v236, v[196:199], s[32:33] offset:2048
	global_store_dwordx4 v236, v[200:203], s[32:33] offset:3072
	v_mul_f32_e32 v132, v188, v188
	v_mul_f32_e32 v133, v189, v189
	v_fmac_f32_e32 v132, v190, v190
	v_fmac_f32_e32 v133, v191, v191
	v_fmac_f32_e32 v132, v192, v192
	v_fmac_f32_e32 v133, v193, v193
	v_fmac_f32_e32 v132, v194, v194
	v_fmac_f32_e32 v133, v195, v195
	v_fmac_f32_e32 v132, v196, v196
	v_fmac_f32_e32 v133, v197, v197
	v_fmac_f32_e32 v132, v198, v198
	v_fmac_f32_e32 v133, v199, v199
	v_fmac_f32_e32 v132, v200, v200
	v_fmac_f32_e32 v133, v201, v201
	v_fmac_f32_e32 v132, v202, v202
	v_fmac_f32_e32 v133, v203, v203
	v_add_f32_e32 v132, v132, v133
	s_nop 1
	v_add_f32_dpp v132, v132, v132 quad_perm:[1,0,3,2] row_mask:0xf bank_mask:0xf bound_ctrl:1
	s_nop 1
	v_add_f32_dpp v132, v132, v132 quad_perm:[2,3,0,1] row_mask:0xf bank_mask:0xf bound_ctrl:1
	s_nop 1
	v_add_f32_dpp v132, v132, v132 row_ror:4 row_mask:0xf bank_mask:0xf bound_ctrl:1
	s_nop 1
	v_add_f32_dpp v132, v132, v132 row_ror:8 row_mask:0xf bank_mask:0xf bound_ctrl:1
	s_nop 1
	v_readlane_b32 s9, v132, 0
	v_readlane_b32 s38, v132, 16
	v_readlane_b32 s39, v132, 32
	v_readlane_b32 s40, v132, 48
	s_nop 2
	v_mov_b32_e32 v132, s9
	v_add_f32_e32 v132, s38, v132
	v_mov_b32_e32 v135, s39
	v_add_f32_e32 v135, s40, v135
	v_add_f32_e32 v132, v132, v135
	v_fmamk_f32 v132, v132, 0x3a800000, v238
	v_rsq_f32_e32 v132, v132
	s_nop 0
	v_mul_f32_e32 v116, v188, v132
	v_mul_f32_e32 v117, v189, v132
	v_mul_f32_e32 v118, v190, v132
	v_mul_f32_e32 v119, v191, v132
	v_mul_f32_e32 v120, v192, v132
	v_mul_f32_e32 v121, v193, v132
	v_mul_f32_e32 v122, v194, v132
	v_mul_f32_e32 v123, v195, v132
	v_mul_f32_e32 v124, v196, v132
	v_mul_f32_e32 v125, v197, v132
	v_mul_f32_e32 v126, v198, v132
	v_mul_f32_e32 v127, v199, v132
	v_mul_f32_e32 v128, v200, v132
	v_mul_f32_e32 v129, v201, v132
	v_mul_f32_e32 v130, v202, v132
	v_mul_f32_e32 v131, v203, v132
	v_fma_f32 v116, v116, v156, v172
	v_fma_f32 v117, v117, v157, v173
	v_fma_f32 v118, v118, v158, v174
	v_fma_f32 v119, v119, v159, v175
	v_fma_f32 v120, v120, v160, v176
	v_fma_f32 v121, v121, v161, v177
	v_fma_f32 v122, v122, v162, v178
	v_fma_f32 v123, v123, v163, v179
	v_fma_f32 v124, v124, v164, v180
	v_fma_f32 v125, v125, v165, v181
	v_fma_f32 v126, v126, v166, v182
	v_fma_f32 v127, v127, v167, v183
	v_fma_f32 v128, v128, v168, v184
	v_fma_f32 v129, v129, v169, v185
	v_fma_f32 v130, v130, v170, v186
	v_fma_f32 v131, v131, v171, v187
	v_cvt_pk_bf16_f32 v116, v116, v117
	v_cvt_pk_bf16_f32 v117, v118, v119
	v_cvt_pk_bf16_f32 v118, v120, v121
	v_cvt_pk_bf16_f32 v119, v122, v123
	v_cvt_pk_bf16_f32 v120, v124, v125
	v_cvt_pk_bf16_f32 v121, v126, v127
	v_cvt_pk_bf16_f32 v122, v128, v129
	v_cvt_pk_bf16_f32 v123, v130, v131
	global_store_dwordx2 v237, v[116:117], s[34:35] offset:0
	global_store_dwordx2 v237, v[118:119], s[34:35] offset:512
	global_store_dwordx2 v237, v[120:121], s[34:35] offset:1024
	global_store_dwordx2 v237, v[122:123], s[34:35] offset:1536
	s_cmp_lt_u32 s6, s7
	s_cbranch_scc0 .Lrp10_done
	s_sub_u32 s9, s6, 0x2000
	s_ashr_i32 s9, s9, 10
	s_add_i32 s9, s9, 1
	s_max_i32 s9, s9, 0
	s_cmp_eq_u32 s9, s8
	s_cbranch_scc1 .Lrp10_same1
	s_mov_b32 s8, s9
	s_add_i32 s9, s8, 0
	s_mul_i32 s9, s9, 0x6000
	s_add_u32 s36, s22, s9
	s_addc_u32 s37, s23, 0
	s_add_u32 s38, s36, 0x2000
	s_addc_u32 s39, s37, 0
	global_load_dwordx4 v[32:35], v236, s[38:39] offset:0
	global_load_dwordx4 v[36:39], v236, s[38:39] offset:1024
	global_load_dwordx4 v[40:43], v236, s[38:39] offset:2048
	global_load_dwordx4 v[44:47], v236, s[38:39] offset:3072
	global_load_dwordx4 v[48:51], v236, s[10:11] offset:0
	global_load_dwordx4 v[52:55], v236, s[10:11] offset:1024
	global_load_dwordx4 v[56:59], v236, s[10:11] offset:2048
	global_load_dwordx4 v[64:67], v236, s[10:11] offset:3072
	global_load_dwordx4 v[68:71], v236, s[12:13] offset:0
	global_load_dwordx4 v[72:75], v236, s[12:13] offset:1024
	global_load_dwordx4 v[76:79], v236, s[12:13] offset:2048
	global_load_dwordx4 v[100:103], v236, s[12:13] offset:3072
	s_add_u32 s38, s36, 0x4000
	s_addc_u32 s39, s37, 0
	global_load_dwordx4 v[104:107], v236, s[38:39] offset:0
	global_load_dwordx4 v[108:111], v236, s[38:39] offset:1024
	global_load_dwordx4 v[112:115], v236, s[38:39] offset:2048
	global_load_dwordx4 v[116:119], v236, s[38:39] offset:3072
	s_add_u32 s38, s36, 0x3000
	s_addc_u32 s39, s37, 0
	global_load_dwordx4 v[172:175], v236, s[38:39] offset:0
	global_load_dwordx4 v[176:179], v236, s[38:39] offset:1024
	global_load_dwordx4 v[180:183], v236, s[38:39] offset:2048
	global_load_dwordx4 v[184:187], v236, s[38:39] offset:3072
	s_waitcnt vmcnt(0)
	v_mul_f32_e32 v140, v32, v48
	v_mul_f32_e32 v141, v33, v49
	v_mul_f32_e32 v142, v34, v50
	v_mul_f32_e32 v143, v35, v51
	v_mul_f32_e32 v144, v36, v52
	v_mul_f32_e32 v145, v37, v53
	v_mul_f32_e32 v146, v38, v54
	v_mul_f32_e32 v147, v39, v55
	v_mul_f32_e32 v148, v40, v56
	v_mul_f32_e32 v149, v41, v57
	v_mul_f32_e32 v150, v42, v58
	v_mul_f32_e32 v151, v43, v59
	v_mul_f32_e32 v152, v44, v64
	v_mul_f32_e32 v153, v45, v65
	v_mul_f32_e32 v154, v46, v66
	v_mul_f32_e32 v155, v47, v67
	v_add_f32_e32 v104, 1.0, v104
	v_add_f32_e32 v105, 1.0, v105
	v_add_f32_e32 v106, 1.0, v106
	v_add_f32_e32 v107, 1.0, v107
	v_add_f32_e32 v108, 1.0, v108
	v_add_f32_e32 v109, 1.0, v109
	v_add_f32_e32 v110, 1.0, v110
	v_add_f32_e32 v111, 1.0, v111
	v_add_f32_e32 v112, 1.0, v112
	v_add_f32_e32 v113, 1.0, v113
	v_add_f32_e32 v114, 1.0, v114
	v_add_f32_e32 v115, 1.0, v115
	v_add_f32_e32 v116, 1.0, v116
	v_add_f32_e32 v117, 1.0, v117
	v_add_f32_e32 v118, 1.0, v118
	v_add_f32_e32 v119, 1.0, v119
	v_mul_f32_e32 v156, v68, v104
	v_mul_f32_e32 v157, v69, v105
	v_mul_f32_e32 v158, v70, v106
	v_mul_f32_e32 v159, v71, v107
	v_mul_f32_e32 v160, v72, v108
	v_mul_f32_e32 v161, v73, v109
	v_mul_f32_e32 v162, v74, v110
	v_mul_f32_e32 v163, v75, v111
	v_mul_f32_e32 v164, v76, v112
	v_mul_f32_e32 v165, v77, v113
	v_mul_f32_e32 v166, v78, v114
	v_mul_f32_e32 v167, v79, v115
	v_mul_f32_e32 v168, v100, v116
	v_mul_f32_e32 v169, v101, v117
	v_mul_f32_e32 v170, v102, v118
	v_mul_f32_e32 v171, v103, v119
.Lrp10_same1:
	s_lshl_b32 s9, s6, 12
	s_add_u32 s32, s14, s9
	s_addc_u32 s33, s15, 0
	s_lshl_b32 s9, s6, 11
	s_add_u32 s9, s9, 0x30f8100
	s_add_u32 s34, s20, s9
	s_addc_u32 s35, s21, 0
	s_add_i32 s6, s6, 1
	s_cmp_lt_u32 s6, s7
	s_cbranch_scc0 .Lrp10_last1
	s_cmp_lt_u32 s6, 0x2000
	s_cselect_b32 s24, s16, s18
	s_cselect_b32 s25, s17, s19
	s_cselect_b32 s9, 0, 0x2000
	s_sub_u32 s9, s6, s9
	s_lshl_b32 s9, s9, 12
	s_add_u32 s24, s24, s9
	s_addc_u32 s25, s25, 0
	s_lshl_b32 s9, s6, 11
	s_add_u32 s9, s9, 0x9278100
	s_add_u32 s26, s20, s9
	s_addc_u32 s27, s21, 0
	global_load_dwordx2 v[204:205], v237, s[26:27] offset:0
	global_load_dwordx2 v[206:207], v237, s[26:27] offset:512
	global_load_dwordx2 v[208:209], v237, s[26:27] offset:1024
	global_load_dwordx2 v[210:211], v237, s[26:27] offset:1536
	global_load_dwordx4 v[188:191], v236, s[24:25] offset:0
	global_load_dwordx4 v[192:195], v236, s[24:25] offset:1024
	global_load_dwordx4 v[196:199], v236, s[24:25] offset:2048
	global_load_dwordx4 v[200:203], v236, s[24:25] offset:3072
	s_waitcnt vmcnt(16)
	s_branch .Lrp10_go1

.Lrp10_go1:
	v_lshlrev_b32_e32 v100, 16, v228
	v_and_b32_e32 v101, 0xffff0000, v228
	v_lshlrev_b32_e32 v102, 16, v229
	v_and_b32_e32 v103, 0xffff0000, v229
	v_lshlrev_b32_e32 v104, 16, v230
	v_and_b32_e32 v105, 0xffff0000, v230
	v_lshlrev_b32_e32 v106, 16, v231
	v_and_b32_e32 v107, 0xffff0000, v231
	v_lshlrev_b32_e32 v108, 16, v232
	v_and_b32_e32 v109, 0xffff0000, v232
	v_lshlrev_b32_e32 v110, 16, v233
	v_and_b32_e32 v111, 0xffff0000, v233
	v_lshlrev_b32_e32 v112, 16, v234
	v_and_b32_e32 v113, 0xffff0000, v234
	v_lshlrev_b32_e32 v114, 16, v235
	v_and_b32_e32 v115, 0xffff0000, v235
	v_mul_f32_e32 v132, v100, v100
	v_mul_f32_e32 v133, v101, v101
	v_fmac_f32_e32 v132, v102, v102
	v_fmac_f32_e32 v133, v103, v103
	v_fmac_f32_e32 v132, v104, v104
	v_fmac_f32_e32 v133, v105, v105
	v_fmac_f32_e32 v132, v106, v106
	v_fmac_f32_e32 v133, v107, v107
	v_fmac_f32_e32 v132, v108, v108
	v_fmac_f32_e32 v133, v109, v109
	v_fmac_f32_e32 v132, v110, v110
	v_fmac_f32_e32 v133, v111, v111
	v_fmac_f32_e32 v132, v112, v112
	v_fmac_f32_e32 v133, v113, v113
	v_fmac_f32_e32 v132, v114, v114
	v_fmac_f32_e32 v133, v115, v115
	v_add_f32_e32 v132, v132, v133
	s_nop 1
	v_add_f32_dpp v132, v132, v132 quad_perm:[1,0,3,2] row_mask:0xf bank_mask:0xf bound_ctrl:1
	s_nop 1
	v_add_f32_dpp v132, v132, v132 quad_perm:[2,3,0,1] row_mask:0xf bank_mask:0xf bound_ctrl:1
	s_nop 1
	v_add_f32_dpp v132, v132, v132 row_ror:4 row_mask:0xf bank_mask:0xf bound_ctrl:1
	s_nop 1
	v_add_f32_dpp v132, v132, v132 row_ror:8 row_mask:0xf bank_mask:0xf bound_ctrl:1
	s_nop 1
	v_readlane_b32 s9, v132, 0
	v_readlane_b32 s38, v132, 16
	v_readlane_b32 s39, v132, 32
	v_readlane_b32 s40, v132, 48
	s_nop 2
	v_mov_b32_e32 v132, s9
	v_add_f32_e32 v132, s38, v132
	v_mov_b32_e32 v135, s39
	v_add_f32_e32 v135, s40, v135
	v_add_f32_e32 v132, v132, v135
	v_fmamk_f32 v132, v132, 0x3a800000, v238
	v_rsq_f32_e32 v132, v132
	s_nop 0
	v_mul_f32_e32 v100, v100, v132
	v_mul_f32_e32 v101, v101, v132
	v_mul_f32_e32 v102, v102, v132
	v_mul_f32_e32 v103, v103, v132
	v_mul_f32_e32 v104, v104, v132
	v_mul_f32_e32 v105, v105, v132
	v_mul_f32_e32 v106, v106, v132
	v_mul_f32_e32 v107, v107, v132
	v_mul_f32_e32 v108, v108, v132
	v_mul_f32_e32 v109, v109, v132
	v_mul_f32_e32 v110, v110, v132
	v_mul_f32_e32 v111, v111, v132
	v_mul_f32_e32 v112, v112, v132
	v_mul_f32_e32 v113, v113, v132
	v_mul_f32_e32 v114, v114, v132
	v_mul_f32_e32 v115, v115, v132
	v_fmac_f32_e32 v212, v140, v100
	v_fmac_f32_e32 v213, v141, v101
	v_fmac_f32_e32 v214, v142, v102
	v_fmac_f32_e32 v215, v143, v103
	v_fmac_f32_e32 v216, v144, v104
	v_fmac_f32_e32 v217, v145, v105
	v_fmac_f32_e32 v218, v146, v106
	v_fmac_f32_e32 v219, v147, v107
	v_fmac_f32_e32 v220, v148, v108
	v_fmac_f32_e32 v221, v149, v109
	v_fmac_f32_e32 v222, v150, v110
	v_fmac_f32_e32 v223, v151, v111
	v_fmac_f32_e32 v224, v152, v112
	v_fmac_f32_e32 v225, v153, v113
	v_fmac_f32_e32 v226, v154, v114
	v_fmac_f32_e32 v227, v155, v115
	global_store_dwordx4 v236, v[212:215], s[32:33] offset:0
	global_store_dwordx4 v236, v[216:219], s[32:33] offset:1024
	global_store_dwordx4 v236, v[220:223], s[32:33] offset:2048
	global_store_dwordx4 v236, v[224:227], s[32:33] offset:3072
	v_mul_f32_e32 v132, v212, v212
	v_mul_f32_e32 v133, v213, v213
	v_fmac_f32_e32 v132, v214, v214
	v_fmac_f32_e32 v133, v215, v215
	v_fmac_f32_e32 v132, v216, v216
	v_fmac_f32_e32 v133, v217, v217
	v_fmac_f32_e32 v132, v218, v218
	v_fmac_f32_e32 v133, v219, v219
	v_fmac_f32_e32 v132, v220, v220
	v_fmac_f32_e32 v133, v221, v221
	v_fmac_f32_e32 v132, v222, v222
	v_fmac_f32_e32 v133, v223, v223
	v_fmac_f32_e32 v132, v224, v224
	v_fmac_f32_e32 v133, v225, v225
	v_fmac_f32_e32 v132, v226, v226
	v_fmac_f32_e32 v133, v227, v227
	v_add_f32_e32 v132, v132, v133
	s_nop 1
	v_add_f32_dpp v132, v132, v132 quad_perm:[1,0,3,2] row_mask:0xf bank_mask:0xf bound_ctrl:1
	s_nop 1
	v_add_f32_dpp v132, v132, v132 quad_perm:[2,3,0,1] row_mask:0xf bank_mask:0xf bound_ctrl:1
	s_nop 1
	v_add_f32_dpp v132, v132, v132 row_ror:4 row_mask:0xf bank_mask:0xf bound_ctrl:1
	s_nop 1
	v_add_f32_dpp v132, v132, v132 row_ror:8 row_mask:0xf bank_mask:0xf bound_ctrl:1
	s_nop 1
	v_readlane_b32 s9, v132, 0
	v_readlane_b32 s38, v132, 16
	v_readlane_b32 s39, v132, 32
	v_readlane_b32 s40, v132, 48
	s_nop 2
	v_mov_b32_e32 v132, s9
	v_add_f32_e32 v132, s38, v132
	v_mov_b32_e32 v135, s39
	v_add_f32_e32 v135, s40, v135
	v_add_f32_e32 v132, v132, v135
	v_fmamk_f32 v132, v132, 0x3a800000, v238
	v_rsq_f32_e32 v132, v132
	s_nop 0
	v_mul_f32_e32 v116, v212, v132
	v_mul_f32_e32 v117, v213, v132
	v_mul_f32_e32 v118, v214, v132
	v_mul_f32_e32 v119, v215, v132
	v_mul_f32_e32 v120, v216, v132
	v_mul_f32_e32 v121, v217, v132
	v_mul_f32_e32 v122, v218, v132
	v_mul_f32_e32 v123, v219, v132
	v_mul_f32_e32 v124, v220, v132
	v_mul_f32_e32 v125, v221, v132
	v_mul_f32_e32 v126, v222, v132
	v_mul_f32_e32 v127, v223, v132
	v_mul_f32_e32 v128, v224, v132
	v_mul_f32_e32 v129, v225, v132
	v_mul_f32_e32 v130, v226, v132
	v_mul_f32_e32 v131, v227, v132
	v_fma_f32 v116, v116, v156, v172
	v_fma_f32 v117, v117, v157, v173
	v_fma_f32 v118, v118, v158, v174
	v_fma_f32 v119, v119, v159, v175
	v_fma_f32 v120, v120, v160, v176
	v_fma_f32 v121, v121, v161, v177
	v_fma_f32 v122, v122, v162, v178
	v_fma_f32 v123, v123, v163, v179
	v_fma_f32 v124, v124, v164, v180
	v_fma_f32 v125, v125, v165, v181
	v_fma_f32 v126, v126, v166, v182
	v_fma_f32 v127, v127, v167, v183
	v_fma_f32 v128, v128, v168, v184
	v_fma_f32 v129, v129, v169, v185
	v_fma_f32 v130, v130, v170, v186
	v_fma_f32 v131, v131, v171, v187
	v_cvt_pk_bf16_f32 v116, v116, v117
	v_cvt_pk_bf16_f32 v117, v118, v119
	v_cvt_pk_bf16_f32 v118, v120, v121
	v_cvt_pk_bf16_f32 v119, v122, v123
	v_cvt_pk_bf16_f32 v120, v124, v125
	v_cvt_pk_bf16_f32 v121, v126, v127
	v_cvt_pk_bf16_f32 v122, v128, v129
	v_cvt_pk_bf16_f32 v123, v130, v131
	global_store_dwordx2 v237, v[116:117], s[34:35] offset:0
	global_store_dwordx2 v237, v[118:119], s[34:35] offset:512
	global_store_dwordx2 v237, v[120:121], s[34:35] offset:1024
	global_store_dwordx2 v237, v[122:123], s[34:35] offset:1536
	s_cmp_lt_u32 s6, s7
	s_cbranch_scc1 .Lrp10_loop
.Lrp10_done:
	s_mov_b64 s[4:5], 0
.LBB0_1148:
	s_or_b64 exec, exec, s[4:5]

.LBB0_1317:
	s_or_b64 exec, exec, s[0:1]
	s_lshl_b32 s68, s66, 2
	s_abs_i32 s0, s68
	v_cvt_f32_u32_e32 v1, s0
	s_sub_i32 s3, 0, s0
	s_add_i32 s1, s68, 0x27ff
	s_xor_b32 s2, s1, s68
	v_rcp_iflag_f32_e32 v1, v1
	s_abs_i32 s1, s1
	s_ashr_i32 s2, s2, 31
	s_waitcnt lgkmcnt(0)
	v_mov_b32_e32 v0, v137
	v_mul_f32_e32 v1, 0x4f7ffffe, v1
	v_cvt_u32_f32_e32 v1, v1
	s_barrier
	v_readfirstlane_b32 s4, v1
	s_mul_i32 s3, s3, s4
	s_mul_hi_u32 s3, s4, s3
	s_add_i32 s4, s4, s3
	s_mul_hi_u32 s3, s1, s4
	s_mul_i32 s4, s3, s0
	s_sub_i32 s1, s1, s4
	s_add_i32 s4, s3, 1
	s_sub_i32 s5, s1, s0
	s_cmp_ge_u32 s1, s0
	s_cselect_b32 s3, s4, s3
	s_cselect_b32 s1, s5, s1
	s_add_i32 s4, s3, 1
	s_cmp_ge_u32 s1, s0
	s_cselect_b32 s0, s4, s3
	s_xor_b32 s0, s0, s2
	s_sub_i32 s1, s0, s2
	v_ashrrev_i32_e32 v2, 6, v0
	v_readlane_b32 s0, v242, 0
	v_writelane_b32 v242, s1, 56
	s_nop 0
	v_lshl_add_u32 v1, s0, 2, v2
	v_mul_lo_u32 v28, v1, s1
	v_add_u32_e32 v1, s1, v28
	v_min_i32_e32 v90, 0x2800, v1
	v_cmp_lt_i32_e32 vcc, v28, v90
	s_and_saveexec_b64 s[0:1], vcc
	s_cbranch_execz .LBB0_1322
	v_readfirstlane_b32 s6, v28
	v_readfirstlane_b32 s7, v90
	v_readlane_b32 s36, v242, 42
	v_readlane_b32 s37, v242, 43
	v_readlane_b32 s14, v242, 1
	v_readlane_b32 s15, v242, 2
	v_readlane_b32 s20, v242, 3
	v_readlane_b32 s21, v242, 4
	v_and_b32_e32 v236, 63, v137
	v_lshlrev_b32_e32 v237, 3, v236
	v_lshlrev_b32_e32 v236, 4, v236
	v_mov_b32_e32 v238, 0x358637bd
	s_sub_u32 s36, s36, 0x118
	s_subb_u32 s37, s37, 0
	s_load_dwordx2 s[10:11], s[36:37], 0x70
	s_load_dwordx2 s[12:13], s[36:37], 0x58
	s_add_u32 s22, s20, 0x2f90000
	s_addc_u32 s23, s21, 0
	s_mov_b32 s8, -1
	s_waitcnt lgkmcnt(0)
	s_add_u32 s12, s12, 0x1000
	s_addc_u32 s13, s13, 0
	s_lshl_b32 s9, s6, 12
	s_add_u32 s24, s14, s9
	s_addc_u32 s25, s15, 0
	s_lshl_b32 s9, s6, 11
	s_add_u32 s9, s9, 0x9278100
	s_add_u32 s26, s20, s9
	s_addc_u32 s27, s21, 0
	global_load_dwordx2 v[204:205], v237, s[26:27] offset:0
	global_load_dwordx2 v[206:207], v237, s[26:27] offset:512
	global_load_dwordx2 v[208:209], v237, s[26:27] offset:1024
	global_load_dwordx2 v[210:211], v237, s[26:27] offset:1536
	global_load_dwordx4 v[188:191], v236, s[24:25] offset:0
	global_load_dwordx4 v[192:195], v236, s[24:25] offset:1024
	global_load_dwordx4 v[196:199], v236, s[24:25] offset:2048
	global_load_dwordx4 v[200:203], v236, s[24:25] offset:3072
.Lrp20_loop:
	s_sub_u32 s9, s6, 0x2000
	s_ashr_i32 s9, s9, 10
	s_add_i32 s9, s9, 1
	s_max_i32 s9, s9, 0
	s_cmp_eq_u32 s9, s8
	s_cbranch_scc1 .Lrp20_same0
	s_mov_b32 s8, s9
	s_add_i32 s9, s8, 0
	s_mul_i32 s9, s9, 0x6000
	s_add_u32 s36, s22, s9
	s_addc_u32 s37, s23, 0
	s_add_u32 s38, s36, 0x5000
	s_addc_u32 s39, s37, 0
	global_load_dwordx4 v[32:35], v236, s[38:39] offset:0
	global_load_dwordx4 v[36:39], v236, s[38:39] offset:1024
	global_load_dwordx4 v[40:43], v236, s[38:39] offset:2048
	global_load_dwordx4 v[44:47], v236, s[38:39] offset:3072
	global_load_dwordx4 v[48:51], v236, s[10:11] offset:0
	global_load_dwordx4 v[52:55], v236, s[10:11] offset:1024
	global_load_dwordx4 v[56:59], v236, s[10:11] offset:2048
	global_load_dwordx4 v[64:67], v236, s[10:11] offset:3072
	s_add_i32 s9, s8, 3
	s_mul_i32 s9, s9, 0x6000
	s_add_u32 s36, s22, s9
	s_addc_u32 s37, s23, 0
	global_load_dwordx4 v[68:71], v236, s[12:13] offset:0
	global_load_dwordx4 v[72:75], v236, s[12:13] offset:1024
	global_load_dwordx4 v[76:79], v236, s[12:13] offset:2048
	global_load_dwordx4 v[100:103], v236, s[12:13] offset:3072
	s_add_u32 s38, s36, 0x1000
	s_addc_u32 s39, s37, 0
	global_load_dwordx4 v[104:107], v236, s[38:39] offset:0
	global_load_dwordx4 v[108:111], v236, s[38:39] offset:1024
	global_load_dwordx4 v[112:115], v236, s[38:39] offset:2048
	global_load_dwordx4 v[116:119], v236, s[38:39] offset:3072
	s_add_u32 s38, s36, 0x0
	s_addc_u32 s39, s37, 0
	global_load_dwordx4 v[172:175], v236, s[38:39] offset:0
	global_load_dwordx4 v[176:179], v236, s[38:39] offset:1024
	global_load_dwordx4 v[180:183], v236, s[38:39] offset:2048
	global_load_dwordx4 v[184:187], v236, s[38:39] offset:3072
	s_waitcnt vmcnt(0)
	v_mul_f32_e32 v140, v32, v48
	v_mul_f32_e32 v141, v33, v49
	v_mul_f32_e32 v142, v34, v50
	v_mul_f32_e32 v143, v35, v51
	v_mul_f32_e32 v144, v36, v52
	v_mul_f32_e32 v145, v37, v53
	v_mul_f32_e32 v146, v38, v54
	v_mul_f32_e32 v147, v39, v55
	v_mul_f32_e32 v148, v40, v56
	v_mul_f32_e32 v149, v41, v57
	v_mul_f32_e32 v150, v42, v58
	v_mul_f32_e32 v151, v43, v59
	v_mul_f32_e32 v152, v44, v64
	v_mul_f32_e32 v153, v45, v65
	v_mul_f32_e32 v154, v46, v66
	v_mul_f32_e32 v155, v47, v67
	v_add_f32_e32 v104, 1.0, v104
	v_add_f32_e32 v105, 1.0, v105
	v_add_f32_e32 v106, 1.0, v106
	v_add_f32_e32 v107, 1.0, v107
	v_add_f32_e32 v108, 1.0, v108
	v_add_f32_e32 v109, 1.0, v109
	v_add_f32_e32 v110, 1.0, v110
	v_add_f32_e32 v111, 1.0, v111
	v_add_f32_e32 v112, 1.0, v112
	v_add_f32_e32 v113, 1.0, v113
	v_add_f32_e32 v114, 1.0, v114
	v_add_f32_e32 v115, 1.0, v115
	v_add_f32_e32 v116, 1.0, v116
	v_add_f32_e32 v117, 1.0, v117
	v_add_f32_e32 v118, 1.0, v118
	v_add_f32_e32 v119, 1.0, v119
	v_mul_f32_e32 v156, v68, v104
	v_mul_f32_e32 v157, v69, v105
	v_mul_f32_e32 v158, v70, v106
	v_mul_f32_e32 v159, v71, v107
	v_mul_f32_e32 v160, v72, v108
	v_mul_f32_e32 v161, v73, v109
	v_mul_f32_e32 v162, v74, v110
	v_mul_f32_e32 v163, v75, v111
	v_mul_f32_e32 v164, v76, v112
	v_mul_f32_e32 v165, v77, v113
	v_mul_f32_e32 v166, v78, v114
	v_mul_f32_e32 v167, v79, v115
	v_mul_f32_e32 v168, v100, v116
	v_mul_f32_e32 v169, v101, v117
	v_mul_f32_e32 v170, v102, v118
	v_mul_f32_e32 v171, v103, v119
.Lrp20_same0:
	s_lshl_b32 s9, s6, 12
	s_add_u32 s32, s14, s9
	s_addc_u32 s33, s15, 0
	s_lshl_b32 s9, s6, 11
	s_add_u32 s9, s9, 0x30f8100
	s_add_u32 s34, s20, s9
	s_addc_u32 s35, s21, 0
	s_add_i32 s6, s6, 1
	s_cmp_lt_u32 s6, s7
	s_cbranch_scc0 .Lrp20_last0
	s_lshl_b32 s9, s6, 12
	s_add_u32 s28, s14, s9
	s_addc_u32 s29, s15, 0
	s_lshl_b32 s9, s6, 11
	s_add_u32 s9, s9, 0x9278100
	s_add_u32 s30, s20, s9
	s_addc_u32 s31, s21, 0
	global_load_dwordx2 v[228:229], v237, s[30:31] offset:0
	global_load_dwordx2 v[230:231], v237, s[30:31] offset:512
	global_load_dwordx2 v[232:233], v237, s[30:31] offset:1024
	global_load_dwordx2 v[234:235], v237, s[30:31] offset:1536
	global_load_dwordx4 v[212:215], v236, s[28:29] offset:0
	global_load_dwordx4 v[216:219], v236, s[28:29] offset:1024
	global_load_dwordx4 v[220:223], v236, s[28:29] offset:2048
	global_load_dwordx4 v[224:227], v236, s[28:29] offset:3072
	s_waitcnt vmcnt(16)
	s_branch .Lrp20_go0

.Lrp20_go0:
	v_lshlrev_b32_e32 v100, 16, v204
	v_and_b32_e32 v101, 0xffff0000, v204
	v_lshlrev_b32_e32 v102, 16, v205
	v_and_b32_e32 v103, 0xffff0000, v205
	v_lshlrev_b32_e32 v104, 16, v206
	v_and_b32_e32 v105, 0xffff0000, v206
	v_lshlrev_b32_e32 v106, 16, v207
	v_and_b32_e32 v107, 0xffff0000, v207
	v_lshlrev_b32_e32 v108, 16, v208
	v_and_b32_e32 v109, 0xffff0000, v208
	v_lshlrev_b32_e32 v110, 16, v209
	v_and_b32_e32 v111, 0xffff0000, v209
	v_lshlrev_b32_e32 v112, 16, v210
	v_and_b32_e32 v113, 0xffff0000, v210
	v_lshlrev_b32_e32 v114, 16, v211
	v_and_b32_e32 v115, 0xffff0000, v211
	v_mul_f32_e32 v132, v100, v100
	v_mul_f32_e32 v133, v101, v101
	v_fmac_f32_e32 v132, v102, v102
	v_fmac_f32_e32 v133, v103, v103
	v_fmac_f32_e32 v132, v104, v104
	v_fmac_f32_e32 v133, v105, v105
	v_fmac_f32_e32 v132, v106, v106
	v_fmac_f32_e32 v133, v107, v107
	v_fmac_f32_e32 v132, v108, v108
	v_fmac_f32_e32 v133, v109, v109
	v_fmac_f32_e32 v132, v110, v110
	v_fmac_f32_e32 v133, v111, v111
	v_fmac_f32_e32 v132, v112, v112
	v_fmac_f32_e32 v133, v113, v113
	v_fmac_f32_e32 v132, v114, v114
	v_fmac_f32_e32 v133, v115, v115
	v_add_f32_e32 v132, v132, v133
	s_nop 1
	v_add_f32_dpp v132, v132, v132 quad_perm:[1,0,3,2] row_mask:0xf bank_mask:0xf bound_ctrl:1
	s_nop 1
	v_add_f32_dpp v132, v132, v132 quad_perm:[2,3,0,1] row_mask:0xf bank_mask:0xf bound_ctrl:1
	s_nop 1
	v_add_f32_dpp v132, v132, v132 row_ror:4 row_mask:0xf bank_mask:0xf bound_ctrl:1
	s_nop 1
	v_add_f32_dpp v132, v132, v132 row_ror:8 row_mask:0xf bank_mask:0xf bound_ctrl:1
	s_nop 1
	v_readlane_b32 s9, v132, 0
	v_readlane_b32 s38, v132, 16
	v_readlane_b32 s39, v132, 32
	v_readlane_b32 s40, v132, 48
	s_nop 2
	v_mov_b32_e32 v132, s9
	v_add_f32_e32 v132, s38, v132
	v_mov_b32_e32 v135, s39
	v_add_f32_e32 v135, s40, v135
	v_add_f32_e32 v132, v132, v135
	v_fmamk_f32 v132, v132, 0x3a800000, v238
	v_rsq_f32_e32 v132, v132
	s_nop 0
	v_mul_f32_e32 v100, v100, v132
	v_mul_f32_e32 v101, v101, v132
	v_mul_f32_e32 v102, v102, v132
	v_mul_f32_e32 v103, v103, v132
	v_mul_f32_e32 v104, v104, v132
	v_mul_f32_e32 v105, v105, v132
	v_mul_f32_e32 v106, v106, v132
	v_mul_f32_e32 v107, v107, v132
	v_mul_f32_e32 v108, v108, v132
	v_mul_f32_e32 v109, v109, v132
	v_mul_f32_e32 v110, v110, v132
	v_mul_f32_e32 v111, v111, v132
	v_mul_f32_e32 v112, v112, v132
	v_mul_f32_e32 v113, v113, v132
	v_mul_f32_e32 v114, v114, v132
	v_mul_f32_e32 v115, v115, v132
	v_fmac_f32_e32 v188, v140, v100
	v_fmac_f32_e32 v189, v141, v101
	v_fmac_f32_e32 v190, v142, v102
	v_fmac_f32_e32 v191, v143, v103
	v_fmac_f32_e32 v192, v144, v104
	v_fmac_f32_e32 v193, v145, v105
	v_fmac_f32_e32 v194, v146, v106
	v_fmac_f32_e32 v195, v147, v107
	v_fmac_f32_e32 v196, v148, v108
	v_fmac_f32_e32 v197, v149, v109
	v_fmac_f32_e32 v198, v150, v110
	v_fmac_f32_e32 v199, v151, v111
	v_fmac_f32_e32 v200, v152, v112
	v_fmac_f32_e32 v201, v153, v113
	v_fmac_f32_e32 v202, v154, v114
	v_fmac_f32_e32 v203, v155, v115
	global_store_dwordx4 v236, v[188:191], s[32:33] offset:0
	global_store_dwordx4 v236, v[192:195], s[32:33] offset:1024
	global_store_dwordx4 v236, v[196:199], s[32:33] offset:2048
	global_store_dwordx4 v236, v[200:203], s[32:33] offset:3072
	v_mul_f32_e32 v132, v188, v188
	v_mul_f32_e32 v133, v189, v189
	v_fmac_f32_e32 v132, v190, v190
	v_fmac_f32_e32 v133, v191, v191
	v_fmac_f32_e32 v132, v192, v192
	v_fmac_f32_e32 v133, v193, v193
	v_fmac_f32_e32 v132, v194, v194
	v_fmac_f32_e32 v133, v195, v195
	v_fmac_f32_e32 v132, v196, v196
	v_fmac_f32_e32 v133, v197, v197
	v_fmac_f32_e32 v132, v198, v198
	v_fmac_f32_e32 v133, v199, v199
	v_fmac_f32_e32 v132, v200, v200
	v_fmac_f32_e32 v133, v201, v201
	v_fmac_f32_e32 v132, v202, v202
	v_fmac_f32_e32 v133, v203, v203
	v_add_f32_e32 v132, v132, v133
	s_nop 1
	v_add_f32_dpp v132, v132, v132 quad_perm:[1,0,3,2] row_mask:0xf bank_mask:0xf bound_ctrl:1
	s_nop 1
	v_add_f32_dpp v132, v132, v132 quad_perm:[2,3,0,1] row_mask:0xf bank_mask:0xf bound_ctrl:1
	s_nop 1
	v_add_f32_dpp v132, v132, v132 row_ror:4 row_mask:0xf bank_mask:0xf bound_ctrl:1
	s_nop 1
	v_add_f32_dpp v132, v132, v132 row_ror:8 row_mask:0xf bank_mask:0xf bound_ctrl:1
	s_nop 1
	v_readlane_b32 s9, v132, 0
	v_readlane_b32 s38, v132, 16
	v_readlane_b32 s39, v132, 32
	v_readlane_b32 s40, v132, 48
	s_nop 2
	v_mov_b32_e32 v132, s9
	v_add_f32_e32 v132, s38, v132
	v_mov_b32_e32 v135, s39
	v_add_f32_e32 v135, s40, v135
	v_add_f32_e32 v132, v132, v135
	v_fmamk_f32 v132, v132, 0x3a800000, v238
	v_rsq_f32_e32 v132, v132
	s_nop 0
	v_mul_f32_e32 v116, v188, v132
	v_mul_f32_e32 v117, v189, v132
	v_mul_f32_e32 v118, v190, v132
	v_mul_f32_e32 v119, v191, v132
	v_mul_f32_e32 v120, v192, v132
	v_mul_f32_e32 v121, v193, v132
	v_mul_f32_e32 v122, v194, v132
	v_mul_f32_e32 v123, v195, v132
	v_mul_f32_e32 v124, v196, v132
	v_mul_f32_e32 v125, v197, v132
	v_mul_f32_e32 v126, v198, v132
	v_mul_f32_e32 v127, v199, v132
	v_mul_f32_e32 v128, v200, v132
	v_mul_f32_e32 v129, v201, v132
	v_mul_f32_e32 v130, v202, v132
	v_mul_f32_e32 v131, v203, v132
	v_fma_f32 v116, v116, v156, v172
	v_fma_f32 v117, v117, v157, v173
	v_fma_f32 v118, v118, v158, v174
	v_fma_f32 v119, v119, v159, v175
	v_fma_f32 v120, v120, v160, v176
	v_fma_f32 v121, v121, v161, v177
	v_fma_f32 v122, v122, v162, v178
	v_fma_f32 v123, v123, v163, v179
	v_fma_f32 v124, v124, v164, v180
	v_fma_f32 v125, v125, v165, v181
	v_fma_f32 v126, v126, v166, v182
	v_fma_f32 v127, v127, v167, v183
	v_fma_f32 v128, v128, v168, v184
	v_fma_f32 v129, v129, v169, v185
	v_fma_f32 v130, v130, v170, v186
	v_fma_f32 v131, v131, v171, v187
	v_cvt_pk_bf16_f32 v116, v116, v117
	v_cvt_pk_bf16_f32 v117, v118, v119
	v_cvt_pk_bf16_f32 v118, v120, v121
	v_cvt_pk_bf16_f32 v119, v122, v123
	v_cvt_pk_bf16_f32 v120, v124, v125
	v_cvt_pk_bf16_f32 v121, v126, v127
	v_cvt_pk_bf16_f32 v122, v128, v129
	v_cvt_pk_bf16_f32 v123, v130, v131
	global_store_dwordx2 v237, v[116:117], s[34:35] offset:0
	global_store_dwordx2 v237, v[118:119], s[34:35] offset:512
	global_store_dwordx2 v237, v[120:121], s[34:35] offset:1024
	global_store_dwordx2 v237, v[122:123], s[34:35] offset:1536
	s_cmp_lt_u32 s6, s7
	s_cbranch_scc0 .Lrp20_done
	s_sub_u32 s9, s6, 0x2000
	s_ashr_i32 s9, s9, 10
	s_add_i32 s9, s9, 1
	s_max_i32 s9, s9, 0
	s_cmp_eq_u32 s9, s8
	s_cbranch_scc1 .Lrp20_same1
	s_mov_b32 s8, s9
	s_add_i32 s9, s8, 0
	s_mul_i32 s9, s9, 0x6000
	s_add_u32 s36, s22, s9
	s_addc_u32 s37, s23, 0
	s_add_u32 s38, s36, 0x5000
	s_addc_u32 s39, s37, 0
	global_load_dwordx4 v[32:35], v236, s[38:39] offset:0
	global_load_dwordx4 v[36:39], v236, s[38:39] offset:1024
	global_load_dwordx4 v[40:43], v236, s[38:39] offset:2048
	global_load_dwordx4 v[44:47], v236, s[38:39] offset:3072
	global_load_dwordx4 v[48:51], v236, s[10:11] offset:0
	global_load_dwordx4 v[52:55], v236, s[10:11] offset:1024
	global_load_dwordx4 v[56:59], v236, s[10:11] offset:2048
	global_load_dwordx4 v[64:67], v236, s[10:11] offset:3072
	s_add_i32 s9, s8, 3
	s_mul_i32 s9, s9, 0x6000
	s_add_u32 s36, s22, s9
	s_addc_u32 s37, s23, 0
	global_load_dwordx4 v[68:71], v236, s[12:13] offset:0
	global_load_dwordx4 v[72:75], v236, s[12:13] offset:1024
	global_load_dwordx4 v[76:79], v236, s[12:13] offset:2048
	global_load_dwordx4 v[100:103], v236, s[12:13] offset:3072
	s_add_u32 s38, s36, 0x1000
	s_addc_u32 s39, s37, 0
	global_load_dwordx4 v[104:107], v236, s[38:39] offset:0
	global_load_dwordx4 v[108:111], v236, s[38:39] offset:1024
	global_load_dwordx4 v[112:115], v236, s[38:39] offset:2048
	global_load_dwordx4 v[116:119], v236, s[38:39] offset:3072
	s_add_u32 s38, s36, 0x0
	s_addc_u32 s39, s37, 0
	global_load_dwordx4 v[172:175], v236, s[38:39] offset:0
	global_load_dwordx4 v[176:179], v236, s[38:39] offset:1024
	global_load_dwordx4 v[180:183], v236, s[38:39] offset:2048
	global_load_dwordx4 v[184:187], v236, s[38:39] offset:3072
	s_waitcnt vmcnt(0)
	v_mul_f32_e32 v140, v32, v48
	v_mul_f32_e32 v141, v33, v49
	v_mul_f32_e32 v142, v34, v50
	v_mul_f32_e32 v143, v35, v51
	v_mul_f32_e32 v144, v36, v52
	v_mul_f32_e32 v145, v37, v53
	v_mul_f32_e32 v146, v38, v54
	v_mul_f32_e32 v147, v39, v55
	v_mul_f32_e32 v148, v40, v56
	v_mul_f32_e32 v149, v41, v57
	v_mul_f32_e32 v150, v42, v58
	v_mul_f32_e32 v151, v43, v59
	v_mul_f32_e32 v152, v44, v64
	v_mul_f32_e32 v153, v45, v65
	v_mul_f32_e32 v154, v46, v66
	v_mul_f32_e32 v155, v47, v67
	v_add_f32_e32 v104, 1.0, v104
	v_add_f32_e32 v105, 1.0, v105
	v_add_f32_e32 v106, 1.0, v106
	v_add_f32_e32 v107, 1.0, v107
	v_add_f32_e32 v108, 1.0, v108
	v_add_f32_e32 v109, 1.0, v109
	v_add_f32_e32 v110, 1.0, v110
	v_add_f32_e32 v111, 1.0, v111
	v_add_f32_e32 v112, 1.0, v112
	v_add_f32_e32 v113, 1.0, v113
	v_add_f32_e32 v114, 1.0, v114
	v_add_f32_e32 v115, 1.0, v115
	v_add_f32_e32 v116, 1.0, v116
	v_add_f32_e32 v117, 1.0, v117
	v_add_f32_e32 v118, 1.0, v118
	v_add_f32_e32 v119, 1.0, v119
	v_mul_f32_e32 v156, v68, v104
	v_mul_f32_e32 v157, v69, v105
	v_mul_f32_e32 v158, v70, v106
	v_mul_f32_e32 v159, v71, v107
	v_mul_f32_e32 v160, v72, v108
	v_mul_f32_e32 v161, v73, v109
	v_mul_f32_e32 v162, v74, v110
	v_mul_f32_e32 v163, v75, v111
	v_mul_f32_e32 v164, v76, v112
	v_mul_f32_e32 v165, v77, v113
	v_mul_f32_e32 v166, v78, v114
	v_mul_f32_e32 v167, v79, v115
	v_mul_f32_e32 v168, v100, v116
	v_mul_f32_e32 v169, v101, v117
	v_mul_f32_e32 v170, v102, v118
	v_mul_f32_e32 v171, v103, v119
.Lrp20_same1:
	s_lshl_b32 s9, s6, 12
	s_add_u32 s32, s14, s9
	s_addc_u32 s33, s15, 0
	s_lshl_b32 s9, s6, 11
	s_add_u32 s9, s9, 0x30f8100
	s_add_u32 s34, s20, s9
	s_addc_u32 s35, s21, 0
	s_add_i32 s6, s6, 1
	s_cmp_lt_u32 s6, s7
	s_cbranch_scc0 .Lrp20_last1
	s_lshl_b32 s9, s6, 12
	s_add_u32 s24, s14, s9
	s_addc_u32 s25, s15, 0
	s_lshl_b32 s9, s6, 11
	s_add_u32 s9, s9, 0x9278100
	s_add_u32 s26, s20, s9
	s_addc_u32 s27, s21, 0
	global_load_dwordx2 v[204:205], v237, s[26:27] offset:0
	global_load_dwordx2 v[206:207], v237, s[26:27] offset:512
	global_load_dwordx2 v[208:209], v237, s[26:27] offset:1024
	global_load_dwordx2 v[210:211], v237, s[26:27] offset:1536
	global_load_dwordx4 v[188:191], v236, s[24:25] offset:0
	global_load_dwordx4 v[192:195], v236, s[24:25] offset:1024
	global_load_dwordx4 v[196:199], v236, s[24:25] offset:2048
	global_load_dwordx4 v[200:203], v236, s[24:25] offset:3072
	s_waitcnt vmcnt(16)
	s_branch .Lrp20_go1

.Lrp20_done:
.LBB0_1322:
	s_or_b64 exec, exec, s[0:1]
	s_waitcnt vmcnt(0)
	s_barrier
	s_mov_b64 s[0:1], exec
	v_readlane_b32 s2, v242, 5
	v_readlane_b32 s3, v242, 6
	s_and_b64 s[2:3], s[0:1], s[2:3]
	s_mov_b64 exec, s[2:3]
	s_cbranch_execz .LBB0_1374
	s_add_i32 s2, 0, 0x12008
	v_mov_b32_e32 v0, s2
	s_waitcnt vmcnt(0) expcnt(0) lgkmcnt(0)
	ds_read_b32 v2, v0
	s_add_i32 s2, 0, 0x1200c
	v_mov_b32_e32 v0, s2
	ds_read_b32 v0, v0
	s_waitcnt lgkmcnt(1)
	v_cmp_ne_u32_e32 vcc, 0, v2
	s_cbranch_vccnz .LBB0_1338
	v_readlane_b32 s2, v242, 42
	v_readlane_b32 s3, v242, 43
	v_readlane_b32 s36, v242, 1
	s_load_dwordx2 s[6:7], s[2:3], 0x4
	v_readlane_b32 s38, v242, 3
	v_readlane_b32 s39, v242, 4
	s_add_u32 s2, s38, 0x30f4300
	s_addc_u32 s3, s39, 0
	s_add_u32 s4, s38, 0x30f4500
	s_addc_u32 s5, s39, 0
	s_waitcnt lgkmcnt(0)
	s_mul_i32 s33, s6, s66
	s_add_u32 s6, s38, 0x30f4600
	s_mul_i32 s33, s33, s7
	s_addc_u32 s7, s39, 0
	s_add_u32 s8, s38, 0x30f4700
	s_addc_u32 s9, s39, 0
	s_add_u32 s10, s38, 0x30f4800
	s_addc_u32 s11, s39, 0
	s_add_u32 s12, s38, 0x30f4900
	s_addc_u32 s13, s39, 0
	s_add_u32 s14, s38, 0x30f4a00
	s_addc_u32 s15, s39, 0
	s_add_u32 s16, s38, 0x30f4b00
	s_addc_u32 s17, s39, 0
	s_add_u32 s18, s38, 0x30f4c00
	s_addc_u32 s19, s39, 0
	s_add_u32 s20, s38, 0x30f4d00
	s_addc_u32 s21, s39, 0
	s_add_u32 s22, s38, 0x30f4e00
	s_addc_u32 s23, s39, 0
	s_add_u32 s24, s38, 0x30f4f00
	s_addc_u32 s25, s39, 0
	s_add_u32 s26, s38, 0x30f5000
	s_addc_u32 s27, s39, 0
	s_add_u32 s28, s38, 0x30f5100
	s_addc_u32 s29, s39, 0
	s_add_u32 s30, s38, 0x30f5200
	s_addc_u32 s31, s39, 0
	s_add_u32 s34, s38, 0x30f5300
	s_addc_u32 s35, s39, 0
	v_readlane_b32 s37, v242, 2
	s_add_u32 s36, s38, 0x30f5400
	s_addc_u32 s37, s39, 0
	s_mov_b32 s40, 1
	v_mov_b32_e32 v16, 0
	s_branch .LBB0_1326

.LBB0_1959:
	s_waitcnt vmcnt(0) lgkmcnt(0)
	v_readlane_b32 s0, v242, 42
	v_readlane_b32 s1, v242, 43
	v_readlane_b32 s4, v242, 3
	v_readlane_b32 s5, v242, 4
	s_lshr_b32 s6, s24, 2
	s_and_b32 s7, s24, 3
	s_cmp_gt_u32 s6, 11
	s_cselect_b32 s8, 1, 0
	s_mul_i32 s9, s8, 12
	s_sub_i32 s9, s6, s9
	s_sub_u32 s0, s0, 0x118
	s_subb_u32 s1, s1, 0
	s_load_dwordx2 s[2:3], s[0:1], 0x30
	s_lshr_b32 s10, s9, 1
	s_and_b32 s11, s9, 1
	s_lshl_b32 s29, s8, 1
	s_add_i32 s29, s29, 1
	s_lshl_b32 s29, s29, 1
	s_add_i32 s29, s29, s11
	s_mul_i32 s29, s29, 6
	s_add_i32 s29, s29, s10
	s_lshl_b32 s29, s29, 14
	v_and_b32_e32 v20, 15, v137
	v_lshrrev_b32_e32 v21, 4, v137
	v_lshlrev_b32_e32 v22, 4, v137
	s_lshl_b32 s38, s7, 12
	v_add_u32_e32 v22, s38, v22
	s_waitcnt lgkmcnt(0)
	s_add_u32 s2, s2, s29
	s_addc_u32 s3, s3, 0
	global_load_dwordx4 v[0:3], v22, s[2:3]
	s_mul_i32 s38, s11, 0xf00000
	s_mul_i32 s39, s11, 0x780000
	s_add_u32 s29, s38, 0x9278100
	s_add_u32 s12, s4, s29
	s_addc_u32 s13, s5, 0
	s_add_u32 s29, s39, 0xb078100
	s_add_u32 s14, s4, s29
	s_addc_u32 s15, s5, 0
	s_add_u32 s29, s39, 0xbf78100
	s_add_u32 s18, s4, s29
	s_addc_u32 s19, s5, 0
	s_add_u32 s29, s39, 0xddc8100
	s_add_u32 s22, s4, s29
	s_addc_u32 s23, s5, 0
	s_add_u32 s16, s4, 0xce78100
	s_addc_u32 s17, s5, 0
	s_add_u32 s20, s4, 0x5b78100
	s_addc_u32 s21, s5, 0
	s_lshl_b32 s38, s11, 1
	s_sub_i32 s38, 1, s38
	s_mul_i32 s25, s38, 24576
	s_mul_i32 s26, s38, 12288
	s_mul_i32 s27, s38, 0x16000
	s_lshl_b32 s39, s8, 10
	s_addk_i32 s39, 0x2000
	s_mul_i32 s44, s11, 1023
	s_add_i32 s39, s39, s44
	v_mul_i32_i24_e32 v23, s38, v21
	v_mul_i32_i24_e32 v24, s38, v20
	v_add_u32_e32 v23, s39, v23
	v_add_u32_e32 v24, s39, v24
	s_lshl_b32 s38, s10, 8
	s_lshl_b32 s39, s10, 7
	s_movk_i32 s44, 0x600
	v_lshlrev_b32_e32 v25, 4, v20
	v_mul_lo_u32 v174, v23, s44
	v_add3_u32 v174, v174, s38, v25
	s_movk_i32 s44, 0x300
	v_lshlrev_b32_e32 v26, 3, v20
	v_mul_lo_u32 v175, v23, s44
	v_add3_u32 v175, v175, s39, v26
	v_mul_lo_u32 v145, v24, s44
	s_lshl_b32 s44, s7, 5
	s_add_i32 s44, s44, s39
	v_lshlrev_b32_e32 v27, 1, v21
	v_add3_u32 v145, v145, s44, v27
	s_movk_i32 s44, 0x1600
	v_mul_lo_u32 v180, v23, s44
	v_lshlrev_b32_e32 v28, 2, v20
	s_lshl_b32 s44, s7, 6
	s_add_i32 s44, s44, s38
	s_addk_i32 s44, 0xc00
	v_add3_u32 v181, v180, s44, v28
	v_add3_u32 v180, v180, s38, v25
	v_mov_b32_e32 v88, v25
	v_lshlrev_b32_e32 v90, 4, v21
	v_mul_u32_u24_e32 v91, 0x600, v21
	v_add_u32_e32 v91, v91, v25
	v_and_b32_e32 v29, 3, v20
	v_cmp_eq_u32_e64 s[30:31], 1, v29
	v_cmp_eq_u32_e64 s[34:35], 2, v29
	v_cmp_eq_u32_e64 s[36:37], 3, v29
	s_mov_b32 s28, 0
	s_setprio 3
	global_load_dwordx4 v[104:107], v174, s[12:13]
	global_load_dwordx2 v[146:147], v175, s[14:15]
	global_load_dwordx2 v[148:149], v175, s[16:17]
	global_load_dwordx2 v[150:151], v175, s[18:19]
	global_load_dwordx4 v[108:111], v180, s[20:21]
	global_load_dword v170, v181, s[20:21]
	v_add_u32_e32 v174, s25, v174
	v_add_u32_e32 v175, s26, v175
	v_add_u32_e32 v180, s27, v180
	v_add_u32_e32 v181, s27, v181
	global_load_dwordx4 v[112:115], v174, s[12:13]
	global_load_dwordx2 v[152:153], v175, s[14:15]
	global_load_dwordx2 v[154:155], v175, s[16:17]
	global_load_dwordx2 v[156:157], v175, s[18:19]
	global_load_dwordx4 v[116:119], v180, s[20:21]
	global_load_dword v171, v181, s[20:21]
	v_add_u32_e32 v174, s25, v174
	v_add_u32_e32 v175, s26, v175
	v_add_u32_e32 v180, s27, v180
	v_add_u32_e32 v181, s27, v181
	global_load_dwordx4 v[120:123], v174, s[12:13]
	global_load_dwordx2 v[158:159], v175, s[14:15]
	global_load_dwordx2 v[160:161], v175, s[16:17]
	global_load_dwordx2 v[162:163], v175, s[18:19]
	global_load_dwordx4 v[124:127], v180, s[20:21]
	global_load_dword v172, v181, s[20:21]
	v_add_u32_e32 v174, s25, v174
	v_add_u32_e32 v175, s26, v175
	v_add_u32_e32 v180, s27, v180
	v_add_u32_e32 v181, s27, v181
	global_load_dwordx4 v[128:131], v174, s[12:13]
	global_load_dwordx2 v[164:165], v175, s[14:15]
	global_load_dwordx2 v[166:167], v175, s[16:17]
	global_load_dwordx2 v[168:169], v175, s[18:19]
	global_load_dwordx4 v[132:135], v180, s[20:21]
	global_load_dword v173, v181, s[20:21]
	v_add_u32_e32 v174, s25, v174
	v_add_u32_e32 v175, s26, v175
	v_add_u32_e32 v180, s27, v180
	v_add_u32_e32 v181, s27, v181
	s_waitcnt vmcnt(18)
	ds_write_b128 v91, v[104:107] offset:0
	ds_write_b128 v91, v[108:111] offset:1024
	ds_write_b32 v91, v170 offset:1280
	v_lshlrev_b32_e32 v176, 16, v146
	v_and_b32_e32 v177, 0xffff0000, v146
	v_lshlrev_b32_e32 v178, 16, v147
	v_and_b32_e32 v179, 0xffff0000, v147
	ds_write_b128 v91, v[176:179] offset:256
	v_lshlrev_b32_e32 v176, 16, v148
	v_and_b32_e32 v177, 0xffff0000, v148
	v_lshlrev_b32_e32 v178, 16, v149
	v_and_b32_e32 v179, 0xffff0000, v149
	ds_write_b128 v91, v[176:179] offset:512
	v_lshlrev_b32_e32 v176, 16, v150
	v_and_b32_e32 v177, 0xffff0000, v150
	v_lshlrev_b32_e32 v178, 16, v151
	v_and_b32_e32 v179, 0xffff0000, v151
	ds_write_b128 v91, v[176:179] offset:768
	s_waitcnt lgkmcnt(0)
	s_barrier
	ds_read_b128 v[28:31], v88 offset:512
	ds_read_b128 v[24:27], v88 offset:256
	ds_read_b128 v[20:23], v88 offset:0
	ds_read_b128 v[32:35], v88 offset:768
	ds_read_b128 v[36:39], v88 offset:1024
	ds_read2st64_b32 v[16:17], v90 offset0:5 offset1:11
	ds_read_b128 v[48:51], v88 offset:2048
	ds_read_b128 v[44:47], v88 offset:1792
	ds_read_b128 v[40:43], v88 offset:1536
	ds_read_b128 v[52:55], v88 offset:2304
	ds_read_b128 v[56:59], v88 offset:2560

.LBB0_2141:
	s_or_b64 exec, exec, s[0:1]
	s_waitcnt lgkmcnt(0)
	v_mov_b32_e32 v0, v137
	s_barrier
	v_readlane_b32 s0, v242, 0
	v_ashrrev_i32_e32 v1, 6, v0
	s_nop 0
	v_lshl_add_u32 v1, s0, 2, v1
	v_mul_lo_u32 v16, v1, s56
	v_add_u32_e32 v1, s56, v16
	v_min_i32_e32 v62, 0x2800, v1
	v_cmp_lt_i32_e32 vcc, v16, v62
	s_and_saveexec_b64 s[0:1], vcc
	s_xor_b64 s[0:1], exec, s[0:1]
	s_cbranch_execz .LBB0_2147
	v_readfirstlane_b32 s6, v16
	v_readfirstlane_b32 s7, v62
	v_readlane_b32 s36, v242, 42
	v_readlane_b32 s37, v242, 43
	v_readlane_b32 s14, v242, 1
	v_readlane_b32 s15, v242, 2
	v_readlane_b32 s20, v242, 3
	v_readlane_b32 s21, v242, 4
	v_and_b32_e32 v236, 63, v137
	v_lshlrev_b32_e32 v237, 3, v236
	v_lshlrev_b32_e32 v236, 4, v236
	v_mov_b32_e32 v238, 0x358637bd
	s_sub_u32 s36, s36, 0x118
	s_subb_u32 s37, s37, 0
	s_load_dwordx2 s[10:11], s[36:37], 0x60
	s_load_dwordx2 s[12:13], s[36:37], 0x68
	s_add_u32 s22, s20, 0x2f90000
	s_addc_u32 s23, s21, 0
	s_mov_b32 s8, -1
	s_waitcnt lgkmcnt(0)
	s_add_u32 s10, s10, 0x1000
	s_addc_u32 s11, s11, 0
	s_add_u32 s12, s12, 0x1000
	s_addc_u32 s13, s13, 0
	s_lshl_b32 s9, s6, 12
	s_add_u32 s24, s14, s9
	s_addc_u32 s25, s15, 0
	s_lshl_b32 s9, s6, 11
	s_add_u32 s9, s9, 0x9278100
	s_add_u32 s26, s20, s9
	s_addc_u32 s27, s21, 0
	global_load_dwordx2 v[204:205], v237, s[26:27] offset:0
	global_load_dwordx2 v[206:207], v237, s[26:27] offset:512
	global_load_dwordx2 v[208:209], v237, s[26:27] offset:1024
	global_load_dwordx2 v[210:211], v237, s[26:27] offset:1536
	global_load_dwordx4 v[188:191], v236, s[24:25] offset:0
	global_load_dwordx4 v[192:195], v236, s[24:25] offset:1024
	global_load_dwordx4 v[196:199], v236, s[24:25] offset:2048
	global_load_dwordx4 v[200:203], v236, s[24:25] offset:3072
.Lrp11_loop:
	s_sub_u32 s9, s6, 0x2000
	s_ashr_i32 s9, s9, 10
	s_add_i32 s9, s9, 1
	s_max_i32 s9, s9, 0
	s_cmp_eq_u32 s9, s8
	s_cbranch_scc1 .Lrp11_same0
	s_mov_b32 s8, s9
	s_add_i32 s9, s8, 3
	s_mul_i32 s9, s9, 0x6000
	s_add_u32 s36, s22, s9
	s_addc_u32 s37, s23, 0
	s_add_u32 s38, s36, 0x2000
	s_addc_u32 s39, s37, 0
	global_load_dwordx4 v[32:35], v236, s[38:39] offset:0
	global_load_dwordx4 v[36:39], v236, s[38:39] offset:1024
	global_load_dwordx4 v[40:43], v236, s[38:39] offset:2048
	global_load_dwordx4 v[44:47], v236, s[38:39] offset:3072
	global_load_dwordx4 v[48:51], v236, s[10:11] offset:0
	global_load_dwordx4 v[52:55], v236, s[10:11] offset:1024
	global_load_dwordx4 v[56:59], v236, s[10:11] offset:2048
	global_load_dwordx4 v[64:67], v236, s[10:11] offset:3072
	global_load_dwordx4 v[68:71], v236, s[12:13] offset:0
	global_load_dwordx4 v[72:75], v236, s[12:13] offset:1024
	global_load_dwordx4 v[76:79], v236, s[12:13] offset:2048
	global_load_dwordx4 v[100:103], v236, s[12:13] offset:3072
	s_add_u32 s38, s36, 0x4000
	s_addc_u32 s39, s37, 0
	global_load_dwordx4 v[104:107], v236, s[38:39] offset:0
	global_load_dwordx4 v[108:111], v236, s[38:39] offset:1024
	global_load_dwordx4 v[112:115], v236, s[38:39] offset:2048
	global_load_dwordx4 v[116:119], v236, s[38:39] offset:3072
	s_add_u32 s38, s36, 0x3000
	s_addc_u32 s39, s37, 0
	global_load_dwordx4 v[172:175], v236, s[38:39] offset:0
	global_load_dwordx4 v[176:179], v236, s[38:39] offset:1024
	global_load_dwordx4 v[180:183], v236, s[38:39] offset:2048
	global_load_dwordx4 v[184:187], v236, s[38:39] offset:3072
	s_waitcnt vmcnt(0)
	v_mul_f32_e32 v140, v32, v48
	v_mul_f32_e32 v141, v33, v49
	v_mul_f32_e32 v142, v34, v50
	v_mul_f32_e32 v143, v35, v51
	v_mul_f32_e32 v144, v36, v52
	v_mul_f32_e32 v145, v37, v53
	v_mul_f32_e32 v146, v38, v54
	v_mul_f32_e32 v147, v39, v55
	v_mul_f32_e32 v148, v40, v56
	v_mul_f32_e32 v149, v41, v57
	v_mul_f32_e32 v150, v42, v58
	v_mul_f32_e32 v151, v43, v59
	v_mul_f32_e32 v152, v44, v64
	v_mul_f32_e32 v153, v45, v65
	v_mul_f32_e32 v154, v46, v66
	v_mul_f32_e32 v155, v47, v67
	v_add_f32_e32 v104, 1.0, v104
	v_add_f32_e32 v105, 1.0, v105
	v_add_f32_e32 v106, 1.0, v106
	v_add_f32_e32 v107, 1.0, v107
	v_add_f32_e32 v108, 1.0, v108
	v_add_f32_e32 v109, 1.0, v109
	v_add_f32_e32 v110, 1.0, v110
	v_add_f32_e32 v111, 1.0, v111
	v_add_f32_e32 v112, 1.0, v112
	v_add_f32_e32 v113, 1.0, v113
	v_add_f32_e32 v114, 1.0, v114
	v_add_f32_e32 v115, 1.0, v115
	v_add_f32_e32 v116, 1.0, v116
	v_add_f32_e32 v117, 1.0, v117
	v_add_f32_e32 v118, 1.0, v118
	v_add_f32_e32 v119, 1.0, v119
	v_mul_f32_e32 v156, v68, v104
	v_mul_f32_e32 v157, v69, v105
	v_mul_f32_e32 v158, v70, v106
	v_mul_f32_e32 v159, v71, v107
	v_mul_f32_e32 v160, v72, v108
	v_mul_f32_e32 v161, v73, v109
	v_mul_f32_e32 v162, v74, v110
	v_mul_f32_e32 v163, v75, v111
	v_mul_f32_e32 v164, v76, v112
	v_mul_f32_e32 v165, v77, v113
	v_mul_f32_e32 v166, v78, v114
	v_mul_f32_e32 v167, v79, v115
	v_mul_f32_e32 v168, v100, v116
	v_mul_f32_e32 v169, v101, v117
	v_mul_f32_e32 v170, v102, v118
	v_mul_f32_e32 v171, v103, v119

.Lrp11_go0:
	v_lshlrev_b32_e32 v100, 16, v204
	v_and_b32_e32 v101, 0xffff0000, v204
	v_lshlrev_b32_e32 v102, 16, v205
	v_and_b32_e32 v103, 0xffff0000, v205
	v_lshlrev_b32_e32 v104, 16, v206
	v_and_b32_e32 v105, 0xffff0000, v206
	v_lshlrev_b32_e32 v106, 16, v207
	v_and_b32_e32 v107, 0xffff0000, v207
	v_lshlrev_b32_e32 v108, 16, v208
	v_and_b32_e32 v109, 0xffff0000, v208
	v_lshlrev_b32_e32 v110, 16, v209
	v_and_b32_e32 v111, 0xffff0000, v209
	v_lshlrev_b32_e32 v112, 16, v210
	v_and_b32_e32 v113, 0xffff0000, v210
	v_lshlrev_b32_e32 v114, 16, v211
	v_and_b32_e32 v115, 0xffff0000, v211
	v_mul_f32_e32 v132, v100, v100
	v_mul_f32_e32 v133, v101, v101
	v_fmac_f32_e32 v132, v102, v102
	v_fmac_f32_e32 v133, v103, v103
	v_fmac_f32_e32 v132, v104, v104
	v_fmac_f32_e32 v133, v105, v105
	v_fmac_f32_e32 v132, v106, v106
	v_fmac_f32_e32 v133, v107, v107
	v_fmac_f32_e32 v132, v108, v108
	v_fmac_f32_e32 v133, v109, v109
	v_fmac_f32_e32 v132, v110, v110
	v_fmac_f32_e32 v133, v111, v111
	v_fmac_f32_e32 v132, v112, v112
	v_fmac_f32_e32 v133, v113, v113
	v_fmac_f32_e32 v132, v114, v114
	v_fmac_f32_e32 v133, v115, v115
	v_add_f32_e32 v132, v132, v133
	s_nop 1
	v_add_f32_dpp v132, v132, v132 quad_perm:[1,0,3,2] row_mask:0xf bank_mask:0xf bound_ctrl:1
	s_nop 1
	v_add_f32_dpp v132, v132, v132 quad_perm:[2,3,0,1] row_mask:0xf bank_mask:0xf bound_ctrl:1
	s_nop 1
	v_add_f32_dpp v132, v132, v132 row_ror:4 row_mask:0xf bank_mask:0xf bound_ctrl:1
	s_nop 1
	v_add_f32_dpp v132, v132, v132 row_ror:8 row_mask:0xf bank_mask:0xf bound_ctrl:1
	s_nop 1
	v_readlane_b32 s9, v132, 0
	v_readlane_b32 s38, v132, 16
	v_readlane_b32 s39, v132, 32
	v_readlane_b32 s40, v132, 48
	s_nop 2
	v_mov_b32_e32 v132, s9
	v_add_f32_e32 v132, s38, v132
	v_mov_b32_e32 v135, s39
	v_add_f32_e32 v135, s40, v135
	v_add_f32_e32 v132, v132, v135
	v_fmamk_f32 v132, v132, 0x3a800000, v238
	v_rsq_f32_e32 v132, v132
	s_nop 0
	v_mul_f32_e32 v100, v100, v132
	v_mul_f32_e32 v101, v101, v132
	v_mul_f32_e32 v102, v102, v132
	v_mul_f32_e32 v103, v103, v132
	v_mul_f32_e32 v104, v104, v132
	v_mul_f32_e32 v105, v105, v132
	v_mul_f32_e32 v106, v106, v132
	v_mul_f32_e32 v107, v107, v132
	v_mul_f32_e32 v108, v108, v132
	v_mul_f32_e32 v109, v109, v132
	v_mul_f32_e32 v110, v110, v132
	v_mul_f32_e32 v111, v111, v132
	v_mul_f32_e32 v112, v112, v132
	v_mul_f32_e32 v113, v113, v132
	v_mul_f32_e32 v114, v114, v132
	v_mul_f32_e32 v115, v115, v132
	v_fmac_f32_e32 v188, v140, v100
	v_fmac_f32_e32 v189, v141, v101
	v_fmac_f32_e32 v190, v142, v102
	v_fmac_f32_e32 v191, v143, v103
	v_fmac_f32_e32 v192, v144, v104
	v_fmac_f32_e32 v193, v145, v105
	v_fmac_f32_e32 v194, v146, v106
	v_fmac_f32_e32 v195, v147, v107
	v_fmac_f32_e32 v196, v148, v108
	v_fmac_f32_e32 v197, v149, v109
	v_fmac_f32_e32 v198, v150, v110
	v_fmac_f32_e32 v199, v151, v111
	v_fmac_f32_e32 v200, v152, v112
	v_fmac_f32_e32 v201, v153, v113
	v_fmac_f32_e32 v202, v154, v114
	v_fmac_f32_e32 v203, v155, v115
	global_store_dwordx4 v236, v[188:191], s[32:33] offset:0
	global_store_dwordx4 v236, v[192:195], s[32:33] offset:1024
	global_store_dwordx4 v236, v[196:199], s[32:33] offset:2048
	global_store_dwordx4 v236, v[200:203], s[32:33] offset:3072
	v_mul_f32_e32 v132, v188, v188
	v_mul_f32_e32 v133, v189, v189
	v_fmac_f32_e32 v132, v190, v190
	v_fmac_f32_e32 v133, v191, v191
	v_fmac_f32_e32 v132, v192, v192
	v_fmac_f32_e32 v133, v193, v193
	v_fmac_f32_e32 v132, v194, v194
	v_fmac_f32_e32 v133, v195, v195
	v_fmac_f32_e32 v132, v196, v196
	v_fmac_f32_e32 v133, v197, v197
	v_fmac_f32_e32 v132, v198, v198
	v_fmac_f32_e32 v133, v199, v199
	v_fmac_f32_e32 v132, v200, v200
	v_fmac_f32_e32 v133, v201, v201
	v_fmac_f32_e32 v132, v202, v202
	v_fmac_f32_e32 v133, v203, v203
	v_add_f32_e32 v132, v132, v133
	s_nop 1
	v_add_f32_dpp v132, v132, v132 quad_perm:[1,0,3,2] row_mask:0xf bank_mask:0xf bound_ctrl:1
	s_nop 1
	v_add_f32_dpp v132, v132, v132 quad_perm:[2,3,0,1] row_mask:0xf bank_mask:0xf bound_ctrl:1
	s_nop 1
	v_add_f32_dpp v132, v132, v132 row_ror:4 row_mask:0xf bank_mask:0xf bound_ctrl:1
	s_nop 1
	v_add_f32_dpp v132, v132, v132 row_ror:8 row_mask:0xf bank_mask:0xf bound_ctrl:1
	s_nop 1
	v_readlane_b32 s9, v132, 0
	v_readlane_b32 s38, v132, 16
	v_readlane_b32 s39, v132, 32
	v_readlane_b32 s40, v132, 48
	s_nop 2
	v_mov_b32_e32 v132, s9
	v_add_f32_e32 v132, s38, v132
	v_mov_b32_e32 v135, s39
	v_add_f32_e32 v135, s40, v135
	v_add_f32_e32 v132, v132, v135
	v_fmamk_f32 v132, v132, 0x3a800000, v238
	v_rsq_f32_e32 v132, v132
	s_nop 0
	v_mul_f32_e32 v116, v188, v132
	v_mul_f32_e32 v117, v189, v132
	v_mul_f32_e32 v118, v190, v132
	v_mul_f32_e32 v119, v191, v132
	v_mul_f32_e32 v120, v192, v132
	v_mul_f32_e32 v121, v193, v132
	v_mul_f32_e32 v122, v194, v132
	v_mul_f32_e32 v123, v195, v132
	v_mul_f32_e32 v124, v196, v132
	v_mul_f32_e32 v125, v197, v132
	v_mul_f32_e32 v126, v198, v132
	v_mul_f32_e32 v127, v199, v132
	v_mul_f32_e32 v128, v200, v132
	v_mul_f32_e32 v129, v201, v132
	v_mul_f32_e32 v130, v202, v132
	v_mul_f32_e32 v131, v203, v132
	v_fma_f32 v116, v116, v156, v172
	v_fma_f32 v117, v117, v157, v173
	v_fma_f32 v118, v118, v158, v174
	v_fma_f32 v119, v119, v159, v175
	v_fma_f32 v120, v120, v160, v176
	v_fma_f32 v121, v121, v161, v177
	v_fma_f32 v122, v122, v162, v178
	v_fma_f32 v123, v123, v163, v179
	v_fma_f32 v124, v124, v164, v180
	v_fma_f32 v125, v125, v165, v181
	v_fma_f32 v126, v126, v166, v182
	v_fma_f32 v127, v127, v167, v183
	v_fma_f32 v128, v128, v168, v184
	v_fma_f32 v129, v129, v169, v185
	v_fma_f32 v130, v130, v170, v186
	v_fma_f32 v131, v131, v171, v187
	v_cvt_pk_bf16_f32 v116, v116, v117
	v_cvt_pk_bf16_f32 v117, v118, v119
	v_cvt_pk_bf16_f32 v118, v120, v121
	v_cvt_pk_bf16_f32 v119, v122, v123
	v_cvt_pk_bf16_f32 v120, v124, v125
	v_cvt_pk_bf16_f32 v121, v126, v127
	v_cvt_pk_bf16_f32 v122, v128, v129
	v_cvt_pk_bf16_f32 v123, v130, v131
	global_store_dwordx2 v237, v[116:117], s[34:35] offset:0
	global_store_dwordx2 v237, v[118:119], s[34:35] offset:512
	global_store_dwordx2 v237, v[120:121], s[34:35] offset:1024
	global_store_dwordx2 v237, v[122:123], s[34:35] offset:1536
	s_cmp_lt_u32 s6, s7
	s_cbranch_scc0 .Lrp11_done
	s_sub_u32 s9, s6, 0x2000
	s_ashr_i32 s9, s9, 10
	s_add_i32 s9, s9, 1
	s_max_i32 s9, s9, 0
	s_cmp_eq_u32 s9, s8
	s_cbranch_scc1 .Lrp11_same1
	s_mov_b32 s8, s9
	s_add_i32 s9, s8, 3
	s_mul_i32 s9, s9, 0x6000
	s_add_u32 s36, s22, s9
	s_addc_u32 s37, s23, 0
	s_add_u32 s38, s36, 0x2000
	s_addc_u32 s39, s37, 0
	global_load_dwordx4 v[32:35], v236, s[38:39] offset:0
	global_load_dwordx4 v[36:39], v236, s[38:39] offset:1024
	global_load_dwordx4 v[40:43], v236, s[38:39] offset:2048
	global_load_dwordx4 v[44:47], v236, s[38:39] offset:3072
	global_load_dwordx4 v[48:51], v236, s[10:11] offset:0
	global_load_dwordx4 v[52:55], v236, s[10:11] offset:1024
	global_load_dwordx4 v[56:59], v236, s[10:11] offset:2048
	global_load_dwordx4 v[64:67], v236, s[10:11] offset:3072
	global_load_dwordx4 v[68:71], v236, s[12:13] offset:0
	global_load_dwordx4 v[72:75], v236, s[12:13] offset:1024
	global_load_dwordx4 v[76:79], v236, s[12:13] offset:2048
	global_load_dwordx4 v[100:103], v236, s[12:13] offset:3072
	s_add_u32 s38, s36, 0x4000
	s_addc_u32 s39, s37, 0
	global_load_dwordx4 v[104:107], v236, s[38:39] offset:0
	global_load_dwordx4 v[108:111], v236, s[38:39] offset:1024
	global_load_dwordx4 v[112:115], v236, s[38:39] offset:2048
	global_load_dwordx4 v[116:119], v236, s[38:39] offset:3072
	s_add_u32 s38, s36, 0x3000
	s_addc_u32 s39, s37, 0
	global_load_dwordx4 v[172:175], v236, s[38:39] offset:0
	global_load_dwordx4 v[176:179], v236, s[38:39] offset:1024
	global_load_dwordx4 v[180:183], v236, s[38:39] offset:2048
	global_load_dwordx4 v[184:187], v236, s[38:39] offset:3072
	s_waitcnt vmcnt(0)
	v_mul_f32_e32 v140, v32, v48
	v_mul_f32_e32 v141, v33, v49
	v_mul_f32_e32 v142, v34, v50
	v_mul_f32_e32 v143, v35, v51
	v_mul_f32_e32 v144, v36, v52
	v_mul_f32_e32 v145, v37, v53
	v_mul_f32_e32 v146, v38, v54
	v_mul_f32_e32 v147, v39, v55
	v_mul_f32_e32 v148, v40, v56
	v_mul_f32_e32 v149, v41, v57
	v_mul_f32_e32 v150, v42, v58
	v_mul_f32_e32 v151, v43, v59
	v_mul_f32_e32 v152, v44, v64
	v_mul_f32_e32 v153, v45, v65
	v_mul_f32_e32 v154, v46, v66
	v_mul_f32_e32 v155, v47, v67
	v_add_f32_e32 v104, 1.0, v104
	v_add_f32_e32 v105, 1.0, v105
	v_add_f32_e32 v106, 1.0, v106
	v_add_f32_e32 v107, 1.0, v107
	v_add_f32_e32 v108, 1.0, v108
	v_add_f32_e32 v109, 1.0, v109
	v_add_f32_e32 v110, 1.0, v110
	v_add_f32_e32 v111, 1.0, v111
	v_add_f32_e32 v112, 1.0, v112
	v_add_f32_e32 v113, 1.0, v113
	v_add_f32_e32 v114, 1.0, v114
	v_add_f32_e32 v115, 1.0, v115
	v_add_f32_e32 v116, 1.0, v116
	v_add_f32_e32 v117, 1.0, v117
	v_add_f32_e32 v118, 1.0, v118
	v_add_f32_e32 v119, 1.0, v119
	v_mul_f32_e32 v156, v68, v104
	v_mul_f32_e32 v157, v69, v105
	v_mul_f32_e32 v158, v70, v106
	v_mul_f32_e32 v159, v71, v107
	v_mul_f32_e32 v160, v72, v108
	v_mul_f32_e32 v161, v73, v109
	v_mul_f32_e32 v162, v74, v110
	v_mul_f32_e32 v163, v75, v111
	v_mul_f32_e32 v164, v76, v112
	v_mul_f32_e32 v165, v77, v113
	v_mul_f32_e32 v166, v78, v114
	v_mul_f32_e32 v167, v79, v115
	v_mul_f32_e32 v168, v100, v116
	v_mul_f32_e32 v169, v101, v117
	v_mul_f32_e32 v170, v102, v118
	v_mul_f32_e32 v171, v103, v119

.Lrp11_done:
	s_mov_b64 s[4:5], 0
.LBB0_2146:
	s_or_b64 exec, exec, s[4:5]

.LBB0_2315:
	s_or_b64 exec, exec, s[0:1]
	s_waitcnt lgkmcnt(0)
	s_barrier
	v_readlane_b32 s0, v242, 0
	v_ashrrev_i32_e32 v0, 6, v137
	s_nop 0
	v_lshl_add_u32 v0, s0, 2, v0
	v_mul_lo_u32 v0, v0, s56
	v_add_u32_e32 v1, s56, v0
	v_min_i32_e32 v26, 0x2800, v1
	v_cmp_lt_i32_e32 vcc, v0, v26
	s_and_saveexec_b64 s[0:1], vcc
	s_cbranch_execz .LBB0_2320
	v_readfirstlane_b32 s6, v0
	v_readfirstlane_b32 s7, v26
	v_readlane_b32 s36, v242, 42
	v_readlane_b32 s37, v242, 43
	v_readlane_b32 s14, v242, 1
	v_readlane_b32 s15, v242, 2
	v_readlane_b32 s20, v242, 3
	v_readlane_b32 s21, v242, 4
	v_and_b32_e32 v236, 63, v137
	v_lshlrev_b32_e32 v237, 3, v236
	v_lshlrev_b32_e32 v236, 4, v236
	v_mov_b32_e32 v238, 0x358637bd
	s_sub_u32 s36, s36, 0x118
	s_subb_u32 s37, s37, 0
	s_load_dwordx2 s[10:11], s[36:37], 0x70
	s_add_u32 s22, s20, 0x2f90000
	s_addc_u32 s23, s21, 0
	s_mov_b32 s8, -1
	s_waitcnt lgkmcnt(0)
	s_add_u32 s10, s10, 0x1000
	s_addc_u32 s11, s11, 0
	s_lshl_b32 s9, s6, 12
	s_add_u32 s24, s14, s9
	s_addc_u32 s25, s15, 0
	s_lshl_b32 s9, s6, 11
	s_add_u32 s9, s9, 0x9278100
	s_add_u32 s26, s20, s9
	s_addc_u32 s27, s21, 0
	global_load_dwordx2 v[204:205], v237, s[26:27] offset:0
	global_load_dwordx2 v[206:207], v237, s[26:27] offset:512
	global_load_dwordx2 v[208:209], v237, s[26:27] offset:1024
	global_load_dwordx2 v[210:211], v237, s[26:27] offset:1536
	global_load_dwordx4 v[188:191], v236, s[24:25] offset:0
	global_load_dwordx4 v[192:195], v236, s[24:25] offset:1024
	global_load_dwordx4 v[196:199], v236, s[24:25] offset:2048
	global_load_dwordx4 v[200:203], v236, s[24:25] offset:3072
.Lrp21_loop:
	s_sub_u32 s9, s6, 0x2000
	s_ashr_i32 s9, s9, 10
	s_add_i32 s9, s9, 1
	s_max_i32 s9, s9, 0
	s_cmp_eq_u32 s9, s8
	s_cbranch_scc1 .Lrp21_same0
	s_mov_b32 s8, s9
	s_add_i32 s9, s8, 3
	s_mul_i32 s9, s9, 0x6000
	s_add_u32 s36, s22, s9
	s_addc_u32 s37, s23, 0
	s_add_u32 s38, s36, 0x5000
	s_addc_u32 s39, s37, 0
	global_load_dwordx4 v[32:35], v236, s[38:39] offset:0
	global_load_dwordx4 v[36:39], v236, s[38:39] offset:1024
	global_load_dwordx4 v[40:43], v236, s[38:39] offset:2048
	global_load_dwordx4 v[44:47], v236, s[38:39] offset:3072
	global_load_dwordx4 v[48:51], v236, s[10:11] offset:0
	global_load_dwordx4 v[52:55], v236, s[10:11] offset:1024
	global_load_dwordx4 v[56:59], v236, s[10:11] offset:2048
	global_load_dwordx4 v[64:67], v236, s[10:11] offset:3072
	s_waitcnt vmcnt(0)
	v_mul_f32_e32 v140, v32, v48
	v_mul_f32_e32 v141, v33, v49
	v_mul_f32_e32 v142, v34, v50
	v_mul_f32_e32 v143, v35, v51
	v_mul_f32_e32 v144, v36, v52
	v_mul_f32_e32 v145, v37, v53
	v_mul_f32_e32 v146, v38, v54
	v_mul_f32_e32 v147, v39, v55
	v_mul_f32_e32 v148, v40, v56
	v_mul_f32_e32 v149, v41, v57
	v_mul_f32_e32 v150, v42, v58
	v_mul_f32_e32 v151, v43, v59
	v_mul_f32_e32 v152, v44, v64
	v_mul_f32_e32 v153, v45, v65
	v_mul_f32_e32 v154, v46, v66
	v_mul_f32_e32 v155, v47, v67
.Lrp21_same0:
	s_lshl_b32 s9, s6, 12
	s_add_u32 s32, s14, s9
	s_addc_u32 s33, s15, 0
	s_add_i32 s6, s6, 1
	s_cmp_lt_u32 s6, s7
	s_cbranch_scc0 .Lrp21_last0
	s_lshl_b32 s9, s6, 12
	s_add_u32 s28, s14, s9
	s_addc_u32 s29, s15, 0
	s_lshl_b32 s9, s6, 11
	s_add_u32 s9, s9, 0x9278100
	s_add_u32 s30, s20, s9
	s_addc_u32 s31, s21, 0
	global_load_dwordx2 v[228:229], v237, s[30:31] offset:0
	global_load_dwordx2 v[230:231], v237, s[30:31] offset:512
	global_load_dwordx2 v[232:233], v237, s[30:31] offset:1024
	global_load_dwordx2 v[234:235], v237, s[30:31] offset:1536
	global_load_dwordx4 v[212:215], v236, s[28:29] offset:0
	global_load_dwordx4 v[216:219], v236, s[28:29] offset:1024
	global_load_dwordx4 v[220:223], v236, s[28:29] offset:2048
	global_load_dwordx4 v[224:227], v236, s[28:29] offset:3072
	s_waitcnt vmcnt(12)
	s_branch .Lrp21_go0
.Lrp21_last0:
	s_waitcnt vmcnt(4)
.Lrp21_go0:
	v_lshlrev_b32_e32 v100, 16, v204
	v_and_b32_e32 v101, 0xffff0000, v204
	v_lshlrev_b32_e32 v102, 16, v205
	v_and_b32_e32 v103, 0xffff0000, v205
	v_lshlrev_b32_e32 v104, 16, v206
	v_and_b32_e32 v105, 0xffff0000, v206
	v_lshlrev_b32_e32 v106, 16, v207
	v_and_b32_e32 v107, 0xffff0000, v207
	v_lshlrev_b32_e32 v108, 16, v208
	v_and_b32_e32 v109, 0xffff0000, v208
	v_lshlrev_b32_e32 v110, 16, v209
	v_and_b32_e32 v111, 0xffff0000, v209
	v_lshlrev_b32_e32 v112, 16, v210
	v_and_b32_e32 v113, 0xffff0000, v210
	v_lshlrev_b32_e32 v114, 16, v211
	v_and_b32_e32 v115, 0xffff0000, v211
	v_mul_f32_e32 v132, v100, v100
	v_mul_f32_e32 v133, v101, v101
	v_fmac_f32_e32 v132, v102, v102
	v_fmac_f32_e32 v133, v103, v103
	v_fmac_f32_e32 v132, v104, v104
	v_fmac_f32_e32 v133, v105, v105
	v_fmac_f32_e32 v132, v106, v106
	v_fmac_f32_e32 v133, v107, v107
	v_fmac_f32_e32 v132, v108, v108
	v_fmac_f32_e32 v133, v109, v109
	v_fmac_f32_e32 v132, v110, v110
	v_fmac_f32_e32 v133, v111, v111
	v_fmac_f32_e32 v132, v112, v112
	v_fmac_f32_e32 v133, v113, v113
	v_fmac_f32_e32 v132, v114, v114
	v_fmac_f32_e32 v133, v115, v115
	v_add_f32_e32 v132, v132, v133
	s_nop 1
	v_add_f32_dpp v132, v132, v132 quad_perm:[1,0,3,2] row_mask:0xf bank_mask:0xf bound_ctrl:1
	s_nop 1
	v_add_f32_dpp v132, v132, v132 quad_perm:[2,3,0,1] row_mask:0xf bank_mask:0xf bound_ctrl:1
	s_nop 1
	v_add_f32_dpp v132, v132, v132 row_ror:4 row_mask:0xf bank_mask:0xf bound_ctrl:1
	s_nop 1
	v_add_f32_dpp v132, v132, v132 row_ror:8 row_mask:0xf bank_mask:0xf bound_ctrl:1
	s_nop 1
	v_readlane_b32 s9, v132, 0
	v_readlane_b32 s38, v132, 16
	v_readlane_b32 s39, v132, 32
	v_readlane_b32 s40, v132, 48
	s_nop 2
	v_mov_b32_e32 v132, s9
	v_add_f32_e32 v132, s38, v132
	v_mov_b32_e32 v135, s39
	v_add_f32_e32 v135, s40, v135
	v_add_f32_e32 v132, v132, v135
	v_fmamk_f32 v132, v132, 0x3a800000, v238
	v_rsq_f32_e32 v132, v132
	s_nop 0
	v_mul_f32_e32 v100, v100, v132
	v_mul_f32_e32 v101, v101, v132
	v_mul_f32_e32 v102, v102, v132
	v_mul_f32_e32 v103, v103, v132
	v_mul_f32_e32 v104, v104, v132
	v_mul_f32_e32 v105, v105, v132
	v_mul_f32_e32 v106, v106, v132
	v_mul_f32_e32 v107, v107, v132
	v_mul_f32_e32 v108, v108, v132
	v_mul_f32_e32 v109, v109, v132
	v_mul_f32_e32 v110, v110, v132
	v_mul_f32_e32 v111, v111, v132
	v_mul_f32_e32 v112, v112, v132
	v_mul_f32_e32 v113, v113, v132
	v_mul_f32_e32 v114, v114, v132
	v_mul_f32_e32 v115, v115, v132
	v_fmac_f32_e32 v188, v140, v100
	v_fmac_f32_e32 v189, v141, v101
	v_fmac_f32_e32 v190, v142, v102
	v_fmac_f32_e32 v191, v143, v103
	v_fmac_f32_e32 v192, v144, v104
	v_fmac_f32_e32 v193, v145, v105
	v_fmac_f32_e32 v194, v146, v106
	v_fmac_f32_e32 v195, v147, v107
	v_fmac_f32_e32 v196, v148, v108
	v_fmac_f32_e32 v197, v149, v109
	v_fmac_f32_e32 v198, v150, v110
	v_fmac_f32_e32 v199, v151, v111
	v_fmac_f32_e32 v200, v152, v112
	v_fmac_f32_e32 v201, v153, v113
	v_fmac_f32_e32 v202, v154, v114
	v_fmac_f32_e32 v203, v155, v115
	global_store_dwordx4 v236, v[188:191], s[32:33] offset:0
	global_store_dwordx4 v236, v[192:195], s[32:33] offset:1024
	global_store_dwordx4 v236, v[196:199], s[32:33] offset:2048
	global_store_dwordx4 v236, v[200:203], s[32:33] offset:3072
	s_cmp_lt_u32 s6, s7
	s_cbranch_scc0 .Lrp21_done
	s_sub_u32 s9, s6, 0x2000
	s_ashr_i32 s9, s9, 10
	s_add_i32 s9, s9, 1
	s_max_i32 s9, s9, 0
	s_cmp_eq_u32 s9, s8
	s_cbranch_scc1 .Lrp21_same1
	s_mov_b32 s8, s9
	s_add_i32 s9, s8, 3
	s_mul_i32 s9, s9, 0x6000
	s_add_u32 s36, s22, s9
	s_addc_u32 s37, s23, 0
	s_add_u32 s38, s36, 0x5000
	s_addc_u32 s39, s37, 0
	global_load_dwordx4 v[32:35], v236, s[38:39] offset:0
	global_load_dwordx4 v[36:39], v236, s[38:39] offset:1024
	global_load_dwordx4 v[40:43], v236, s[38:39] offset:2048
	global_load_dwordx4 v[44:47], v236, s[38:39] offset:3072
	global_load_dwordx4 v[48:51], v236, s[10:11] offset:0
	global_load_dwordx4 v[52:55], v236, s[10:11] offset:1024
	global_load_dwordx4 v[56:59], v236, s[10:11] offset:2048
	global_load_dwordx4 v[64:67], v236, s[10:11] offset:3072
	s_waitcnt vmcnt(0)
	v_mul_f32_e32 v140, v32, v48
	v_mul_f32_e32 v141, v33, v49
	v_mul_f32_e32 v142, v34, v50
	v_mul_f32_e32 v143, v35, v51
	v_mul_f32_e32 v144, v36, v52
	v_mul_f32_e32 v145, v37, v53
	v_mul_f32_e32 v146, v38, v54
	v_mul_f32_e32 v147, v39, v55
	v_mul_f32_e32 v148, v40, v56
	v_mul_f32_e32 v149, v41, v57
	v_mul_f32_e32 v150, v42, v58
	v_mul_f32_e32 v151, v43, v59
	v_mul_f32_e32 v152, v44, v64
	v_mul_f32_e32 v153, v45, v65
	v_mul_f32_e32 v154, v46, v66
	v_mul_f32_e32 v155, v47, v67
.Lrp21_same1:
	s_lshl_b32 s9, s6, 12
	s_add_u32 s32, s14, s9
	s_addc_u32 s33, s15, 0
	s_add_i32 s6, s6, 1
	s_cmp_lt_u32 s6, s7
	s_cbranch_scc0 .Lrp21_last1
	s_lshl_b32 s9, s6, 12
	s_add_u32 s24, s14, s9
	s_addc_u32 s25, s15, 0
	s_lshl_b32 s9, s6, 11
	s_add_u32 s9, s9, 0x9278100
	s_add_u32 s26, s20, s9
	s_addc_u32 s27, s21, 0
	global_load_dwordx2 v[204:205], v237, s[26:27] offset:0
	global_load_dwordx2 v[206:207], v237, s[26:27] offset:512
	global_load_dwordx2 v[208:209], v237, s[26:27] offset:1024
	global_load_dwordx2 v[210:211], v237, s[26:27] offset:1536
	global_load_dwordx4 v[188:191], v236, s[24:25] offset:0
	global_load_dwordx4 v[192:195], v236, s[24:25] offset:1024
	global_load_dwordx4 v[196:199], v236, s[24:25] offset:2048
	global_load_dwordx4 v[200:203], v236, s[24:25] offset:3072
	s_waitcnt vmcnt(12)
	s_branch .Lrp21_go1

.Lrp21_go1:
	v_lshlrev_b32_e32 v100, 16, v228
	v_and_b32_e32 v101, 0xffff0000, v228
	v_lshlrev_b32_e32 v102, 16, v229
	v_and_b32_e32 v103, 0xffff0000, v229
	v_lshlrev_b32_e32 v104, 16, v230
	v_and_b32_e32 v105, 0xffff0000, v230
	v_lshlrev_b32_e32 v106, 16, v231
	v_and_b32_e32 v107, 0xffff0000, v231
	v_lshlrev_b32_e32 v108, 16, v232
	v_and_b32_e32 v109, 0xffff0000, v232
	v_lshlrev_b32_e32 v110, 16, v233
	v_and_b32_e32 v111, 0xffff0000, v233
	v_lshlrev_b32_e32 v112, 16, v234
	v_and_b32_e32 v113, 0xffff0000, v234
	v_lshlrev_b32_e32 v114, 16, v235
	v_and_b32_e32 v115, 0xffff0000, v235
	v_mul_f32_e32 v132, v100, v100
	v_mul_f32_e32 v133, v101, v101
	v_fmac_f32_e32 v132, v102, v102
	v_fmac_f32_e32 v133, v103, v103
	v_fmac_f32_e32 v132, v104, v104
	v_fmac_f32_e32 v133, v105, v105
	v_fmac_f32_e32 v132, v106, v106
	v_fmac_f32_e32 v133, v107, v107
	v_fmac_f32_e32 v132, v108, v108
	v_fmac_f32_e32 v133, v109, v109
	v_fmac_f32_e32 v132, v110, v110
	v_fmac_f32_e32 v133, v111, v111
	v_fmac_f32_e32 v132, v112, v112
	v_fmac_f32_e32 v133, v113, v113
	v_fmac_f32_e32 v132, v114, v114
	v_fmac_f32_e32 v133, v115, v115
	v_add_f32_e32 v132, v132, v133
	s_nop 1
	v_add_f32_dpp v132, v132, v132 quad_perm:[1,0,3,2] row_mask:0xf bank_mask:0xf bound_ctrl:1
	s_nop 1
	v_add_f32_dpp v132, v132, v132 quad_perm:[2,3,0,1] row_mask:0xf bank_mask:0xf bound_ctrl:1
	s_nop 1
	v_add_f32_dpp v132, v132, v132 row_ror:4 row_mask:0xf bank_mask:0xf bound_ctrl:1
	s_nop 1
	v_add_f32_dpp v132, v132, v132 row_ror:8 row_mask:0xf bank_mask:0xf bound_ctrl:1
	s_nop 1
	v_readlane_b32 s9, v132, 0
	v_readlane_b32 s38, v132, 16
	v_readlane_b32 s39, v132, 32
	v_readlane_b32 s40, v132, 48
	s_nop 2
	v_mov_b32_e32 v132, s9
	v_add_f32_e32 v132, s38, v132
	v_mov_b32_e32 v135, s39
	v_add_f32_e32 v135, s40, v135
	v_add_f32_e32 v132, v132, v135
	v_fmamk_f32 v132, v132, 0x3a800000, v238
	v_rsq_f32_e32 v132, v132
	s_nop 0
	v_mul_f32_e32 v100, v100, v132
	v_mul_f32_e32 v101, v101, v132
	v_mul_f32_e32 v102, v102, v132
	v_mul_f32_e32 v103, v103, v132
	v_mul_f32_e32 v104, v104, v132
	v_mul_f32_e32 v105, v105, v132
	v_mul_f32_e32 v106, v106, v132
	v_mul_f32_e32 v107, v107, v132
	v_mul_f32_e32 v108, v108, v132
	v_mul_f32_e32 v109, v109, v132
	v_mul_f32_e32 v110, v110, v132
	v_mul_f32_e32 v111, v111, v132
	v_mul_f32_e32 v112, v112, v132
	v_mul_f32_e32 v113, v113, v132
	v_mul_f32_e32 v114, v114, v132
	v_mul_f32_e32 v115, v115, v132
	v_fmac_f32_e32 v212, v140, v100
	v_fmac_f32_e32 v213, v141, v101
	v_fmac_f32_e32 v214, v142, v102
	v_fmac_f32_e32 v215, v143, v103
	v_fmac_f32_e32 v216, v144, v104
	v_fmac_f32_e32 v217, v145, v105
	v_fmac_f32_e32 v218, v146, v106
	v_fmac_f32_e32 v219, v147, v107
	v_fmac_f32_e32 v220, v148, v108
	v_fmac_f32_e32 v221, v149, v109
	v_fmac_f32_e32 v222, v150, v110
	v_fmac_f32_e32 v223, v151, v111
	v_fmac_f32_e32 v224, v152, v112
	v_fmac_f32_e32 v225, v153, v113
	v_fmac_f32_e32 v226, v154, v114
	v_fmac_f32_e32 v227, v155, v115
	global_store_dwordx4 v236, v[212:215], s[32:33] offset:0
	global_store_dwordx4 v236, v[216:219], s[32:33] offset:1024
	global_store_dwordx4 v236, v[220:223], s[32:33] offset:2048
	global_store_dwordx4 v236, v[224:227], s[32:33] offset:3072
	s_cmp_lt_u32 s6, s7
	s_cbranch_scc1 .Lrp21_loop
.Lrp21_done:
.LBB0_2320:
	s_endpgm
